# G2 merge epilogue: gate/br0/br1 loads prefetched three fragments ahead into idle fragment registers (was two dependent round trips per fragment)
# speedup vs baseline: 1.0372x; 1.0102x over previous
; __device__ __forceinline__ float sigmoidf_(float x) { return 1.f / (1.f + __expf(-x)); }
;     __device__ __forceinline__ void operator()(const f32x4 (&acc)[2][2][4][2], const pg8::Unit& u, int wr, int wc, int fr, int fq) const {
;     ...
;             for (int m = 0; m < 4; ++m) { const int row = row0 + ai * 128 + m * 16;
; #pragma unroll
;                 for (int bj = 0; bj < 2; ++bj) { const int col = col0 + bj * 128;
;                     const u32x4 gw = *(const u32x4*)(P + (size_t)row * NINP + GATEOFF + 2 * 2048 + col); float gt[8]; unpack8(gw, gt);
;                     const u32x4 w0 = *(const u32x4*)(br0 + (size_t)row * D + col); float b0[8]; unpack8(w0, b0);
;                     const u32x4 w1 = *(const u32x4*)(br1 + (size_t)row * D + col); float b1[8]; unpack8(w1, b1);
;                     const f32x4 v0 = acc[ai][bj][m][0], v1 = acc[ai][bj][m][1];
;                     float o[8];
; #pragma unroll
;                     for (int j = 0; j < 4; ++j) { o[j] = b0[j] + b1[j] + sigmoidf_(gt[j]) * v0[j]; o[4 + j] = b0[4 + j] + b1[4 + j] + sigmoidf_(gt[4 + j]) * v1[j]; }
.LBB0_759:
	s_mul_hi_i32 s15, s24, 0x78787879
	s_lshr_b32 s17, s15, 31
	s_lshr_b32 s15, s15, 4
	s_add_i32 s15, s15, s17
	s_mul_i32 s15, s15, 34
	s_sub_i32 s15, s24, s15
	v_lshl_add_u32 v146, s15, 8, v0
	v_lshl_or_b32 v144, s22, 8, v150
	v_mov_b64_e32 v[152:153], s[96:97]
	v_mad_i64_i32 v[142:143], s[22:23], v146, s79, v[152:153]
	s_mov_b64 s[30:31], 0x5440
	v_ashrrev_i32_e32 v145, 31, v144
	v_lshl_add_u64 v[170:171], v[142:143], 0, s[30:31]
	v_lshlrev_b64 v[142:143], 1, v[144:145]
	v_lshl_add_u64 v[154:155], v[170:171], 0, v[142:143]
	v_ashrrev_i32_e32 v147, 31, v146
	v_readlane_b32 s26, v252, 60
	v_readlane_b32 s27, v252, 61
	v_readlane_b32 s28, v252, 62
	v_readlane_b32 s29, v252, 63
	v_readlane_b32 s48, v255, 14
	v_readlane_b32 s74, v255, 13
	v_readlane_b32 s49, v255, 15
	v_readlane_b32 s50, v255, 16
	v_readlane_b32 s51, v255, 17
	v_readlane_b32 s52, v255, 18
	v_readlane_b32 s53, v255, 19
	v_readlane_b32 s54, v255, 20
	v_readlane_b32 s55, v255, 21
	v_readlane_b32 s56, v255, 22
	v_readlane_b32 s57, v255, 23
	v_readlane_b32 s58, v255, 24
	v_readlane_b32 s59, v255, 25
	v_readlane_b32 s60, v255, 26
	v_readlane_b32 s61, v255, 27
	v_readlane_b32 s62, v255, 28
	v_readlane_b32 s63, v255, 29
	v_mad_i64_i32 v[246:247], s[22:23], v146, s79, v[152:153]
	v_lshl_add_u64 v[246:247], v[246:247], 0, s[30:31]
	v_lshl_add_u64 v[246:247], v[246:247], 0, v[142:143]
	global_load_dwordx4 v[184:187], v[246:247], off
	v_mov_b32_e32 v248, v146
	v_ashrrev_i32_e32 v249, 31, v146
	v_lshlrev_b64 v[248:249], 12, v[248:249]
	v_lshl_add_u64 v[250:251], s[26:27], 0, v[248:249]
	v_lshl_add_u64 v[250:251], v[250:251], 0, v[142:143]
	global_load_dwordx4 v[214:217], v[250:251], off
	v_lshl_add_u64 v[248:249], s[90:91], 0, v[248:249]
	v_lshl_add_u64 v[248:249], v[248:249], 0, v[142:143]
	global_load_dwordx4 v[218:221], v[248:249], off
	v_mad_i64_i32 v[246:247], s[22:23], v146, s79, v[152:153]
	v_lshl_add_u64 v[246:247], v[246:247], 0, s[30:31]
	v_lshl_add_u64 v[246:247], v[246:247], 0, v[142:143]
	global_load_dwordx4 v[222:225], v[246:247], off offset:256
	v_mov_b32_e32 v248, v146
	v_ashrrev_i32_e32 v249, 31, v146
	v_lshlrev_b64 v[248:249], 12, v[248:249]
	v_lshl_add_u64 v[250:251], s[26:27], 0, v[248:249]
	v_lshl_add_u64 v[250:251], v[250:251], 0, v[142:143]
	global_load_dwordx4 v[226:229], v[250:251], off offset:256
	v_lshl_add_u64 v[248:249], s[90:91], 0, v[248:249]
	v_lshl_add_u64 v[248:249], v[248:249], 0, v[142:143]
	global_load_dwordx4 v[230:233], v[248:249], off offset:256
	v_or_b32_e32 v213, 16, v146
	v_mad_i64_i32 v[246:247], s[22:23], v213, s79, v[152:153]
	v_lshl_add_u64 v[246:247], v[246:247], 0, s[30:31]
	v_lshl_add_u64 v[246:247], v[246:247], 0, v[142:143]
	global_load_dwordx4 v[234:237], v[246:247], off
	v_mov_b32_e32 v248, v213
	v_ashrrev_i32_e32 v249, 31, v213
	v_lshlrev_b64 v[248:249], 12, v[248:249]
	v_lshl_add_u64 v[250:251], s[26:27], 0, v[248:249]
	v_lshl_add_u64 v[250:251], v[250:251], 0, v[142:143]
	global_load_dwordx4 v[238:241], v[250:251], off
	v_lshl_add_u64 v[248:249], s[90:91], 0, v[248:249]
	v_lshl_add_u64 v[248:249], v[248:249], 0, v[142:143]
	global_load_dwordx4 v[242:245], v[248:249], off
	s_waitcnt vmcnt(6)
	s_nop 1
	v_mov_b32_e32 v154, v184
	v_mov_b32_e32 v155, v185
	v_mov_b32_e32 v156, v186
	v_mov_b32_e32 v157, v187
	v_lshlrev_b32_e32 v145, 16, v154
	v_and_b32_e32 v161, 0xffff0000, v154
	v_lshlrev_b32_e32 v180, 16, v155
	v_and_b32_e32 v181, 0xffff0000, v155
	v_lshlrev_b64 v[154:155], 12, v[146:147]
	v_lshlrev_b32_e32 v173, 16, v156
	v_and_b32_e32 v175, 0xffff0000, v156
	v_lshlrev_b32_e32 v182, 16, v157
	v_and_b32_e32 v183, 0xffff0000, v157
	v_lshl_add_u64 v[156:157], s[26:27], 0, v[154:155]
	v_lshl_add_u64 v[158:159], v[156:157], 0, v[142:143]
	v_lshl_add_u64 v[156:157], s[90:91], 0, v[154:155]
	v_lshl_add_u64 v[156:157], v[156:157], 0, v[142:143]
	v_mul_f32_e32 v145, 0xbfb8aa3b, v145
	v_exp_f32_e32 v172, v145
	v_mul_f32_e32 v145, 0xbfb8aa3b, v173
	v_exp_f32_e32 v174, v145
	v_mul_f32_e32 v145, 0xbfb8aa3b, v161
	v_exp_f32_e32 v173, v145
	v_mov_b32_e32 v162, v214
	v_mov_b32_e32 v163, v215
	v_mov_b32_e32 v164, v216
	v_mov_b32_e32 v165, v217
	v_lshlrev_b32_e32 v176, 16, v162
	v_pk_add_f32 v[172:173], v[172:173], 1.0 op_sel_hi:[1,0]
	v_and_b32_e32 v177, 0xffff0000, v162
	v_div_scale_f32 v145, s[22:23], v173, v173, 1.0
	v_rcp_f32_e32 v147, v145
	v_mov_b32_e32 v166, v218
	v_mov_b32_e32 v167, v219
	v_mov_b32_e32 v168, v220
	v_mov_b32_e32 v169, v221
	v_or_b32_e32 v213, 16, v146
	v_mad_i64_i32 v[246:247], s[22:23], v213, s79, v[152:153]
	v_lshl_add_u64 v[246:247], v[246:247], 0, s[30:31]
	v_lshl_add_u64 v[246:247], v[246:247], 0, v[142:143]
	global_load_dwordx4 v[184:187], v[246:247], off offset:256
	v_mov_b32_e32 v248, v213
	v_ashrrev_i32_e32 v249, 31, v213
	v_lshlrev_b64 v[248:249], 12, v[248:249]
	v_lshl_add_u64 v[250:251], s[26:27], 0, v[248:249]
	v_lshl_add_u64 v[250:251], v[250:251], 0, v[142:143]
	global_load_dwordx4 v[214:217], v[250:251], off offset:256
	v_lshl_add_u64 v[248:249], s[90:91], 0, v[248:249]
	v_lshl_add_u64 v[248:249], v[248:249], 0, v[142:143]
	global_load_dwordx4 v[218:221], v[248:249], off offset:256
	v_lshlrev_b32_e32 v178, 16, v166
	v_and_b32_e32 v179, 0xffff0000, v166
	v_pk_add_f32 v[176:177], v[176:177], v[178:179]
	v_fma_f32 v161, -v145, v147, 1.0
	v_fmac_f32_e32 v147, v161, v147
	v_div_scale_f32 v161, vcc, 1.0, v173, 1.0
	v_mul_f32_e32 v162, v161, v147
	v_fma_f32 v166, -v145, v162, v161
	v_fmac_f32_e32 v162, v166, v147
	v_fma_f32 v145, -v145, v162, v161
	v_div_fmas_f32 v145, v145, v147, v162
	v_div_fixup_f32 v173, v145, v173, 1.0
	v_div_scale_f32 v145, s[22:23], v172, v172, 1.0
	v_rcp_f32_e32 v147, v145
	s_nop 0
; __device__ __forceinline__ unsigned pk2(float lo, float hi) { return pg8::cvt_pk_bf16(lo, hi); }
; __device__ __forceinline__ float sigmoidf_(float x) { return 1.f / (1.f + __expf(-x)); }
;     __device__ __forceinline__ void operator()(const f32x4 (&acc)[2][2][4][2], const pg8::Unit& u, int wr, int wc, int fr, int fq) const {
;     ...
;                     const f32x4 v0 = acc[ai][bj][m][0], v1 = acc[ai][bj][m][1];
;                     float o[8];
; #pragma unroll
;                     for (int j = 0; j < 4; ++j) { o[j] = b0[j] + b1[j] + sigmoidf_(gt[j]) * v0[j]; o[4 + j] = b0[4 + j] + b1[4 + j] + sigmoidf_(gt[4 + j]) * v1[j]; }
;                     u32x4 w; w.x = pk2(o[0], o[1]); w.y = pk2(o[2], o[3]); w.z = pk2(o[4], o[5]); w.w = pk2(o[6], o[7]);
;                     *(u32x4*)(mrg + (size_t)row * D + col) = w; } }
	v_fma_f32 v161, -v145, v147, 1.0
	v_fmac_f32_e32 v147, v161, v147
	v_div_scale_f32 v161, vcc, 1.0, v172, 1.0
	v_mul_f32_e32 v162, v161, v147
	v_fma_f32 v166, -v145, v162, v161
	v_fmac_f32_e32 v162, v166, v147
	v_fma_f32 v145, -v145, v162, v161
	v_div_fmas_f32 v145, v145, v147, v162
	v_div_fixup_f32 v172, v145, v172, 1.0
	v_mul_f32_e32 v145, 0xbfb8aa3b, v175
	v_exp_f32_e32 v175, v145
	v_pk_fma_f32 v[126:127], v[126:127], v[172:173], v[176:177]
	v_lshlrev_b32_e32 v172, 16, v164
	v_and_b32_e32 v173, 0xffff0000, v164
	v_pk_add_f32 v[174:175], v[174:175], 1.0 op_sel_hi:[1,0]
	v_lshlrev_b32_e32 v176, 16, v168
	v_div_scale_f32 v145, s[22:23], v175, v175, 1.0
	v_rcp_f32_e32 v147, v145
	v_and_b32_e32 v177, 0xffff0000, v168
	v_pk_add_f32 v[172:173], v[172:173], v[176:177]
	v_lshlrev_b32_e32 v166, 16, v167
	v_fma_f32 v161, -v145, v147, 1.0
	v_fmac_f32_e32 v147, v161, v147
	v_div_scale_f32 v161, vcc, 1.0, v175, 1.0
	v_mul_f32_e32 v162, v161, v147
	v_fma_f32 v164, -v145, v162, v161
	v_fmac_f32_e32 v162, v164, v147
	v_fma_f32 v145, -v145, v162, v161
	v_div_fmas_f32 v145, v145, v147, v162
	v_div_fixup_f32 v175, v145, v175, 1.0
	v_div_scale_f32 v145, s[22:23], v174, v174, 1.0
	v_rcp_f32_e32 v147, v145
	v_and_b32_e32 v167, 0xffff0000, v167
	v_fma_f32 v161, -v145, v147, 1.0
	v_fmac_f32_e32 v147, v161, v147
	v_div_scale_f32 v161, vcc, 1.0, v174, 1.0
	v_mul_f32_e32 v162, v161, v147
	v_fma_f32 v164, -v145, v162, v161
	v_fmac_f32_e32 v162, v164, v147
	v_fma_f32 v145, -v145, v162, v161
	v_div_fmas_f32 v145, v145, v147, v162
	v_div_fixup_f32 v174, v145, v174, 1.0
	v_pk_fma_f32 v[172:173], v[122:123], v[174:175], v[172:173]
	v_mul_f32_e32 v123, 0xbfb8aa3b, v182
	v_mul_f32_e32 v122, 0xbfb8aa3b, v180
	v_exp_f32_e32 v162, v123
	v_mul_f32_e32 v123, 0xbfb8aa3b, v181
	v_exp_f32_e32 v122, v122
	v_exp_f32_e32 v123, v123
	v_lshlrev_b32_e32 v174, 16, v163
	v_and_b32_e32 v175, 0xffff0000, v163
	v_pk_add_f32 v[166:167], v[174:175], v[166:167]
	v_pk_add_f32 v[122:123], v[122:123], 1.0 op_sel_hi:[1,0]
	s_nop 0
	v_div_scale_f32 v145, s[22:23], v123, v123, 1.0
	v_rcp_f32_e32 v147, v145
	s_nop 0
	v_fma_f32 v161, -v145, v147, 1.0
	v_fmac_f32_e32 v147, v161, v147
	v_div_scale_f32 v161, vcc, 1.0, v123, 1.0
	v_mul_f32_e32 v163, v161, v147
	v_fma_f32 v164, -v145, v163, v161
	v_fmac_f32_e32 v163, v164, v147
	v_fma_f32 v145, -v145, v163, v161
	v_div_fmas_f32 v145, v145, v147, v163
	v_div_fixup_f32 v123, v145, v123, 1.0
	v_div_scale_f32 v145, s[22:23], v122, v122, 1.0
	v_rcp_f32_e32 v147, v145
	s_nop 0
	v_fma_f32 v161, -v145, v147, 1.0
	v_fmac_f32_e32 v147, v161, v147
	v_div_scale_f32 v161, vcc, 1.0, v122, 1.0
	v_mul_f32_e32 v163, v161, v147
	v_fma_f32 v164, -v145, v163, v161
	v_fmac_f32_e32 v163, v164, v147
	v_fma_f32 v145, -v145, v163, v161
	v_div_fmas_f32 v145, v145, v147, v163
	v_div_fixup_f32 v122, v145, v122, 1.0
	v_pk_fma_f32 v[128:129], v[128:129], v[122:123], v[166:167]
	v_mul_f32_e32 v122, 0xbfb8aa3b, v183
	v_exp_f32_e32 v163, v122
	v_lshlrev_b32_e32 v122, 16, v165
	v_and_b32_e32 v123, 0xffff0000, v165
	v_lshlrev_b32_e32 v164, 16, v169
	v_pk_add_f32 v[162:163], v[162:163], 1.0 op_sel_hi:[1,0]
	v_and_b32_e32 v165, 0xffff0000, v169
	v_div_scale_f32 v145, s[22:23], v163, v163, 1.0
	v_rcp_f32_e32 v147, v145
	v_pk_add_f32 v[122:123], v[122:123], v[164:165]
	v_fma_f32 v161, -v145, v147, 1.0
	v_fmac_f32_e32 v147, v161, v147
	v_div_scale_f32 v161, vcc, 1.0, v163, 1.0
	v_mul_f32_e32 v164, v161, v147
	v_fma_f32 v165, -v145, v164, v161
	v_fmac_f32_e32 v164, v165, v147
	v_fma_f32 v145, -v145, v164, v161
	v_div_fmas_f32 v145, v145, v147, v164
	v_div_fixup_f32 v163, v145, v163, 1.0
	v_div_scale_f32 v145, s[22:23], v162, v162, 1.0
	v_rcp_f32_e32 v147, v145
	s_nop 0
	v_fma_f32 v161, -v145, v147, 1.0
	v_fmac_f32_e32 v147, v161, v147
	v_div_scale_f32 v161, vcc, 1.0, v162, 1.0
	v_mul_f32_e32 v164, v161, v147
	v_fma_f32 v165, -v145, v164, v161
	v_fmac_f32_e32 v164, v165, v147
	v_fma_f32 v145, -v145, v164, v161
	v_div_fmas_f32 v145, v145, v147, v164
	v_div_fixup_f32 v162, v145, v162, 1.0
	v_pk_fma_f32 v[162:163], v[124:125], v[162:163], v[122:123]
	v_cvt_pk_bf16_f32 v122, v126, v127
	v_lshl_add_u64 v[126:127], s[28:29], 0, v[154:155]
	v_cvt_pk_bf16_f32 v123, v128, v129
	v_cvt_pk_bf16_f32 v124, v172, v173
	v_cvt_pk_bf16_f32 v125, v162, v163
	v_lshl_add_u64 v[154:155], v[126:127], 0, v[142:143]
	global_store_dwordx4 v[154:155], v[122:125], off
	s_nop 1
	v_or_b32_e32 v122, 0x80, v144
	v_ashrrev_i32_e32 v123, 31, v122
	v_lshlrev_b64 v[144:145], 1, v[122:123]
	v_lshl_add_u64 v[122:123], v[170:171], 0, v[144:145]
	s_waitcnt vmcnt(7)
; __device__ __forceinline__ unsigned pk2(float lo, float hi) { return pg8::cvt_pk_bf16(lo, hi); }
; __device__ __forceinline__ float sigmoidf_(float x) { return 1.f / (1.f + __expf(-x)); }
;     __device__ __forceinline__ void operator()(const f32x4 (&acc)[2][2][4][2], const pg8::Unit& u, int wr, int wc, int fr, int fq) const {
;     ...
;                 for (int bj = 0; bj < 2; ++bj) { const int col = col0 + bj * 128;
;                     const u32x4 gw = *(const u32x4*)(P + (size_t)row * NINP + GATEOFF + 2 * 2048 + col); float gt[8]; unpack8(gw, gt);
;                     const u32x4 w0 = *(const u32x4*)(br0 + (size_t)row * D + col); float b0[8]; unpack8(w0, b0);
;                     const u32x4 w1 = *(const u32x4*)(br1 + (size_t)row * D + col); float b1[8]; unpack8(w1, b1);
;                     const f32x4 v0 = acc[ai][bj][m][0], v1 = acc[ai][bj][m][1];
;                     float o[8];
; #pragma unroll
;                     for (int j = 0; j < 4; ++j) { o[j] = b0[j] + b1[j] + sigmoidf_(gt[j]) * v0[j]; o[4 + j] = b0[4 + j] + b1[4 + j] + sigmoidf_(gt[4 + j]) * v1[j]; }
;                     u32x4 w; w.x = pk2(o[0], o[1]); w.y = pk2(o[2], o[3]); w.z = pk2(o[4], o[5]); w.w = pk2(o[6], o[7]);
;                     *(u32x4*)(mrg + (size_t)row * D + col) = w; } }
	s_nop 1
	v_mov_b32_e32 v122, v222
	v_mov_b32_e32 v123, v223
	v_mov_b32_e32 v124, v224
	v_mov_b32_e32 v125, v225
	v_lshlrev_b32_e32 v166, 16, v122
	v_and_b32_e32 v165, 0xffff0000, v122
	v_lshlrev_b32_e32 v162, 16, v123
	v_and_b32_e32 v161, 0xffff0000, v123
	v_lshlrev_b32_e32 v167, 16, v124
	v_and_b32_e32 v164, 0xffff0000, v124
	v_lshlrev_b32_e32 v163, 16, v125
	v_and_b32_e32 v147, 0xffff0000, v125
	v_mul_f32_e32 v157, 0xbfb8aa3b, v167
	v_mul_f32_e32 v156, 0xbfb8aa3b, v166
	v_exp_f32_e32 v158, v157
	v_mul_f32_e32 v157, 0xbfb8aa3b, v165
	v_exp_f32_e32 v156, v156
	v_exp_f32_e32 v157, v157
	v_mov_b32_e32 v122, v226
	v_mov_b32_e32 v123, v227
	v_mov_b32_e32 v124, v228
	v_mov_b32_e32 v125, v229
	v_lshlrev_b32_e32 v166, 16, v122
	v_pk_add_f32 v[156:157], v[156:157], 1.0 op_sel_hi:[1,0]
	v_and_b32_e32 v167, 0xffff0000, v122
	v_div_scale_f32 v122, s[22:23], v157, v157, 1.0
	v_mov_b32_e32 v126, v230
	v_mov_b32_e32 v127, v231
	v_mov_b32_e32 v128, v232
	v_mov_b32_e32 v129, v233
	v_or_b32_e32 v213, 32, v146
	v_mad_i64_i32 v[246:247], s[22:23], v213, s79, v[152:153]
	v_lshl_add_u64 v[246:247], v[246:247], 0, s[30:31]
	v_lshl_add_u64 v[246:247], v[246:247], 0, v[142:143]
	global_load_dwordx4 v[222:225], v[246:247], off
	v_mov_b32_e32 v248, v213
	v_ashrrev_i32_e32 v249, 31, v213
	v_lshlrev_b64 v[248:249], 12, v[248:249]
	v_lshl_add_u64 v[250:251], s[26:27], 0, v[248:249]
	v_lshl_add_u64 v[250:251], v[250:251], 0, v[142:143]
	global_load_dwordx4 v[226:229], v[250:251], off
	v_lshl_add_u64 v[248:249], s[90:91], 0, v[248:249]
	v_lshl_add_u64 v[248:249], v[248:249], 0, v[142:143]
	global_load_dwordx4 v[230:233], v[248:249], off
	v_lshlrev_b32_e32 v168, 16, v126
	v_and_b32_e32 v169, 0xffff0000, v126
	v_rcp_f32_e32 v126, v122
	v_pk_add_f32 v[166:167], v[166:167], v[168:169]
	v_fma_f32 v159, -v122, v126, 1.0
	v_fmac_f32_e32 v126, v159, v126
	v_div_scale_f32 v159, vcc, 1.0, v157, 1.0
	v_mul_f32_e32 v165, v159, v126
	v_fma_f32 v168, -v122, v165, v159
	v_fmac_f32_e32 v165, v168, v126
	v_fma_f32 v122, -v122, v165, v159
	v_div_fmas_f32 v122, v122, v126, v165
	v_div_fixup_f32 v157, v122, v157, 1.0
	v_div_scale_f32 v122, s[22:23], v156, v156, 1.0
	v_rcp_f32_e32 v126, v122
	s_nop 0
	v_fma_f32 v159, -v122, v126, 1.0
	v_fmac_f32_e32 v126, v159, v126
	v_div_scale_f32 v159, vcc, 1.0, v156, 1.0
	v_mul_f32_e32 v165, v159, v126
	v_fma_f32 v168, -v122, v165, v159
	v_fmac_f32_e32 v165, v168, v126
	v_fma_f32 v122, -v122, v165, v159
	v_div_fmas_f32 v122, v122, v126, v165
	v_div_fixup_f32 v156, v122, v156, 1.0
	v_mul_f32_e32 v122, 0xbfb8aa3b, v164
	v_exp_f32_e32 v159, v122
	v_pk_fma_f32 v[118:119], v[118:119], v[156:157], v[166:167]
	v_lshlrev_b32_e32 v156, 16, v124
	v_and_b32_e32 v157, 0xffff0000, v124
	v_pk_add_f32 v[158:159], v[158:159], 1.0 op_sel_hi:[1,0]
	v_lshlrev_b32_e32 v164, 16, v128
	v_div_scale_f32 v122, s[22:23], v159, v159, 1.0
	v_rcp_f32_e32 v124, v122
	v_and_b32_e32 v165, 0xffff0000, v128
	v_pk_add_f32 v[156:157], v[156:157], v[164:165]
	v_fma_f32 v126, -v122, v124, 1.0
	v_fmac_f32_e32 v124, v126, v124
	v_div_scale_f32 v126, vcc, 1.0, v159, 1.0
	v_mul_f32_e32 v128, v126, v124
	v_fma_f32 v164, -v122, v128, v126
	v_fmac_f32_e32 v128, v164, v124
	v_fma_f32 v122, -v122, v128, v126
	v_div_fmas_f32 v122, v122, v124, v128
	v_div_fixup_f32 v159, v122, v159, 1.0
	v_div_scale_f32 v122, s[22:23], v158, v158, 1.0
	v_rcp_f32_e32 v124, v122
	s_nop 0
	v_fma_f32 v126, -v122, v124, 1.0
	v_fmac_f32_e32 v124, v126, v124
	v_div_scale_f32 v126, vcc, 1.0, v158, 1.0
	v_mul_f32_e32 v128, v126, v124
	v_fma_f32 v164, -v122, v128, v126
	v_fmac_f32_e32 v128, v164, v124
	v_fma_f32 v122, -v122, v128, v126
	v_div_fmas_f32 v122, v122, v124, v128
	v_div_fixup_f32 v158, v122, v158, 1.0
	v_pk_fma_f32 v[156:157], v[114:115], v[158:159], v[156:157]
	v_mul_f32_e32 v115, 0xbfb8aa3b, v163
	v_mul_f32_e32 v114, 0xbfb8aa3b, v162
	v_exp_f32_e32 v122, v115
	v_mul_f32_e32 v115, 0xbfb8aa3b, v161
	v_exp_f32_e32 v114, v114
	v_exp_f32_e32 v115, v115
	v_lshlrev_b32_e32 v158, 16, v123
	v_and_b32_e32 v159, 0xffff0000, v123
	v_lshlrev_b32_e32 v126, 16, v127
	v_pk_add_f32 v[114:115], v[114:115], 1.0 op_sel_hi:[1,0]
	v_and_b32_e32 v127, 0xffff0000, v127
	v_div_scale_f32 v123, s[22:23], v115, v115, 1.0
	v_rcp_f32_e32 v124, v123
	v_pk_add_f32 v[126:127], v[158:159], v[126:127]
	v_fma_f32 v128, -v123, v124, 1.0
	v_fmac_f32_e32 v124, v128, v124
	v_div_scale_f32 v128, vcc, 1.0, v115, 1.0
	v_mul_f32_e32 v158, v128, v124
	v_fma_f32 v159, -v123, v158, v128
	v_fmac_f32_e32 v158, v159, v124
	v_fma_f32 v123, -v123, v158, v128
	v_div_fmas_f32 v123, v123, v124, v158
	v_div_fixup_f32 v115, v123, v115, 1.0
	v_div_scale_f32 v123, s[22:23], v114, v114, 1.0
	v_rcp_f32_e32 v124, v123
	s_nop 0
	v_fma_f32 v128, -v123, v124, 1.0
	v_fmac_f32_e32 v124, v128, v124
	v_div_scale_f32 v128, vcc, 1.0, v114, 1.0
	v_mul_f32_e32 v158, v128, v124
	v_fma_f32 v159, -v123, v158, v128
	v_fmac_f32_e32 v158, v159, v124
	v_fma_f32 v123, -v123, v158, v128
	v_div_fmas_f32 v123, v123, v124, v158
	v_div_fixup_f32 v114, v123, v114, 1.0
	v_pk_fma_f32 v[120:121], v[120:121], v[114:115], v[126:127]
	v_mul_f32_e32 v114, 0xbfb8aa3b, v147
	v_exp_f32_e32 v123, v114
	v_lshlrev_b32_e32 v114, 16, v125
	v_and_b32_e32 v115, 0xffff0000, v125
	v_lshlrev_b32_e32 v124, 16, v129
	v_and_b32_e32 v125, 0xffff0000, v129
	v_pk_add_f32 v[122:123], v[122:123], 1.0 op_sel_hi:[1,0]
	v_pk_add_f32 v[114:115], v[114:115], v[124:125]
	v_div_scale_f32 v124, s[22:23], v123, v123, 1.0
	v_rcp_f32_e32 v125, v124
	s_nop 0
	v_fma_f32 v126, -v124, v125, 1.0
	v_fmac_f32_e32 v125, v126, v125
	v_div_scale_f32 v126, vcc, 1.0, v123, 1.0
	v_mul_f32_e32 v127, v126, v125
	v_fma_f32 v128, -v124, v127, v126
	v_fmac_f32_e32 v127, v128, v125
	v_fma_f32 v124, -v124, v127, v126
	v_div_fmas_f32 v124, v124, v125, v127
	v_div_fixup_f32 v123, v124, v123, 1.0
	v_div_scale_f32 v124, s[22:23], v122, v122, 1.0
	v_rcp_f32_e32 v125, v124
	s_nop 0
	v_fma_f32 v126, -v124, v125, 1.0
	v_fmac_f32_e32 v125, v126, v125
	v_div_scale_f32 v126, vcc, 1.0, v122, 1.0
	v_mul_f32_e32 v127, v126, v125
	v_fma_f32 v128, -v124, v127, v126
	v_fmac_f32_e32 v127, v128, v125
	v_fma_f32 v124, -v124, v127, v126
	v_div_fmas_f32 v124, v124, v125, v127
	v_div_fixup_f32 v122, v124, v122, 1.0
	v_pk_fma_f32 v[122:123], v[116:117], v[122:123], v[114:115]
	v_cvt_pk_bf16_f32 v114, v118, v119
	v_cvt_pk_bf16_f32 v115, v120, v121
	v_cvt_pk_bf16_f32 v116, v156, v157
	v_cvt_pk_bf16_f32 v117, v122, v123
	v_or_b32_e32 v118, 16, v146
	global_store_dwordx4 v[154:155], v[114:117], off offset:256
	v_ashrrev_i32_e32 v119, 31, v118
	v_lshlrev_b64 v[128:129], 12, v[118:119]
	v_mad_i64_i32 v[114:115], s[22:23], v118, s79, v[152:153]
	v_lshl_add_u64 v[126:127], v[114:115], 0, s[30:31]
	v_lshl_add_u64 v[114:115], v[126:127], 0, v[142:143]
	v_lshl_add_u64 v[118:119], s[90:91], 0, v[128:129]
	v_lshl_add_u64 v[122:123], v[118:119], 0, v[142:143]
	s_waitcnt vmcnt(8)
; __device__ __forceinline__ unsigned pk2(float lo, float hi) { return pg8::cvt_pk_bf16(lo, hi); }
; __device__ __forceinline__ float sigmoidf_(float x) { return 1.f / (1.f + __expf(-x)); }
;     __device__ __forceinline__ void operator()(const f32x4 (&acc)[2][2][4][2], const pg8::Unit& u, int wr, int wc, int fr, int fq) const {
;     ...
;             for (int m = 0; m < 4; ++m) { const int row = row0 + ai * 128 + m * 16;
; #pragma unroll
;                 for (int bj = 0; bj < 2; ++bj) { const int col = col0 + bj * 128;
;                     const u32x4 gw = *(const u32x4*)(P + (size_t)row * NINP + GATEOFF + 2 * 2048 + col); float gt[8]; unpack8(gw, gt);
;                     const u32x4 w0 = *(const u32x4*)(br0 + (size_t)row * D + col); float b0[8]; unpack8(w0, b0);
;                     const u32x4 w1 = *(const u32x4*)(br1 + (size_t)row * D + col); float b1[8]; unpack8(w1, b1);
;                     const f32x4 v0 = acc[ai][bj][m][0], v1 = acc[ai][bj][m][1];
;                     float o[8];
; #pragma unroll
;                     for (int j = 0; j < 4; ++j) { o[j] = b0[j] + b1[j] + sigmoidf_(gt[j]) * v0[j]; o[4 + j] = b0[4 + j] + b1[4 + j] + sigmoidf_(gt[4 + j]) * v1[j]; }
;                     u32x4 w; w.x = pk2(o[0], o[1]); w.y = pk2(o[2], o[3]); w.z = pk2(o[4], o[5]); w.w = pk2(o[6], o[7]);
;                     *(u32x4*)(mrg + (size_t)row * D + col) = w; } }
	s_nop 1
	v_mov_b32_e32 v114, v234
	v_mov_b32_e32 v115, v235
	v_mov_b32_e32 v116, v236
	v_mov_b32_e32 v117, v237
	v_lshlrev_b32_e32 v147, 16, v114
	v_and_b32_e32 v155, 0xffff0000, v114
	v_lshlrev_b32_e32 v161, 16, v115
	v_and_b32_e32 v164, 0xffff0000, v115
	v_lshl_add_u64 v[114:115], s[26:27], 0, v[128:129]
	v_lshl_add_u64 v[124:125], v[114:115], 0, v[142:143]
	v_lshlrev_b32_e32 v156, 16, v116
	v_and_b32_e32 v157, 0xffff0000, v116
	v_lshlrev_b32_e32 v165, 16, v117
	v_and_b32_e32 v166, 0xffff0000, v117
	v_mul_f32_e32 v147, 0xbfb8aa3b, v147
	v_exp_f32_e32 v154, v147
	v_mul_f32_e32 v147, 0xbfb8aa3b, v156
	v_exp_f32_e32 v156, v147
	v_mul_f32_e32 v147, 0xbfb8aa3b, v155
	v_exp_f32_e32 v155, v147
	v_mov_b32_e32 v118, v238
	v_mov_b32_e32 v119, v239
	v_mov_b32_e32 v120, v240
	v_mov_b32_e32 v121, v241
	v_lshlrev_b32_e32 v162, 16, v118
	v_and_b32_e32 v163, 0xffff0000, v118
	v_pk_add_f32 v[154:155], v[154:155], 1.0 op_sel_hi:[1,0]
	v_mov_b32_e32 v114, v242
	v_mov_b32_e32 v115, v243
	v_mov_b32_e32 v116, v244
	v_mov_b32_e32 v117, v245
	v_or_b32_e32 v213, 32, v146
	v_mad_i64_i32 v[246:247], s[22:23], v213, s79, v[152:153]
	v_lshl_add_u64 v[246:247], v[246:247], 0, s[30:31]
	v_lshl_add_u64 v[246:247], v[246:247], 0, v[142:143]
	global_load_dwordx4 v[234:237], v[246:247], off offset:256
	v_mov_b32_e32 v248, v213
	v_ashrrev_i32_e32 v249, 31, v213
	v_lshlrev_b64 v[248:249], 12, v[248:249]
	v_lshl_add_u64 v[250:251], s[26:27], 0, v[248:249]
	v_lshl_add_u64 v[250:251], v[250:251], 0, v[142:143]
	global_load_dwordx4 v[238:241], v[250:251], off offset:256
	v_lshl_add_u64 v[248:249], s[90:91], 0, v[248:249]
	v_lshl_add_u64 v[248:249], v[248:249], 0, v[142:143]
	global_load_dwordx4 v[242:245], v[248:249], off offset:256
	v_lshlrev_b32_e32 v158, 16, v114
	v_and_b32_e32 v159, 0xffff0000, v114
	v_div_scale_f32 v114, s[22:23], v155, v155, 1.0
	v_rcp_f32_e32 v118, v114
	v_pk_add_f32 v[158:159], v[158:159], v[162:163]
	v_fma_f32 v147, -v114, v118, 1.0
	v_fmac_f32_e32 v118, v147, v118
	v_div_scale_f32 v147, vcc, 1.0, v155, 1.0
	v_mul_f32_e32 v162, v147, v118
	v_fma_f32 v163, -v114, v162, v147
	v_fmac_f32_e32 v162, v163, v118
	v_fma_f32 v114, -v114, v162, v147
	v_div_fmas_f32 v114, v114, v118, v162
	v_div_fixup_f32 v155, v114, v155, 1.0
	v_div_scale_f32 v114, s[22:23], v154, v154, 1.0
	v_rcp_f32_e32 v118, v114
	s_nop 0
	v_fma_f32 v147, -v114, v118, 1.0
	v_fmac_f32_e32 v118, v147, v118
	v_div_scale_f32 v147, vcc, 1.0, v154, 1.0
	v_mul_f32_e32 v162, v147, v118
	v_fma_f32 v163, -v114, v162, v147
	v_fmac_f32_e32 v162, v163, v118
	v_fma_f32 v114, -v114, v162, v147
	v_div_fmas_f32 v114, v114, v118, v162
	v_div_fixup_f32 v154, v114, v154, 1.0
	v_mul_f32_e32 v114, 0xbfb8aa3b, v157
	v_exp_f32_e32 v157, v114
	v_pk_fma_f32 v[110:111], v[110:111], v[154:155], v[158:159]
	v_lshlrev_b32_e32 v154, 16, v116
	v_and_b32_e32 v155, 0xffff0000, v116
	v_pk_add_f32 v[156:157], v[156:157], 1.0 op_sel_hi:[1,0]
	v_lshlrev_b32_e32 v158, 16, v120
	v_div_scale_f32 v114, s[22:23], v157, v157, 1.0
	v_rcp_f32_e32 v116, v114
	v_and_b32_e32 v159, 0xffff0000, v120
	v_pk_add_f32 v[154:155], v[154:155], v[158:159]
	v_fma_f32 v118, -v114, v116, 1.0
	v_fmac_f32_e32 v116, v118, v116
	v_div_scale_f32 v118, vcc, 1.0, v157, 1.0
	v_mul_f32_e32 v120, v118, v116
	v_fma_f32 v147, -v114, v120, v118
	v_fmac_f32_e32 v120, v147, v116
	v_fma_f32 v114, -v114, v120, v118
	v_div_fmas_f32 v114, v114, v116, v120
	v_div_fixup_f32 v157, v114, v157, 1.0
	v_div_scale_f32 v114, s[22:23], v156, v156, 1.0
	v_rcp_f32_e32 v116, v114
	s_nop 0
	v_fma_f32 v118, -v114, v116, 1.0
	v_fmac_f32_e32 v116, v118, v116
	v_div_scale_f32 v118, vcc, 1.0, v156, 1.0
	v_mul_f32_e32 v120, v118, v116
	v_fma_f32 v147, -v114, v120, v118
	v_fmac_f32_e32 v120, v147, v116
	v_fma_f32 v114, -v114, v120, v118
	v_div_fmas_f32 v114, v114, v116, v120
	v_div_fixup_f32 v156, v114, v156, 1.0
	v_pk_fma_f32 v[154:155], v[106:107], v[156:157], v[154:155]
	v_mul_f32_e32 v107, 0xbfb8aa3b, v165
	v_mul_f32_e32 v106, 0xbfb8aa3b, v161
	v_exp_f32_e32 v114, v107
	v_mul_f32_e32 v107, 0xbfb8aa3b, v164
	v_exp_f32_e32 v106, v106
	v_exp_f32_e32 v107, v107
	v_lshlrev_b32_e32 v156, 16, v115
	v_and_b32_e32 v157, 0xffff0000, v115
	v_lshlrev_b32_e32 v118, 16, v119
	v_pk_add_f32 v[106:107], v[106:107], 1.0 op_sel_hi:[1,0]
	v_and_b32_e32 v119, 0xffff0000, v119
	v_div_scale_f32 v115, s[22:23], v107, v107, 1.0
	v_rcp_f32_e32 v116, v115
	v_pk_add_f32 v[118:119], v[156:157], v[118:119]
	v_fma_f32 v120, -v115, v116, 1.0
	v_fmac_f32_e32 v116, v120, v116
	v_div_scale_f32 v120, vcc, 1.0, v107, 1.0
	v_mul_f32_e32 v147, v120, v116
	v_fma_f32 v156, -v115, v147, v120
	v_fmac_f32_e32 v147, v156, v116
	v_fma_f32 v115, -v115, v147, v120
	v_div_fmas_f32 v115, v115, v116, v147
	v_div_fixup_f32 v107, v115, v107, 1.0
	v_div_scale_f32 v115, s[22:23], v106, v106, 1.0
	v_rcp_f32_e32 v116, v115
	s_nop 0
	v_fma_f32 v120, -v115, v116, 1.0
	v_fmac_f32_e32 v116, v120, v116
	v_div_scale_f32 v120, vcc, 1.0, v106, 1.0
	v_mul_f32_e32 v147, v120, v116
	v_fma_f32 v156, -v115, v147, v120
	v_fmac_f32_e32 v147, v156, v116
	v_fma_f32 v115, -v115, v147, v120
	v_div_fmas_f32 v115, v115, v116, v147
	v_div_fixup_f32 v106, v115, v106, 1.0
	v_pk_fma_f32 v[112:113], v[112:113], v[106:107], v[118:119]
	v_mul_f32_e32 v106, 0xbfb8aa3b, v166
	v_exp_f32_e32 v115, v106
	v_lshlrev_b32_e32 v106, 16, v117
	v_and_b32_e32 v107, 0xffff0000, v117
	v_lshlrev_b32_e32 v116, 16, v121
	v_and_b32_e32 v117, 0xffff0000, v121
	v_pk_add_f32 v[114:115], v[114:115], 1.0 op_sel_hi:[1,0]
	v_pk_add_f32 v[106:107], v[106:107], v[116:117]
	v_div_scale_f32 v116, s[22:23], v115, v115, 1.0
	v_rcp_f32_e32 v117, v116
	s_nop 0
	v_fma_f32 v118, -v116, v117, 1.0
	v_fmac_f32_e32 v117, v118, v117
	v_div_scale_f32 v118, vcc, 1.0, v115, 1.0
	v_mul_f32_e32 v119, v118, v117
	v_fma_f32 v120, -v116, v119, v118
	v_fmac_f32_e32 v119, v120, v117
	v_fma_f32 v116, -v116, v119, v118
	v_div_fmas_f32 v116, v116, v117, v119
	v_div_fixup_f32 v115, v116, v115, 1.0
	v_div_scale_f32 v116, s[22:23], v114, v114, 1.0
	v_rcp_f32_e32 v117, v116
	s_nop 0
	v_fma_f32 v118, -v116, v117, 1.0
	v_fmac_f32_e32 v117, v118, v117
	v_div_scale_f32 v118, vcc, 1.0, v114, 1.0
	v_mul_f32_e32 v119, v118, v117
	v_fma_f32 v120, -v116, v119, v118
	v_fmac_f32_e32 v119, v120, v117
	v_fma_f32 v116, -v116, v119, v118
	v_div_fmas_f32 v116, v116, v117, v119
	v_div_fixup_f32 v114, v116, v114, 1.0
	v_pk_fma_f32 v[114:115], v[108:109], v[114:115], v[106:107]
	v_cvt_pk_bf16_f32 v106, v110, v111
	v_lshl_add_u64 v[110:111], s[28:29], 0, v[128:129]
	v_cvt_pk_bf16_f32 v107, v112, v113
	v_cvt_pk_bf16_f32 v108, v154, v155
	v_cvt_pk_bf16_f32 v109, v114, v115
	v_lshl_add_u64 v[114:115], v[110:111], 0, v[142:143]
	global_store_dwordx4 v[114:115], v[106:109], off
	s_nop 1
	v_lshl_add_u64 v[106:107], v[126:127], 0, v[144:145]
	s_waitcnt vmcnt(9)
; __device__ __forceinline__ unsigned pk2(float lo, float hi) { return pg8::cvt_pk_bf16(lo, hi); }
; __device__ __forceinline__ float sigmoidf_(float x) { return 1.f / (1.f + __expf(-x)); }
;     __device__ __forceinline__ void operator()(const f32x4 (&acc)[2][2][4][2], const pg8::Unit& u, int wr, int wc, int fr, int fq) const {
;     ...
;             for (int m = 0; m < 4; ++m) { const int row = row0 + ai * 128 + m * 16;
; #pragma unroll
;                 for (int bj = 0; bj < 2; ++bj) { const int col = col0 + bj * 128;
;                     const u32x4 gw = *(const u32x4*)(P + (size_t)row * NINP + GATEOFF + 2 * 2048 + col); float gt[8]; unpack8(gw, gt);
;                     const u32x4 w0 = *(const u32x4*)(br0 + (size_t)row * D + col); float b0[8]; unpack8(w0, b0);
;                     const u32x4 w1 = *(const u32x4*)(br1 + (size_t)row * D + col); float b1[8]; unpack8(w1, b1);
;                     const f32x4 v0 = acc[ai][bj][m][0], v1 = acc[ai][bj][m][1];
;                     float o[8];
; #pragma unroll
;                     for (int j = 0; j < 4; ++j) { o[j] = b0[j] + b1[j] + sigmoidf_(gt[j]) * v0[j]; o[4 + j] = b0[4 + j] + b1[4 + j] + sigmoidf_(gt[4 + j]) * v1[j]; }
;                     u32x4 w; w.x = pk2(o[0], o[1]); w.y = pk2(o[2], o[3]); w.z = pk2(o[4], o[5]); w.w = pk2(o[6], o[7]);
;                     *(u32x4*)(mrg + (size_t)row * D + col) = w; } }
	s_nop 1
	v_mov_b32_e32 v106, v184
	v_mov_b32_e32 v107, v185
	v_mov_b32_e32 v108, v186
	v_mov_b32_e32 v109, v187
	v_lshlrev_b32_e32 v126, 16, v106
	v_and_b32_e32 v121, 0xffff0000, v106
	v_lshlrev_b32_e32 v118, 16, v107
	v_and_b32_e32 v117, 0xffff0000, v107
	v_lshlrev_b32_e32 v127, 16, v108
	v_and_b32_e32 v120, 0xffff0000, v108
	v_lshlrev_b32_e32 v119, 16, v109
	v_and_b32_e32 v116, 0xffff0000, v109
	v_mul_f32_e32 v122, 0xbfb8aa3b, v126
	v_mul_f32_e32 v123, 0xbfb8aa3b, v127
	v_mul_f32_e32 v121, 0xbfb8aa3b, v121
	v_exp_f32_e32 v122, v122
	v_exp_f32_e32 v124, v123
	v_exp_f32_e32 v123, v121
	v_mov_b32_e32 v106, v214
	v_mov_b32_e32 v107, v215
	v_mov_b32_e32 v108, v216
	v_mov_b32_e32 v109, v217
	v_lshlrev_b32_e32 v126, 16, v106
	v_pk_add_f32 v[122:123], v[122:123], 1.0 op_sel_hi:[1,0]
	v_and_b32_e32 v127, 0xffff0000, v106
	v_div_scale_f32 v106, s[22:23], v123, v123, 1.0
	v_mov_b32_e32 v110, v218
	v_mov_b32_e32 v111, v219
	v_mov_b32_e32 v112, v220
	v_mov_b32_e32 v113, v221
	v_or_b32_e32 v213, 48, v146
	v_mad_i64_i32 v[246:247], s[22:23], v213, s79, v[152:153]
	v_lshl_add_u64 v[246:247], v[246:247], 0, s[30:31]
	v_lshl_add_u64 v[246:247], v[246:247], 0, v[142:143]
	global_load_dwordx4 v[184:187], v[246:247], off
	v_mov_b32_e32 v248, v213
	v_ashrrev_i32_e32 v249, 31, v213
	v_lshlrev_b64 v[248:249], 12, v[248:249]
	v_lshl_add_u64 v[250:251], s[26:27], 0, v[248:249]
	v_lshl_add_u64 v[250:251], v[250:251], 0, v[142:143]
	global_load_dwordx4 v[214:217], v[250:251], off
	v_lshl_add_u64 v[248:249], s[90:91], 0, v[248:249]
	v_lshl_add_u64 v[248:249], v[248:249], 0, v[142:143]
	global_load_dwordx4 v[218:221], v[248:249], off
	v_lshlrev_b32_e32 v128, 16, v110
	v_and_b32_e32 v129, 0xffff0000, v110
	v_rcp_f32_e32 v110, v106
	v_pk_add_f32 v[126:127], v[126:127], v[128:129]
	v_fma_f32 v121, -v106, v110, 1.0
	v_fmac_f32_e32 v110, v121, v110
	v_div_scale_f32 v121, vcc, 1.0, v123, 1.0
	v_mul_f32_e32 v125, v121, v110
	v_fma_f32 v128, -v106, v125, v121
	v_fmac_f32_e32 v125, v128, v110
	v_fma_f32 v106, -v106, v125, v121
	v_div_fmas_f32 v106, v106, v110, v125
	v_div_fixup_f32 v123, v106, v123, 1.0
	v_div_scale_f32 v106, s[22:23], v122, v122, 1.0
	v_rcp_f32_e32 v110, v106
	s_nop 0
	v_fma_f32 v121, -v106, v110, 1.0
	v_fmac_f32_e32 v110, v121, v110
	v_div_scale_f32 v121, vcc, 1.0, v122, 1.0
	v_mul_f32_e32 v125, v121, v110
	v_fma_f32 v128, -v106, v125, v121
	v_fmac_f32_e32 v125, v128, v110
	v_fma_f32 v106, -v106, v125, v121
	v_div_fmas_f32 v106, v106, v110, v125
	v_div_fixup_f32 v122, v106, v122, 1.0
	v_mul_f32_e32 v106, 0xbfb8aa3b, v120
	v_exp_f32_e32 v125, v106
	v_pk_fma_f32 v[102:103], v[102:103], v[122:123], v[126:127]
	v_lshlrev_b32_e32 v120, 16, v108
	v_and_b32_e32 v121, 0xffff0000, v108
	v_lshlrev_b32_e32 v122, 16, v112
	v_and_b32_e32 v123, 0xffff0000, v112
	v_pk_add_f32 v[120:121], v[120:121], v[122:123]
	v_pk_add_f32 v[122:123], v[124:125], 1.0 op_sel_hi:[1,0]
	s_nop 0
	v_div_scale_f32 v106, s[22:23], v123, v123, 1.0
	v_rcp_f32_e32 v108, v106
	s_nop 0
	v_fma_f32 v110, -v106, v108, 1.0
	v_fmac_f32_e32 v108, v110, v108
	v_div_scale_f32 v110, vcc, 1.0, v123, 1.0
	v_mul_f32_e32 v112, v110, v108
	v_fma_f32 v124, -v106, v112, v110
	v_fmac_f32_e32 v112, v124, v108
	v_fma_f32 v106, -v106, v112, v110
	v_div_fmas_f32 v106, v106, v108, v112
	v_div_fixup_f32 v123, v106, v123, 1.0
	v_div_scale_f32 v106, s[22:23], v122, v122, 1.0
	v_rcp_f32_e32 v108, v106
	s_nop 0
	v_fma_f32 v110, -v106, v108, 1.0
	v_fmac_f32_e32 v108, v110, v108
	v_div_scale_f32 v110, vcc, 1.0, v122, 1.0
	v_mul_f32_e32 v112, v110, v108
	v_fma_f32 v124, -v106, v112, v110
	v_fmac_f32_e32 v112, v124, v108
	v_fma_f32 v106, -v106, v112, v110
	v_div_fmas_f32 v106, v106, v108, v112
	v_div_fixup_f32 v122, v106, v122, 1.0
	v_pk_fma_f32 v[120:121], v[98:99], v[122:123], v[120:121]
	v_mul_f32_e32 v99, 0xbfb8aa3b, v119
	v_mul_f32_e32 v98, 0xbfb8aa3b, v118
	v_exp_f32_e32 v106, v99
	v_mul_f32_e32 v99, 0xbfb8aa3b, v117
	v_exp_f32_e32 v98, v98
	v_exp_f32_e32 v99, v99
	v_lshlrev_b32_e32 v118, 16, v107
	v_and_b32_e32 v119, 0xffff0000, v107
	v_lshlrev_b32_e32 v110, 16, v111
	v_pk_add_f32 v[98:99], v[98:99], 1.0 op_sel_hi:[1,0]
	v_and_b32_e32 v111, 0xffff0000, v111
	v_div_scale_f32 v107, s[22:23], v99, v99, 1.0
	v_rcp_f32_e32 v108, v107
	v_pk_add_f32 v[110:111], v[118:119], v[110:111]
	v_fma_f32 v112, -v107, v108, 1.0
	v_fmac_f32_e32 v108, v112, v108
	v_div_scale_f32 v112, vcc, 1.0, v99, 1.0
	v_mul_f32_e32 v117, v112, v108
	v_fma_f32 v118, -v107, v117, v112
	v_fmac_f32_e32 v117, v118, v108
	v_fma_f32 v107, -v107, v117, v112
	v_div_fmas_f32 v107, v107, v108, v117
	v_div_fixup_f32 v99, v107, v99, 1.0
	v_div_scale_f32 v107, s[22:23], v98, v98, 1.0
	v_rcp_f32_e32 v108, v107
	s_nop 0
	v_fma_f32 v112, -v107, v108, 1.0
	v_fmac_f32_e32 v108, v112, v108
	v_div_scale_f32 v112, vcc, 1.0, v98, 1.0
	v_mul_f32_e32 v117, v112, v108
	v_fma_f32 v118, -v107, v117, v112
	v_fmac_f32_e32 v117, v118, v108
	v_fma_f32 v107, -v107, v117, v112
	v_div_fmas_f32 v107, v107, v108, v117
	v_div_fixup_f32 v98, v107, v98, 1.0
	v_pk_fma_f32 v[104:105], v[104:105], v[98:99], v[110:111]
	v_mul_f32_e32 v98, 0xbfb8aa3b, v116
	v_exp_f32_e32 v107, v98
	v_lshlrev_b32_e32 v98, 16, v109
	v_and_b32_e32 v99, 0xffff0000, v109
	v_lshlrev_b32_e32 v108, 16, v113
	v_and_b32_e32 v109, 0xffff0000, v113
	v_pk_add_f32 v[106:107], v[106:107], 1.0 op_sel_hi:[1,0]
	v_pk_add_f32 v[98:99], v[98:99], v[108:109]
	v_div_scale_f32 v108, s[22:23], v107, v107, 1.0
	v_rcp_f32_e32 v109, v108
	s_nop 0
	v_fma_f32 v110, -v108, v109, 1.0
	v_fmac_f32_e32 v109, v110, v109
	v_div_scale_f32 v110, vcc, 1.0, v107, 1.0
	v_mul_f32_e32 v111, v110, v109
	v_fma_f32 v112, -v108, v111, v110
	v_fmac_f32_e32 v111, v112, v109
	v_fma_f32 v108, -v108, v111, v110
	v_div_fmas_f32 v108, v108, v109, v111
	v_div_fixup_f32 v107, v108, v107, 1.0
	v_div_scale_f32 v108, s[22:23], v106, v106, 1.0
	v_rcp_f32_e32 v109, v108
	s_nop 0
	v_fma_f32 v110, -v108, v109, 1.0
	v_fmac_f32_e32 v109, v110, v109
	v_div_scale_f32 v110, vcc, 1.0, v106, 1.0
	v_mul_f32_e32 v111, v110, v109
	v_fma_f32 v112, -v108, v111, v110
	v_fmac_f32_e32 v111, v112, v109
	v_fma_f32 v108, -v108, v111, v110
	v_div_fmas_f32 v108, v108, v109, v111
	v_div_fixup_f32 v106, v108, v106, 1.0
	v_pk_fma_f32 v[106:107], v[100:101], v[106:107], v[98:99]
	v_cvt_pk_bf16_f32 v98, v102, v103
	v_cvt_pk_bf16_f32 v99, v104, v105
	v_cvt_pk_bf16_f32 v100, v120, v121
	v_cvt_pk_bf16_f32 v101, v106, v107
	v_or_b32_e32 v102, 32, v146
	global_store_dwordx4 v[114:115], v[98:101], off offset:256
	v_ashrrev_i32_e32 v103, 31, v102
	v_lshlrev_b64 v[112:113], 12, v[102:103]
	v_mad_i64_i32 v[98:99], s[22:23], v102, s79, v[152:153]
	v_lshl_add_u64 v[110:111], v[98:99], 0, s[30:31]
	v_lshl_add_u64 v[98:99], v[110:111], 0, v[142:143]
	v_lshl_add_u64 v[102:103], s[90:91], 0, v[112:113]
	v_lshl_add_u64 v[106:107], v[102:103], 0, v[142:143]
	s_waitcnt vmcnt(9)
; __device__ __forceinline__ unsigned pk2(float lo, float hi) { return pg8::cvt_pk_bf16(lo, hi); }
; __device__ __forceinline__ float sigmoidf_(float x) { return 1.f / (1.f + __expf(-x)); }
;     __device__ __forceinline__ void operator()(const f32x4 (&acc)[2][2][4][2], const pg8::Unit& u, int wr, int wc, int fr, int fq) const {
;     ...
;             for (int m = 0; m < 4; ++m) { const int row = row0 + ai * 128 + m * 16;
; #pragma unroll
;                 for (int bj = 0; bj < 2; ++bj) { const int col = col0 + bj * 128;
;                     const u32x4 gw = *(const u32x4*)(P + (size_t)row * NINP + GATEOFF + 2 * 2048 + col); float gt[8]; unpack8(gw, gt);
;                     const u32x4 w0 = *(const u32x4*)(br0 + (size_t)row * D + col); float b0[8]; unpack8(w0, b0);
;                     const u32x4 w1 = *(const u32x4*)(br1 + (size_t)row * D + col); float b1[8]; unpack8(w1, b1);
;                     const f32x4 v0 = acc[ai][bj][m][0], v1 = acc[ai][bj][m][1];
;                     float o[8];
; #pragma unroll
;                     for (int j = 0; j < 4; ++j) { o[j] = b0[j] + b1[j] + sigmoidf_(gt[j]) * v0[j]; o[4 + j] = b0[4 + j] + b1[4 + j] + sigmoidf_(gt[4 + j]) * v1[j]; }
;                     u32x4 w; w.x = pk2(o[0], o[1]); w.y = pk2(o[2], o[3]); w.z = pk2(o[4], o[5]); w.w = pk2(o[6], o[7]);
;                     *(u32x4*)(mrg + (size_t)row * D + col) = w; } }
	s_nop 1
	v_mov_b32_e32 v98, v222
	v_mov_b32_e32 v99, v223
	v_mov_b32_e32 v100, v224
	v_mov_b32_e32 v101, v225
	v_lshlrev_b32_e32 v114, 16, v98
	v_and_b32_e32 v115, 0xffff0000, v98
	v_lshlrev_b32_e32 v122, 16, v99
	v_and_b32_e32 v123, 0xffff0000, v99
	v_lshl_add_u64 v[98:99], s[26:27], 0, v[112:113]
	v_lshl_add_u64 v[108:109], v[98:99], 0, v[142:143]
	v_lshlrev_b32_e32 v116, 16, v100
	v_and_b32_e32 v117, 0xffff0000, v100
	v_lshlrev_b32_e32 v124, 16, v101
	v_and_b32_e32 v125, 0xffff0000, v101
	v_mul_f32_e32 v114, 0xbfb8aa3b, v114
	v_mul_f32_e32 v115, 0xbfb8aa3b, v115
	v_exp_f32_e32 v114, v114
	v_exp_f32_e32 v115, v115
	v_mov_b32_e32 v102, v226
	v_mov_b32_e32 v103, v227
	v_mov_b32_e32 v104, v228
	v_mov_b32_e32 v105, v229
	v_lshlrev_b32_e32 v120, 16, v102
	v_and_b32_e32 v121, 0xffff0000, v102
	v_mul_f32_e32 v116, 0xbfb8aa3b, v116
	v_pk_add_f32 v[114:115], v[114:115], 1.0 op_sel_hi:[1,0]
	v_exp_f32_e32 v116, v116
	v_mov_b32_e32 v98, v230
	v_mov_b32_e32 v99, v231
	v_mov_b32_e32 v100, v232
	v_mov_b32_e32 v101, v233
	v_or_b32_e32 v213, 48, v146
	v_mad_i64_i32 v[246:247], s[22:23], v213, s79, v[152:153]
	v_lshl_add_u64 v[246:247], v[246:247], 0, s[30:31]
	v_lshl_add_u64 v[246:247], v[246:247], 0, v[142:143]
	global_load_dwordx4 v[222:225], v[246:247], off offset:256
	v_mov_b32_e32 v248, v213
	v_ashrrev_i32_e32 v249, 31, v213
	v_lshlrev_b64 v[248:249], 12, v[248:249]
	v_lshl_add_u64 v[250:251], s[26:27], 0, v[248:249]
	v_lshl_add_u64 v[250:251], v[250:251], 0, v[142:143]
	global_load_dwordx4 v[226:229], v[250:251], off offset:256
	v_lshl_add_u64 v[248:249], s[90:91], 0, v[248:249]
	v_lshl_add_u64 v[248:249], v[248:249], 0, v[142:143]
	global_load_dwordx4 v[230:233], v[248:249], off offset:256
	v_lshlrev_b32_e32 v118, 16, v98
	v_and_b32_e32 v119, 0xffff0000, v98
	v_div_scale_f32 v98, s[22:23], v115, v115, 1.0
	v_rcp_f32_e32 v102, v98
	v_pk_add_f32 v[118:119], v[118:119], v[120:121]
	v_fma_f32 v120, -v98, v102, 1.0
	v_fmac_f32_e32 v102, v120, v102
	v_div_scale_f32 v120, vcc, 1.0, v115, 1.0
	v_mul_f32_e32 v121, v120, v102
	v_fma_f32 v126, -v98, v121, v120
	v_fmac_f32_e32 v121, v126, v102
	v_fma_f32 v98, -v98, v121, v120
	v_div_fmas_f32 v98, v98, v102, v121
	v_div_fixup_f32 v115, v98, v115, 1.0
	v_div_scale_f32 v98, s[22:23], v114, v114, 1.0
	v_rcp_f32_e32 v102, v98
	s_nop 0
	v_fma_f32 v120, -v98, v102, 1.0
	v_fmac_f32_e32 v102, v120, v102
	v_div_scale_f32 v120, vcc, 1.0, v114, 1.0
	v_mul_f32_e32 v121, v120, v102
	v_fma_f32 v126, -v98, v121, v120
	v_fmac_f32_e32 v121, v126, v102
	v_fma_f32 v98, -v98, v121, v120
	v_div_fmas_f32 v98, v98, v102, v121
	v_div_fixup_f32 v114, v98, v114, 1.0
	v_mul_f32_e32 v98, 0xbfb8aa3b, v117
	v_exp_f32_e32 v117, v98
	v_pk_fma_f32 v[94:95], v[94:95], v[114:115], v[118:119]
	v_lshlrev_b32_e32 v114, 16, v100
	v_and_b32_e32 v115, 0xffff0000, v100
	v_pk_add_f32 v[116:117], v[116:117], 1.0 op_sel_hi:[1,0]
	v_lshlrev_b32_e32 v118, 16, v104
	v_div_scale_f32 v98, s[22:23], v117, v117, 1.0
	v_rcp_f32_e32 v100, v98
	v_and_b32_e32 v119, 0xffff0000, v104
	v_pk_add_f32 v[114:115], v[114:115], v[118:119]
	v_fma_f32 v102, -v98, v100, 1.0
	v_fmac_f32_e32 v100, v102, v100
	v_div_scale_f32 v102, vcc, 1.0, v117, 1.0
	v_mul_f32_e32 v104, v102, v100
	v_fma_f32 v118, -v98, v104, v102
	v_fmac_f32_e32 v104, v118, v100
	v_fma_f32 v98, -v98, v104, v102
	v_div_fmas_f32 v98, v98, v100, v104
	v_div_fixup_f32 v117, v98, v117, 1.0
	v_div_scale_f32 v98, s[22:23], v116, v116, 1.0
	v_rcp_f32_e32 v100, v98
	s_nop 0
	v_fma_f32 v102, -v98, v100, 1.0
	v_fmac_f32_e32 v100, v102, v100
	v_div_scale_f32 v102, vcc, 1.0, v116, 1.0
	v_mul_f32_e32 v104, v102, v100
	v_fma_f32 v118, -v98, v104, v102
	v_fmac_f32_e32 v104, v118, v100
	v_fma_f32 v98, -v98, v104, v102
	v_div_fmas_f32 v98, v98, v100, v104
	v_div_fixup_f32 v116, v98, v116, 1.0
	v_pk_fma_f32 v[114:115], v[90:91], v[116:117], v[114:115]
	v_mul_f32_e32 v91, 0xbfb8aa3b, v124
	v_mul_f32_e32 v90, 0xbfb8aa3b, v122
	v_exp_f32_e32 v98, v91
	v_mul_f32_e32 v91, 0xbfb8aa3b, v123
	v_exp_f32_e32 v90, v90
	v_exp_f32_e32 v91, v91
	v_lshlrev_b32_e32 v116, 16, v99
	v_and_b32_e32 v117, 0xffff0000, v99
	v_lshlrev_b32_e32 v102, 16, v103
	v_pk_add_f32 v[90:91], v[90:91], 1.0 op_sel_hi:[1,0]
	v_and_b32_e32 v103, 0xffff0000, v103
	v_div_scale_f32 v99, s[22:23], v91, v91, 1.0
	v_rcp_f32_e32 v100, v99
	v_pk_add_f32 v[102:103], v[116:117], v[102:103]
	v_fma_f32 v104, -v99, v100, 1.0
	v_fmac_f32_e32 v100, v104, v100
	v_div_scale_f32 v104, vcc, 1.0, v91, 1.0
	v_mul_f32_e32 v116, v104, v100
	v_fma_f32 v117, -v99, v116, v104
	v_fmac_f32_e32 v116, v117, v100
	v_fma_f32 v99, -v99, v116, v104
	v_div_fmas_f32 v99, v99, v100, v116
	v_div_fixup_f32 v91, v99, v91, 1.0
	v_div_scale_f32 v99, s[22:23], v90, v90, 1.0
	v_rcp_f32_e32 v100, v99
	s_nop 0
	v_fma_f32 v104, -v99, v100, 1.0
	v_fmac_f32_e32 v100, v104, v100
	v_div_scale_f32 v104, vcc, 1.0, v90, 1.0
	v_mul_f32_e32 v116, v104, v100
	v_fma_f32 v117, -v99, v116, v104
	v_fmac_f32_e32 v116, v117, v100
	v_fma_f32 v99, -v99, v116, v104
	v_div_fmas_f32 v99, v99, v100, v116
	v_div_fixup_f32 v90, v99, v90, 1.0
	v_pk_fma_f32 v[96:97], v[96:97], v[90:91], v[102:103]
	v_mul_f32_e32 v90, 0xbfb8aa3b, v125
	v_exp_f32_e32 v99, v90
	v_lshlrev_b32_e32 v90, 16, v101
	v_and_b32_e32 v91, 0xffff0000, v101
	v_lshlrev_b32_e32 v100, 16, v105
	v_and_b32_e32 v101, 0xffff0000, v105
	v_pk_add_f32 v[98:99], v[98:99], 1.0 op_sel_hi:[1,0]
	v_pk_add_f32 v[90:91], v[90:91], v[100:101]
	v_div_scale_f32 v100, s[22:23], v99, v99, 1.0
	v_rcp_f32_e32 v101, v100
	s_nop 0
	v_fma_f32 v102, -v100, v101, 1.0
	v_fmac_f32_e32 v101, v102, v101
	v_div_scale_f32 v102, vcc, 1.0, v99, 1.0
	v_mul_f32_e32 v103, v102, v101
	v_fma_f32 v104, -v100, v103, v102
	v_fmac_f32_e32 v103, v104, v101
	v_fma_f32 v100, -v100, v103, v102
	v_div_fmas_f32 v100, v100, v101, v103
	v_div_fixup_f32 v99, v100, v99, 1.0
	v_div_scale_f32 v100, s[22:23], v98, v98, 1.0
	v_rcp_f32_e32 v101, v100
	s_nop 0
	v_fma_f32 v102, -v100, v101, 1.0
	v_fmac_f32_e32 v101, v102, v101
	v_div_scale_f32 v102, vcc, 1.0, v98, 1.0
	v_mul_f32_e32 v103, v102, v101
	v_fma_f32 v104, -v100, v103, v102
	v_fmac_f32_e32 v103, v104, v101
	v_fma_f32 v100, -v100, v103, v102
	v_div_fmas_f32 v100, v100, v101, v103
	v_div_fixup_f32 v98, v100, v98, 1.0
	v_pk_fma_f32 v[98:99], v[92:93], v[98:99], v[90:91]
	v_cvt_pk_bf16_f32 v90, v94, v95
	v_lshl_add_u64 v[94:95], s[28:29], 0, v[112:113]
	v_cvt_pk_bf16_f32 v91, v96, v97
	v_cvt_pk_bf16_f32 v92, v114, v115
	v_cvt_pk_bf16_f32 v93, v98, v99
	v_lshl_add_u64 v[98:99], v[94:95], 0, v[142:143]
	global_store_dwordx4 v[98:99], v[90:93], off
	s_nop 1
	v_lshl_add_u64 v[90:91], v[110:111], 0, v[144:145]
	s_waitcnt vmcnt(9)
; __device__ __forceinline__ unsigned pk2(float lo, float hi) { return pg8::cvt_pk_bf16(lo, hi); }
; __device__ __forceinline__ float sigmoidf_(float x) { return 1.f / (1.f + __expf(-x)); }
;     __device__ __forceinline__ void operator()(const f32x4 (&acc)[2][2][4][2], const pg8::Unit& u, int wr, int wc, int fr, int fq) const {
;     ...
;             for (int m = 0; m < 4; ++m) { const int row = row0 + ai * 128 + m * 16;
; #pragma unroll
;                 for (int bj = 0; bj < 2; ++bj) { const int col = col0 + bj * 128;
;                     const u32x4 gw = *(const u32x4*)(P + (size_t)row * NINP + GATEOFF + 2 * 2048 + col); float gt[8]; unpack8(gw, gt);
;                     const u32x4 w0 = *(const u32x4*)(br0 + (size_t)row * D + col); float b0[8]; unpack8(w0, b0);
;                     const u32x4 w1 = *(const u32x4*)(br1 + (size_t)row * D + col); float b1[8]; unpack8(w1, b1);
;                     const f32x4 v0 = acc[ai][bj][m][0], v1 = acc[ai][bj][m][1];
;                     float o[8];
; #pragma unroll
;                     for (int j = 0; j < 4; ++j) { o[j] = b0[j] + b1[j] + sigmoidf_(gt[j]) * v0[j]; o[4 + j] = b0[4 + j] + b1[4 + j] + sigmoidf_(gt[4 + j]) * v1[j]; }
;                     u32x4 w; w.x = pk2(o[0], o[1]); w.y = pk2(o[2], o[3]); w.z = pk2(o[4], o[5]); w.w = pk2(o[6], o[7]);
;                     *(u32x4*)(mrg + (size_t)row * D + col) = w; } }
	s_nop 1
	v_mov_b32_e32 v90, v234
	v_mov_b32_e32 v91, v235
	v_mov_b32_e32 v92, v236
	v_mov_b32_e32 v93, v237
	v_lshlrev_b32_e32 v110, 16, v90
	v_and_b32_e32 v105, 0xffff0000, v90
	v_lshlrev_b32_e32 v102, 16, v91
	v_and_b32_e32 v101, 0xffff0000, v91
	v_lshlrev_b32_e32 v111, 16, v92
	v_and_b32_e32 v104, 0xffff0000, v92
	v_lshlrev_b32_e32 v103, 16, v93
	v_and_b32_e32 v100, 0xffff0000, v93
	v_mul_f32_e32 v106, 0xbfb8aa3b, v110
	v_mul_f32_e32 v107, 0xbfb8aa3b, v111
	v_mul_f32_e32 v105, 0xbfb8aa3b, v105
	v_exp_f32_e32 v106, v106
	v_exp_f32_e32 v108, v107
	v_exp_f32_e32 v107, v105
	v_mov_b32_e32 v90, v238
	v_mov_b32_e32 v91, v239
	v_mov_b32_e32 v92, v240
	v_mov_b32_e32 v93, v241
	v_lshlrev_b32_e32 v110, 16, v90
	v_pk_add_f32 v[106:107], v[106:107], 1.0 op_sel_hi:[1,0]
	v_and_b32_e32 v111, 0xffff0000, v90
	v_div_scale_f32 v90, s[22:23], v107, v107, 1.0
	v_mov_b32_e32 v94, v242
	v_mov_b32_e32 v95, v243
	v_mov_b32_e32 v96, v244
	v_mov_b32_e32 v97, v245
	v_add_u32_e32 v213, 0x80, v146
	v_mad_i64_i32 v[246:247], s[22:23], v213, s79, v[152:153]
	v_lshl_add_u64 v[246:247], v[246:247], 0, s[30:31]
	v_lshl_add_u64 v[246:247], v[246:247], 0, v[142:143]
	global_load_dwordx4 v[234:237], v[246:247], off
	v_mov_b32_e32 v248, v213
	v_ashrrev_i32_e32 v249, 31, v213
	v_lshlrev_b64 v[248:249], 12, v[248:249]
	v_lshl_add_u64 v[250:251], s[26:27], 0, v[248:249]
	v_lshl_add_u64 v[250:251], v[250:251], 0, v[142:143]
	global_load_dwordx4 v[238:241], v[250:251], off
	v_lshl_add_u64 v[248:249], s[90:91], 0, v[248:249]
	v_lshl_add_u64 v[248:249], v[248:249], 0, v[142:143]
	global_load_dwordx4 v[242:245], v[248:249], off
	v_lshlrev_b32_e32 v112, 16, v94
	v_and_b32_e32 v113, 0xffff0000, v94
	v_rcp_f32_e32 v94, v90
	v_pk_add_f32 v[110:111], v[110:111], v[112:113]
	v_fma_f32 v105, -v90, v94, 1.0
	v_fmac_f32_e32 v94, v105, v94
	v_div_scale_f32 v105, vcc, 1.0, v107, 1.0
	v_mul_f32_e32 v109, v105, v94
	v_fma_f32 v112, -v90, v109, v105
	v_fmac_f32_e32 v109, v112, v94
	v_fma_f32 v90, -v90, v109, v105
	v_div_fmas_f32 v90, v90, v94, v109
	v_div_fixup_f32 v107, v90, v107, 1.0
	v_div_scale_f32 v90, s[22:23], v106, v106, 1.0
	v_rcp_f32_e32 v94, v90
	s_nop 0
	v_fma_f32 v105, -v90, v94, 1.0
	v_fmac_f32_e32 v94, v105, v94
	v_div_scale_f32 v105, vcc, 1.0, v106, 1.0
	v_mul_f32_e32 v109, v105, v94
	v_fma_f32 v112, -v90, v109, v105
	v_fmac_f32_e32 v109, v112, v94
	v_fma_f32 v90, -v90, v109, v105
	v_div_fmas_f32 v90, v90, v94, v109
	v_div_fixup_f32 v106, v90, v106, 1.0
	v_mul_f32_e32 v90, 0xbfb8aa3b, v104
	v_exp_f32_e32 v109, v90
	v_pk_fma_f32 v[86:87], v[86:87], v[106:107], v[110:111]
	v_lshlrev_b32_e32 v104, 16, v92
	v_and_b32_e32 v105, 0xffff0000, v92
	v_lshlrev_b32_e32 v106, 16, v96
	v_and_b32_e32 v107, 0xffff0000, v96
	v_pk_add_f32 v[104:105], v[104:105], v[106:107]
	v_pk_add_f32 v[106:107], v[108:109], 1.0 op_sel_hi:[1,0]
	s_nop 0
	v_div_scale_f32 v90, s[22:23], v107, v107, 1.0
	v_rcp_f32_e32 v92, v90
	s_nop 0
	v_fma_f32 v94, -v90, v92, 1.0
	v_fmac_f32_e32 v92, v94, v92
	v_div_scale_f32 v94, vcc, 1.0, v107, 1.0
	v_mul_f32_e32 v96, v94, v92
	v_fma_f32 v108, -v90, v96, v94
	v_fmac_f32_e32 v96, v108, v92
	v_fma_f32 v90, -v90, v96, v94
	v_div_fmas_f32 v90, v90, v92, v96
	v_div_fixup_f32 v107, v90, v107, 1.0
	v_div_scale_f32 v90, s[22:23], v106, v106, 1.0
	v_rcp_f32_e32 v92, v90
	s_nop 0
	v_fma_f32 v94, -v90, v92, 1.0
	v_fmac_f32_e32 v92, v94, v92
	v_div_scale_f32 v94, vcc, 1.0, v106, 1.0
	v_mul_f32_e32 v96, v94, v92
	v_fma_f32 v108, -v90, v96, v94
	v_fmac_f32_e32 v96, v108, v92
	v_fma_f32 v90, -v90, v96, v94
	v_div_fmas_f32 v90, v90, v92, v96
	v_div_fixup_f32 v106, v90, v106, 1.0
	v_pk_fma_f32 v[104:105], v[82:83], v[106:107], v[104:105]
	v_mul_f32_e32 v83, 0xbfb8aa3b, v103
	v_mul_f32_e32 v82, 0xbfb8aa3b, v102
	v_exp_f32_e32 v90, v83
	v_mul_f32_e32 v83, 0xbfb8aa3b, v101
	v_exp_f32_e32 v82, v82
	v_exp_f32_e32 v83, v83
	v_lshlrev_b32_e32 v102, 16, v91
	v_and_b32_e32 v103, 0xffff0000, v91
	v_lshlrev_b32_e32 v94, 16, v95
	v_pk_add_f32 v[82:83], v[82:83], 1.0 op_sel_hi:[1,0]
	v_and_b32_e32 v95, 0xffff0000, v95
	v_div_scale_f32 v91, s[22:23], v83, v83, 1.0
	v_rcp_f32_e32 v92, v91
	v_pk_add_f32 v[94:95], v[102:103], v[94:95]
	v_fma_f32 v96, -v91, v92, 1.0
	v_fmac_f32_e32 v92, v96, v92
	v_div_scale_f32 v96, vcc, 1.0, v83, 1.0
	v_mul_f32_e32 v101, v96, v92
	v_fma_f32 v102, -v91, v101, v96
	v_fmac_f32_e32 v101, v102, v92
	v_fma_f32 v91, -v91, v101, v96
	v_div_fmas_f32 v91, v91, v92, v101
	v_div_fixup_f32 v83, v91, v83, 1.0
	v_div_scale_f32 v91, s[22:23], v82, v82, 1.0
	v_rcp_f32_e32 v92, v91
	s_nop 0
	v_fma_f32 v96, -v91, v92, 1.0
	v_fmac_f32_e32 v92, v96, v92
	v_div_scale_f32 v96, vcc, 1.0, v82, 1.0
	v_mul_f32_e32 v101, v96, v92
	v_fma_f32 v102, -v91, v101, v96
	v_fmac_f32_e32 v101, v102, v92
	v_fma_f32 v91, -v91, v101, v96
	v_div_fmas_f32 v91, v91, v92, v101
	v_div_fixup_f32 v82, v91, v82, 1.0
	v_pk_fma_f32 v[88:89], v[88:89], v[82:83], v[94:95]
	v_mul_f32_e32 v82, 0xbfb8aa3b, v100
	v_exp_f32_e32 v91, v82
	v_lshlrev_b32_e32 v82, 16, v93
	v_and_b32_e32 v83, 0xffff0000, v93
	v_lshlrev_b32_e32 v92, 16, v97
	v_and_b32_e32 v93, 0xffff0000, v97
	v_pk_add_f32 v[90:91], v[90:91], 1.0 op_sel_hi:[1,0]
	v_pk_add_f32 v[82:83], v[82:83], v[92:93]
	v_div_scale_f32 v92, s[22:23], v91, v91, 1.0
	v_rcp_f32_e32 v93, v92
	s_nop 0
	v_fma_f32 v94, -v92, v93, 1.0
	v_fmac_f32_e32 v93, v94, v93
	v_div_scale_f32 v94, vcc, 1.0, v91, 1.0
	v_mul_f32_e32 v95, v94, v93
	v_fma_f32 v96, -v92, v95, v94
	v_fmac_f32_e32 v95, v96, v93
	v_fma_f32 v92, -v92, v95, v94
	v_div_fmas_f32 v92, v92, v93, v95
	v_div_fixup_f32 v91, v92, v91, 1.0
	v_div_scale_f32 v92, s[22:23], v90, v90, 1.0
	v_rcp_f32_e32 v93, v92
	s_nop 0
	v_fma_f32 v94, -v92, v93, 1.0
	v_fmac_f32_e32 v93, v94, v93
	v_div_scale_f32 v94, vcc, 1.0, v90, 1.0
	v_mul_f32_e32 v95, v94, v93
	v_fma_f32 v96, -v92, v95, v94
	v_fmac_f32_e32 v95, v96, v93
	v_fma_f32 v92, -v92, v95, v94
	v_div_fmas_f32 v92, v92, v93, v95
	v_div_fixup_f32 v90, v92, v90, 1.0
	v_pk_fma_f32 v[90:91], v[84:85], v[90:91], v[82:83]
	v_cvt_pk_bf16_f32 v82, v86, v87
	v_cvt_pk_bf16_f32 v83, v88, v89
	v_cvt_pk_bf16_f32 v84, v104, v105
	v_cvt_pk_bf16_f32 v85, v90, v91
	v_or_b32_e32 v86, 48, v146
	global_store_dwordx4 v[98:99], v[82:85], off offset:256
	v_ashrrev_i32_e32 v87, 31, v86
	v_lshlrev_b64 v[96:97], 12, v[86:87]
	v_mad_i64_i32 v[82:83], s[22:23], v86, s79, v[152:153]
	v_lshl_add_u64 v[94:95], v[82:83], 0, s[30:31]
	v_lshl_add_u64 v[82:83], v[94:95], 0, v[142:143]
	v_lshl_add_u64 v[86:87], s[90:91], 0, v[96:97]
	v_lshl_add_u64 v[90:91], v[86:87], 0, v[142:143]
	s_waitcnt vmcnt(9)
; __device__ __forceinline__ unsigned pk2(float lo, float hi) { return pg8::cvt_pk_bf16(lo, hi); }
; __device__ __forceinline__ float sigmoidf_(float x) { return 1.f / (1.f + __expf(-x)); }
;     __device__ __forceinline__ void operator()(const f32x4 (&acc)[2][2][4][2], const pg8::Unit& u, int wr, int wc, int fr, int fq) const {
;     ...
;             for (int m = 0; m < 4; ++m) { const int row = row0 + ai * 128 + m * 16;
; #pragma unroll
;                 for (int bj = 0; bj < 2; ++bj) { const int col = col0 + bj * 128;
;                     const u32x4 gw = *(const u32x4*)(P + (size_t)row * NINP + GATEOFF + 2 * 2048 + col); float gt[8]; unpack8(gw, gt);
;                     const u32x4 w0 = *(const u32x4*)(br0 + (size_t)row * D + col); float b0[8]; unpack8(w0, b0);
;                     const u32x4 w1 = *(const u32x4*)(br1 + (size_t)row * D + col); float b1[8]; unpack8(w1, b1);
;                     const f32x4 v0 = acc[ai][bj][m][0], v1 = acc[ai][bj][m][1];
;                     float o[8];
; #pragma unroll
;                     for (int j = 0; j < 4; ++j) { o[j] = b0[j] + b1[j] + sigmoidf_(gt[j]) * v0[j]; o[4 + j] = b0[4 + j] + b1[4 + j] + sigmoidf_(gt[4 + j]) * v1[j]; }
;                     u32x4 w; w.x = pk2(o[0], o[1]); w.y = pk2(o[2], o[3]); w.z = pk2(o[4], o[5]); w.w = pk2(o[6], o[7]);
;                     *(u32x4*)(mrg + (size_t)row * D + col) = w; } }
	s_nop 1
	v_mov_b32_e32 v82, v184
	v_mov_b32_e32 v83, v185
	v_mov_b32_e32 v84, v186
	v_mov_b32_e32 v85, v187
	v_lshlrev_b32_e32 v98, 16, v82
	v_and_b32_e32 v99, 0xffff0000, v82
	v_lshlrev_b32_e32 v106, 16, v83
	v_and_b32_e32 v107, 0xffff0000, v83
	v_lshl_add_u64 v[82:83], s[26:27], 0, v[96:97]
	v_lshl_add_u64 v[92:93], v[82:83], 0, v[142:143]
	v_lshlrev_b32_e32 v100, 16, v84
	v_and_b32_e32 v101, 0xffff0000, v84
	v_lshlrev_b32_e32 v108, 16, v85
	v_and_b32_e32 v109, 0xffff0000, v85
	v_mul_f32_e32 v98, 0xbfb8aa3b, v98
	v_mul_f32_e32 v99, 0xbfb8aa3b, v99
	v_exp_f32_e32 v98, v98
	v_exp_f32_e32 v99, v99
	v_mov_b32_e32 v86, v214
	v_mov_b32_e32 v87, v215
	v_mov_b32_e32 v88, v216
	v_mov_b32_e32 v89, v217
	v_lshlrev_b32_e32 v104, 16, v86
	v_and_b32_e32 v105, 0xffff0000, v86
	v_mul_f32_e32 v100, 0xbfb8aa3b, v100
	v_pk_add_f32 v[98:99], v[98:99], 1.0 op_sel_hi:[1,0]
	v_exp_f32_e32 v100, v100
	v_mov_b32_e32 v82, v218
	v_mov_b32_e32 v83, v219
	v_mov_b32_e32 v84, v220
	v_mov_b32_e32 v85, v221
	v_add_u32_e32 v213, 0x80, v146
	v_mad_i64_i32 v[246:247], s[22:23], v213, s79, v[152:153]
	v_lshl_add_u64 v[246:247], v[246:247], 0, s[30:31]
	v_lshl_add_u64 v[246:247], v[246:247], 0, v[142:143]
	global_load_dwordx4 v[184:187], v[246:247], off offset:256
	v_mov_b32_e32 v248, v213
	v_ashrrev_i32_e32 v249, 31, v213
	v_lshlrev_b64 v[248:249], 12, v[248:249]
	v_lshl_add_u64 v[250:251], s[26:27], 0, v[248:249]
	v_lshl_add_u64 v[250:251], v[250:251], 0, v[142:143]
	global_load_dwordx4 v[214:217], v[250:251], off offset:256
	v_lshl_add_u64 v[248:249], s[90:91], 0, v[248:249]
	v_lshl_add_u64 v[248:249], v[248:249], 0, v[142:143]
	global_load_dwordx4 v[218:221], v[248:249], off offset:256
	v_lshlrev_b32_e32 v102, 16, v82
	v_and_b32_e32 v103, 0xffff0000, v82
	v_div_scale_f32 v82, s[22:23], v99, v99, 1.0
	v_rcp_f32_e32 v86, v82
	v_pk_add_f32 v[102:103], v[102:103], v[104:105]
	v_fma_f32 v104, -v82, v86, 1.0
	v_fmac_f32_e32 v86, v104, v86
	v_div_scale_f32 v104, vcc, 1.0, v99, 1.0
	v_mul_f32_e32 v105, v104, v86
	v_fma_f32 v110, -v82, v105, v104
	v_fmac_f32_e32 v105, v110, v86
	v_fma_f32 v82, -v82, v105, v104
	v_div_fmas_f32 v82, v82, v86, v105
	v_div_fixup_f32 v99, v82, v99, 1.0
	v_div_scale_f32 v82, s[22:23], v98, v98, 1.0
	v_rcp_f32_e32 v86, v82
	s_nop 0
	v_fma_f32 v104, -v82, v86, 1.0
	v_fmac_f32_e32 v86, v104, v86
	v_div_scale_f32 v104, vcc, 1.0, v98, 1.0
	v_mul_f32_e32 v105, v104, v86
	v_fma_f32 v110, -v82, v105, v104
	v_fmac_f32_e32 v105, v110, v86
	v_fma_f32 v82, -v82, v105, v104
	v_div_fmas_f32 v82, v82, v86, v105
	v_div_fixup_f32 v98, v82, v98, 1.0
	v_mul_f32_e32 v82, 0xbfb8aa3b, v101
	v_exp_f32_e32 v101, v82
	v_pk_fma_f32 v[78:79], v[78:79], v[98:99], v[102:103]
	v_lshlrev_b32_e32 v98, 16, v84
	v_and_b32_e32 v99, 0xffff0000, v84
	v_pk_add_f32 v[100:101], v[100:101], 1.0 op_sel_hi:[1,0]
	v_lshlrev_b32_e32 v102, 16, v88
	v_div_scale_f32 v82, s[22:23], v101, v101, 1.0
	v_rcp_f32_e32 v84, v82
	v_and_b32_e32 v103, 0xffff0000, v88
	v_pk_add_f32 v[98:99], v[98:99], v[102:103]
	v_fma_f32 v86, -v82, v84, 1.0
	v_fmac_f32_e32 v84, v86, v84
	v_div_scale_f32 v86, vcc, 1.0, v101, 1.0
	v_mul_f32_e32 v88, v86, v84
	v_fma_f32 v102, -v82, v88, v86
	v_fmac_f32_e32 v88, v102, v84
	v_fma_f32 v82, -v82, v88, v86
	v_div_fmas_f32 v82, v82, v84, v88
	v_div_fixup_f32 v101, v82, v101, 1.0
	v_div_scale_f32 v82, s[22:23], v100, v100, 1.0
	v_rcp_f32_e32 v84, v82
	s_nop 0
	v_fma_f32 v86, -v82, v84, 1.0
	v_fmac_f32_e32 v84, v86, v84
	v_div_scale_f32 v86, vcc, 1.0, v100, 1.0
	v_mul_f32_e32 v88, v86, v84
	v_fma_f32 v102, -v82, v88, v86
	v_fmac_f32_e32 v88, v102, v84
	v_fma_f32 v82, -v82, v88, v86
	v_div_fmas_f32 v82, v82, v84, v88
	v_div_fixup_f32 v100, v82, v100, 1.0
	v_pk_fma_f32 v[98:99], v[74:75], v[100:101], v[98:99]
	v_mul_f32_e32 v75, 0xbfb8aa3b, v108
	v_mul_f32_e32 v74, 0xbfb8aa3b, v106
	v_exp_f32_e32 v82, v75
	v_mul_f32_e32 v75, 0xbfb8aa3b, v107
	v_exp_f32_e32 v74, v74
	v_exp_f32_e32 v75, v75
	v_lshlrev_b32_e32 v100, 16, v83
	v_and_b32_e32 v101, 0xffff0000, v83
	v_lshlrev_b32_e32 v86, 16, v87
	v_pk_add_f32 v[74:75], v[74:75], 1.0 op_sel_hi:[1,0]
	v_and_b32_e32 v87, 0xffff0000, v87
	v_div_scale_f32 v83, s[22:23], v75, v75, 1.0
	v_rcp_f32_e32 v84, v83
	v_pk_add_f32 v[86:87], v[100:101], v[86:87]
	v_fma_f32 v88, -v83, v84, 1.0
	v_fmac_f32_e32 v84, v88, v84
	v_div_scale_f32 v88, vcc, 1.0, v75, 1.0
	v_mul_f32_e32 v100, v88, v84
	v_fma_f32 v101, -v83, v100, v88
	v_fmac_f32_e32 v100, v101, v84
	v_fma_f32 v83, -v83, v100, v88
	v_div_fmas_f32 v83, v83, v84, v100
	v_div_fixup_f32 v75, v83, v75, 1.0
	v_div_scale_f32 v83, s[22:23], v74, v74, 1.0
	v_rcp_f32_e32 v84, v83
	s_nop 0
	v_fma_f32 v88, -v83, v84, 1.0
	v_fmac_f32_e32 v84, v88, v84
	v_div_scale_f32 v88, vcc, 1.0, v74, 1.0
	v_mul_f32_e32 v100, v88, v84
	v_fma_f32 v101, -v83, v100, v88
	v_fmac_f32_e32 v100, v101, v84
	v_fma_f32 v83, -v83, v100, v88
	v_div_fmas_f32 v83, v83, v84, v100
	v_div_fixup_f32 v74, v83, v74, 1.0
	v_pk_fma_f32 v[80:81], v[80:81], v[74:75], v[86:87]
	v_mul_f32_e32 v74, 0xbfb8aa3b, v109
	v_exp_f32_e32 v83, v74
	v_lshlrev_b32_e32 v74, 16, v85
	v_and_b32_e32 v75, 0xffff0000, v85
	v_lshlrev_b32_e32 v84, 16, v89
	v_and_b32_e32 v85, 0xffff0000, v89
	v_pk_add_f32 v[82:83], v[82:83], 1.0 op_sel_hi:[1,0]
	v_pk_add_f32 v[74:75], v[74:75], v[84:85]
	v_div_scale_f32 v84, s[22:23], v83, v83, 1.0
	v_rcp_f32_e32 v85, v84
	s_nop 0
	v_fma_f32 v86, -v84, v85, 1.0
	v_fmac_f32_e32 v85, v86, v85
	v_div_scale_f32 v86, vcc, 1.0, v83, 1.0
	v_mul_f32_e32 v87, v86, v85
	v_fma_f32 v88, -v84, v87, v86
	v_fmac_f32_e32 v87, v88, v85
	v_fma_f32 v84, -v84, v87, v86
	v_div_fmas_f32 v84, v84, v85, v87
	v_div_fixup_f32 v83, v84, v83, 1.0
	v_div_scale_f32 v84, s[22:23], v82, v82, 1.0
	v_rcp_f32_e32 v85, v84
	s_nop 0
	v_fma_f32 v86, -v84, v85, 1.0
	v_fmac_f32_e32 v85, v86, v85
	v_div_scale_f32 v86, vcc, 1.0, v82, 1.0
	v_mul_f32_e32 v87, v86, v85
	v_fma_f32 v88, -v84, v87, v86
	v_fmac_f32_e32 v87, v88, v85
	v_fma_f32 v84, -v84, v87, v86
	v_div_fmas_f32 v84, v84, v85, v87
	v_div_fixup_f32 v82, v84, v82, 1.0
	v_pk_fma_f32 v[82:83], v[76:77], v[82:83], v[74:75]
	v_cvt_pk_bf16_f32 v74, v78, v79
	v_lshl_add_u64 v[78:79], s[28:29], 0, v[96:97]
	v_cvt_pk_bf16_f32 v75, v80, v81
	v_cvt_pk_bf16_f32 v76, v98, v99
	v_cvt_pk_bf16_f32 v77, v82, v83
	v_lshl_add_u64 v[82:83], v[78:79], 0, v[142:143]
	global_store_dwordx4 v[82:83], v[74:77], off
	s_nop 1
	v_lshl_add_u64 v[74:75], v[94:95], 0, v[144:145]
	s_waitcnt vmcnt(9)
; __device__ __forceinline__ unsigned pk2(float lo, float hi) { return pg8::cvt_pk_bf16(lo, hi); }
; __device__ __forceinline__ float sigmoidf_(float x) { return 1.f / (1.f + __expf(-x)); }
;     __device__ __forceinline__ void operator()(const f32x4 (&acc)[2][2][4][2], const pg8::Unit& u, int wr, int wc, int fr, int fq) const {
;     ...
;             for (int m = 0; m < 4; ++m) { const int row = row0 + ai * 128 + m * 16;
; #pragma unroll
;                 for (int bj = 0; bj < 2; ++bj) { const int col = col0 + bj * 128;
;                     const u32x4 gw = *(const u32x4*)(P + (size_t)row * NINP + GATEOFF + 2 * 2048 + col); float gt[8]; unpack8(gw, gt);
;                     const u32x4 w0 = *(const u32x4*)(br0 + (size_t)row * D + col); float b0[8]; unpack8(w0, b0);
;                     const u32x4 w1 = *(const u32x4*)(br1 + (size_t)row * D + col); float b1[8]; unpack8(w1, b1);
;                     const f32x4 v0 = acc[ai][bj][m][0], v1 = acc[ai][bj][m][1];
;                     float o[8];
; #pragma unroll
;                     for (int j = 0; j < 4; ++j) { o[j] = b0[j] + b1[j] + sigmoidf_(gt[j]) * v0[j]; o[4 + j] = b0[4 + j] + b1[4 + j] + sigmoidf_(gt[4 + j]) * v1[j]; }
;                     u32x4 w; w.x = pk2(o[0], o[1]); w.y = pk2(o[2], o[3]); w.z = pk2(o[4], o[5]); w.w = pk2(o[6], o[7]);
;                     *(u32x4*)(mrg + (size_t)row * D + col) = w; } }
	s_nop 1
	v_mov_b32_e32 v74, v222
	v_mov_b32_e32 v75, v223
	v_mov_b32_e32 v76, v224
	v_mov_b32_e32 v77, v225
	v_lshlrev_b32_e32 v94, 16, v74
	v_and_b32_e32 v89, 0xffff0000, v74
	v_lshlrev_b32_e32 v86, 16, v75
	v_and_b32_e32 v85, 0xffff0000, v75
	v_lshlrev_b32_e32 v95, 16, v76
	v_and_b32_e32 v88, 0xffff0000, v76
	v_lshlrev_b32_e32 v87, 16, v77
	v_and_b32_e32 v84, 0xffff0000, v77
	v_mul_f32_e32 v90, 0xbfb8aa3b, v94
	v_mul_f32_e32 v91, 0xbfb8aa3b, v95
	v_mul_f32_e32 v89, 0xbfb8aa3b, v89
	v_exp_f32_e32 v90, v90
	v_exp_f32_e32 v92, v91
	v_exp_f32_e32 v91, v89
	v_mov_b32_e32 v74, v226
	v_mov_b32_e32 v75, v227
	v_mov_b32_e32 v76, v228
	v_mov_b32_e32 v77, v229
	v_lshlrev_b32_e32 v94, 16, v74
	v_pk_add_f32 v[90:91], v[90:91], 1.0 op_sel_hi:[1,0]
	v_and_b32_e32 v95, 0xffff0000, v74
	v_div_scale_f32 v74, s[22:23], v91, v91, 1.0
	v_mov_b32_e32 v78, v230
	v_mov_b32_e32 v79, v231
	v_mov_b32_e32 v80, v232
	v_mov_b32_e32 v81, v233
	v_add_u32_e32 v213, 0x90, v146
	v_mad_i64_i32 v[246:247], s[22:23], v213, s79, v[152:153]
	v_lshl_add_u64 v[246:247], v[246:247], 0, s[30:31]
	v_lshl_add_u64 v[246:247], v[246:247], 0, v[142:143]
	global_load_dwordx4 v[222:225], v[246:247], off
	v_mov_b32_e32 v248, v213
	v_ashrrev_i32_e32 v249, 31, v213
	v_lshlrev_b64 v[248:249], 12, v[248:249]
	v_lshl_add_u64 v[250:251], s[26:27], 0, v[248:249]
	v_lshl_add_u64 v[250:251], v[250:251], 0, v[142:143]
	global_load_dwordx4 v[226:229], v[250:251], off
	v_lshl_add_u64 v[248:249], s[90:91], 0, v[248:249]
	v_lshl_add_u64 v[248:249], v[248:249], 0, v[142:143]
	global_load_dwordx4 v[230:233], v[248:249], off
	v_lshlrev_b32_e32 v96, 16, v78
	v_and_b32_e32 v97, 0xffff0000, v78
	v_rcp_f32_e32 v78, v74
	v_pk_add_f32 v[94:95], v[94:95], v[96:97]
	v_fma_f32 v89, -v74, v78, 1.0
	v_fmac_f32_e32 v78, v89, v78
	v_div_scale_f32 v89, vcc, 1.0, v91, 1.0
	v_mul_f32_e32 v93, v89, v78
	v_fma_f32 v96, -v74, v93, v89
	v_fmac_f32_e32 v93, v96, v78
	v_fma_f32 v74, -v74, v93, v89
	v_div_fmas_f32 v74, v74, v78, v93
	v_div_fixup_f32 v91, v74, v91, 1.0
	v_div_scale_f32 v74, s[22:23], v90, v90, 1.0
	v_rcp_f32_e32 v78, v74
	s_nop 0
	v_fma_f32 v89, -v74, v78, 1.0
	v_fmac_f32_e32 v78, v89, v78
	v_div_scale_f32 v89, vcc, 1.0, v90, 1.0
	v_mul_f32_e32 v93, v89, v78
	v_fma_f32 v96, -v74, v93, v89
	v_fmac_f32_e32 v93, v96, v78
	v_fma_f32 v74, -v74, v93, v89
	v_div_fmas_f32 v74, v74, v78, v93
	v_div_fixup_f32 v90, v74, v90, 1.0
	v_mul_f32_e32 v74, 0xbfb8aa3b, v88
	v_exp_f32_e32 v93, v74
	v_pk_fma_f32 v[70:71], v[70:71], v[90:91], v[94:95]
	v_lshlrev_b32_e32 v88, 16, v76
	v_and_b32_e32 v89, 0xffff0000, v76
	v_lshlrev_b32_e32 v90, 16, v80
	v_and_b32_e32 v91, 0xffff0000, v80
	v_pk_add_f32 v[88:89], v[88:89], v[90:91]
	v_pk_add_f32 v[90:91], v[92:93], 1.0 op_sel_hi:[1,0]
	s_nop 0
	v_div_scale_f32 v74, s[22:23], v91, v91, 1.0
	v_rcp_f32_e32 v76, v74
	s_nop 0
	v_fma_f32 v78, -v74, v76, 1.0
	v_fmac_f32_e32 v76, v78, v76
	v_div_scale_f32 v78, vcc, 1.0, v91, 1.0
	v_mul_f32_e32 v80, v78, v76
	v_fma_f32 v92, -v74, v80, v78
	v_fmac_f32_e32 v80, v92, v76
	v_fma_f32 v74, -v74, v80, v78
	v_div_fmas_f32 v74, v74, v76, v80
	v_div_fixup_f32 v91, v74, v91, 1.0
	v_div_scale_f32 v74, s[22:23], v90, v90, 1.0
	v_rcp_f32_e32 v76, v74
	s_nop 0
	v_fma_f32 v78, -v74, v76, 1.0
	v_fmac_f32_e32 v76, v78, v76
	v_div_scale_f32 v78, vcc, 1.0, v90, 1.0
	v_mul_f32_e32 v80, v78, v76
	v_fma_f32 v92, -v74, v80, v78
	v_fmac_f32_e32 v80, v92, v76
	v_fma_f32 v74, -v74, v80, v78
	v_div_fmas_f32 v74, v74, v76, v80
	v_div_fixup_f32 v90, v74, v90, 1.0
	v_pk_fma_f32 v[88:89], v[66:67], v[90:91], v[88:89]
	v_mul_f32_e32 v67, 0xbfb8aa3b, v87
	v_mul_f32_e32 v66, 0xbfb8aa3b, v86
	v_exp_f32_e32 v74, v67
	v_mul_f32_e32 v67, 0xbfb8aa3b, v85
	v_exp_f32_e32 v66, v66
	v_exp_f32_e32 v67, v67
	v_lshlrev_b32_e32 v86, 16, v75
	v_and_b32_e32 v87, 0xffff0000, v75
	v_lshlrev_b32_e32 v78, 16, v79
	v_pk_add_f32 v[66:67], v[66:67], 1.0 op_sel_hi:[1,0]
	v_and_b32_e32 v79, 0xffff0000, v79
	v_div_scale_f32 v75, s[22:23], v67, v67, 1.0
	v_rcp_f32_e32 v76, v75
	v_pk_add_f32 v[78:79], v[86:87], v[78:79]
	v_fma_f32 v80, -v75, v76, 1.0
	v_fmac_f32_e32 v76, v80, v76
	v_div_scale_f32 v80, vcc, 1.0, v67, 1.0
	v_mul_f32_e32 v85, v80, v76
	v_fma_f32 v86, -v75, v85, v80
	v_fmac_f32_e32 v85, v86, v76
	v_fma_f32 v75, -v75, v85, v80
	v_div_fmas_f32 v75, v75, v76, v85
	v_div_fixup_f32 v67, v75, v67, 1.0
	v_div_scale_f32 v75, s[22:23], v66, v66, 1.0
	v_rcp_f32_e32 v76, v75
	s_nop 0
	v_fma_f32 v80, -v75, v76, 1.0
	v_fmac_f32_e32 v76, v80, v76
	v_div_scale_f32 v80, vcc, 1.0, v66, 1.0
	v_mul_f32_e32 v85, v80, v76
	v_fma_f32 v86, -v75, v85, v80
	v_fmac_f32_e32 v85, v86, v76
	v_fma_f32 v75, -v75, v85, v80
	v_div_fmas_f32 v75, v75, v76, v85
	v_div_fixup_f32 v66, v75, v66, 1.0
	v_pk_fma_f32 v[72:73], v[72:73], v[66:67], v[78:79]
	v_mul_f32_e32 v66, 0xbfb8aa3b, v84
	v_exp_f32_e32 v75, v66
	v_lshlrev_b32_e32 v66, 16, v77
	v_and_b32_e32 v67, 0xffff0000, v77
	v_lshlrev_b32_e32 v76, 16, v81
	v_and_b32_e32 v77, 0xffff0000, v81
	v_pk_add_f32 v[74:75], v[74:75], 1.0 op_sel_hi:[1,0]
	v_pk_add_f32 v[66:67], v[66:67], v[76:77]
	v_div_scale_f32 v76, s[22:23], v75, v75, 1.0
	v_rcp_f32_e32 v77, v76
	s_nop 0
	v_fma_f32 v78, -v76, v77, 1.0
	v_fmac_f32_e32 v77, v78, v77
	v_div_scale_f32 v78, vcc, 1.0, v75, 1.0
	v_mul_f32_e32 v79, v78, v77
	v_fma_f32 v80, -v76, v79, v78
	v_fmac_f32_e32 v79, v80, v77
	v_fma_f32 v76, -v76, v79, v78
	v_div_fmas_f32 v76, v76, v77, v79
	v_div_fixup_f32 v75, v76, v75, 1.0
	v_div_scale_f32 v76, s[22:23], v74, v74, 1.0
	v_rcp_f32_e32 v77, v76
	s_nop 0
	v_fma_f32 v78, -v76, v77, 1.0
	v_fmac_f32_e32 v77, v78, v77
	v_div_scale_f32 v78, vcc, 1.0, v74, 1.0
	v_mul_f32_e32 v79, v78, v77
	v_fma_f32 v80, -v76, v79, v78
	v_fmac_f32_e32 v79, v80, v77
	v_fma_f32 v76, -v76, v79, v78
	v_div_fmas_f32 v76, v76, v77, v79
	v_div_fixup_f32 v74, v76, v74, 1.0
	v_pk_fma_f32 v[74:75], v[68:69], v[74:75], v[66:67]
	v_cvt_pk_bf16_f32 v66, v70, v71
	v_cvt_pk_bf16_f32 v67, v72, v73
	v_cvt_pk_bf16_f32 v68, v88, v89
	v_cvt_pk_bf16_f32 v69, v74, v75
	v_add_u32_e32 v70, 0x80, v146
	global_store_dwordx4 v[82:83], v[66:69], off offset:256
	v_ashrrev_i32_e32 v71, 31, v70
	v_lshlrev_b64 v[80:81], 12, v[70:71]
	v_mad_i64_i32 v[66:67], s[22:23], v70, s79, v[152:153]
	v_lshl_add_u64 v[78:79], v[66:67], 0, s[30:31]
	v_lshl_add_u64 v[66:67], v[78:79], 0, v[142:143]
	v_lshl_add_u64 v[70:71], s[90:91], 0, v[80:81]
	v_lshl_add_u64 v[74:75], v[70:71], 0, v[142:143]
	s_waitcnt vmcnt(9)
; __device__ __forceinline__ unsigned pk2(float lo, float hi) { return pg8::cvt_pk_bf16(lo, hi); }
; __device__ __forceinline__ float sigmoidf_(float x) { return 1.f / (1.f + __expf(-x)); }
;     __device__ __forceinline__ void operator()(const f32x4 (&acc)[2][2][4][2], const pg8::Unit& u, int wr, int wc, int fr, int fq) const {
;     ...
;             for (int m = 0; m < 4; ++m) { const int row = row0 + ai * 128 + m * 16;
; #pragma unroll
;                 for (int bj = 0; bj < 2; ++bj) { const int col = col0 + bj * 128;
;                     const u32x4 gw = *(const u32x4*)(P + (size_t)row * NINP + GATEOFF + 2 * 2048 + col); float gt[8]; unpack8(gw, gt);
;                     const u32x4 w0 = *(const u32x4*)(br0 + (size_t)row * D + col); float b0[8]; unpack8(w0, b0);
;                     const u32x4 w1 = *(const u32x4*)(br1 + (size_t)row * D + col); float b1[8]; unpack8(w1, b1);
;                     const f32x4 v0 = acc[ai][bj][m][0], v1 = acc[ai][bj][m][1];
;                     float o[8];
; #pragma unroll
;                     for (int j = 0; j < 4; ++j) { o[j] = b0[j] + b1[j] + sigmoidf_(gt[j]) * v0[j]; o[4 + j] = b0[4 + j] + b1[4 + j] + sigmoidf_(gt[4 + j]) * v1[j]; }
;                     u32x4 w; w.x = pk2(o[0], o[1]); w.y = pk2(o[2], o[3]); w.z = pk2(o[4], o[5]); w.w = pk2(o[6], o[7]);
;                     *(u32x4*)(mrg + (size_t)row * D + col) = w; } }
	s_nop 1
	v_mov_b32_e32 v66, v234
	v_mov_b32_e32 v67, v235
	v_mov_b32_e32 v68, v236
	v_mov_b32_e32 v69, v237
	v_lshlrev_b32_e32 v82, 16, v66
	v_and_b32_e32 v83, 0xffff0000, v66
	v_lshlrev_b32_e32 v90, 16, v67
	v_and_b32_e32 v91, 0xffff0000, v67
	v_lshl_add_u64 v[66:67], s[26:27], 0, v[80:81]
	v_lshl_add_u64 v[76:77], v[66:67], 0, v[142:143]
	v_lshlrev_b32_e32 v84, 16, v68
	v_and_b32_e32 v85, 0xffff0000, v68
	v_lshlrev_b32_e32 v92, 16, v69
	v_and_b32_e32 v93, 0xffff0000, v69
	v_mul_f32_e32 v82, 0xbfb8aa3b, v82
	v_mul_f32_e32 v83, 0xbfb8aa3b, v83
	v_exp_f32_e32 v82, v82
	v_exp_f32_e32 v83, v83
	v_mov_b32_e32 v70, v238
	v_mov_b32_e32 v71, v239
	v_mov_b32_e32 v72, v240
	v_mov_b32_e32 v73, v241
	v_lshlrev_b32_e32 v88, 16, v70
	v_and_b32_e32 v89, 0xffff0000, v70
	v_mul_f32_e32 v84, 0xbfb8aa3b, v84
	v_pk_add_f32 v[82:83], v[82:83], 1.0 op_sel_hi:[1,0]
	v_exp_f32_e32 v84, v84
	v_mov_b32_e32 v66, v242
	v_mov_b32_e32 v67, v243
	v_mov_b32_e32 v68, v244
	v_mov_b32_e32 v69, v245
	v_add_u32_e32 v213, 0x90, v146
	v_mad_i64_i32 v[246:247], s[22:23], v213, s79, v[152:153]
	v_lshl_add_u64 v[246:247], v[246:247], 0, s[30:31]
	v_lshl_add_u64 v[246:247], v[246:247], 0, v[142:143]
	global_load_dwordx4 v[234:237], v[246:247], off offset:256
	v_mov_b32_e32 v248, v213
	v_ashrrev_i32_e32 v249, 31, v213
	v_lshlrev_b64 v[248:249], 12, v[248:249]
	v_lshl_add_u64 v[250:251], s[26:27], 0, v[248:249]
	v_lshl_add_u64 v[250:251], v[250:251], 0, v[142:143]
	global_load_dwordx4 v[238:241], v[250:251], off offset:256
	v_lshl_add_u64 v[248:249], s[90:91], 0, v[248:249]
	v_lshl_add_u64 v[248:249], v[248:249], 0, v[142:143]
	global_load_dwordx4 v[242:245], v[248:249], off offset:256
	v_lshlrev_b32_e32 v86, 16, v66
	v_and_b32_e32 v87, 0xffff0000, v66
	v_div_scale_f32 v66, s[22:23], v83, v83, 1.0
	v_rcp_f32_e32 v70, v66
	v_pk_add_f32 v[86:87], v[86:87], v[88:89]
	v_fma_f32 v88, -v66, v70, 1.0
	v_fmac_f32_e32 v70, v88, v70
	v_div_scale_f32 v88, vcc, 1.0, v83, 1.0
	v_mul_f32_e32 v89, v88, v70
	v_fma_f32 v94, -v66, v89, v88
	v_fmac_f32_e32 v89, v94, v70
	v_fma_f32 v66, -v66, v89, v88
	v_div_fmas_f32 v66, v66, v70, v89
	v_div_fixup_f32 v83, v66, v83, 1.0
	v_div_scale_f32 v66, s[22:23], v82, v82, 1.0
	v_rcp_f32_e32 v70, v66
	s_nop 0
	v_fma_f32 v88, -v66, v70, 1.0
	v_fmac_f32_e32 v70, v88, v70
	v_div_scale_f32 v88, vcc, 1.0, v82, 1.0
	v_mul_f32_e32 v89, v88, v70
	v_fma_f32 v94, -v66, v89, v88
	v_fmac_f32_e32 v89, v94, v70
	v_fma_f32 v66, -v66, v89, v88
	v_div_fmas_f32 v66, v66, v70, v89
	v_div_fixup_f32 v82, v66, v82, 1.0
	v_mul_f32_e32 v66, 0xbfb8aa3b, v85
	v_exp_f32_e32 v85, v66
	v_pk_fma_f32 v[62:63], v[62:63], v[82:83], v[86:87]
	v_lshlrev_b32_e32 v82, 16, v68
	v_and_b32_e32 v83, 0xffff0000, v68
	v_pk_add_f32 v[84:85], v[84:85], 1.0 op_sel_hi:[1,0]
	v_lshlrev_b32_e32 v86, 16, v72
	v_div_scale_f32 v66, s[22:23], v85, v85, 1.0
	v_rcp_f32_e32 v68, v66
	v_and_b32_e32 v87, 0xffff0000, v72
	v_pk_add_f32 v[82:83], v[82:83], v[86:87]
	v_fma_f32 v70, -v66, v68, 1.0
	v_fmac_f32_e32 v68, v70, v68
	v_div_scale_f32 v70, vcc, 1.0, v85, 1.0
	v_mul_f32_e32 v72, v70, v68
	v_fma_f32 v86, -v66, v72, v70
	v_fmac_f32_e32 v72, v86, v68
	v_fma_f32 v66, -v66, v72, v70
	v_div_fmas_f32 v66, v66, v68, v72
	v_div_fixup_f32 v85, v66, v85, 1.0
	v_div_scale_f32 v66, s[22:23], v84, v84, 1.0
	v_rcp_f32_e32 v68, v66
	s_nop 0
	v_fma_f32 v70, -v66, v68, 1.0
	v_fmac_f32_e32 v68, v70, v68
	v_div_scale_f32 v70, vcc, 1.0, v84, 1.0
	v_mul_f32_e32 v72, v70, v68
	v_fma_f32 v86, -v66, v72, v70
	v_fmac_f32_e32 v72, v86, v68
	v_fma_f32 v66, -v66, v72, v70
	v_div_fmas_f32 v66, v66, v68, v72
	v_div_fixup_f32 v84, v66, v84, 1.0
	v_pk_fma_f32 v[82:83], v[58:59], v[84:85], v[82:83]
	v_mul_f32_e32 v59, 0xbfb8aa3b, v92
	v_mul_f32_e32 v58, 0xbfb8aa3b, v90
	v_exp_f32_e32 v66, v59
	v_mul_f32_e32 v59, 0xbfb8aa3b, v91
	v_exp_f32_e32 v58, v58
	v_exp_f32_e32 v59, v59
	v_lshlrev_b32_e32 v84, 16, v67
	v_and_b32_e32 v85, 0xffff0000, v67
	v_lshlrev_b32_e32 v70, 16, v71
	v_pk_add_f32 v[58:59], v[58:59], 1.0 op_sel_hi:[1,0]
	v_and_b32_e32 v71, 0xffff0000, v71
	v_div_scale_f32 v67, s[22:23], v59, v59, 1.0
	v_rcp_f32_e32 v68, v67
	v_pk_add_f32 v[70:71], v[84:85], v[70:71]
	v_fma_f32 v72, -v67, v68, 1.0
	v_fmac_f32_e32 v68, v72, v68
	v_div_scale_f32 v72, vcc, 1.0, v59, 1.0
	v_mul_f32_e32 v84, v72, v68
	v_fma_f32 v85, -v67, v84, v72
	v_fmac_f32_e32 v84, v85, v68
	v_fma_f32 v67, -v67, v84, v72
	v_div_fmas_f32 v67, v67, v68, v84
	v_div_fixup_f32 v59, v67, v59, 1.0
	v_div_scale_f32 v67, s[22:23], v58, v58, 1.0
	v_rcp_f32_e32 v68, v67
	s_nop 0
	v_fma_f32 v72, -v67, v68, 1.0
	v_fmac_f32_e32 v68, v72, v68
	v_div_scale_f32 v72, vcc, 1.0, v58, 1.0
	v_mul_f32_e32 v84, v72, v68
	v_fma_f32 v85, -v67, v84, v72
	v_fmac_f32_e32 v84, v85, v68
	v_fma_f32 v67, -v67, v84, v72
	v_div_fmas_f32 v67, v67, v68, v84
	v_div_fixup_f32 v58, v67, v58, 1.0
	v_pk_fma_f32 v[64:65], v[64:65], v[58:59], v[70:71]
	v_mul_f32_e32 v58, 0xbfb8aa3b, v93
	v_exp_f32_e32 v67, v58
	v_lshlrev_b32_e32 v58, 16, v69
	v_and_b32_e32 v59, 0xffff0000, v69
	v_lshlrev_b32_e32 v68, 16, v73
	v_and_b32_e32 v69, 0xffff0000, v73
	v_pk_add_f32 v[66:67], v[66:67], 1.0 op_sel_hi:[1,0]
	v_pk_add_f32 v[58:59], v[58:59], v[68:69]
	v_div_scale_f32 v68, s[22:23], v67, v67, 1.0
	v_rcp_f32_e32 v69, v68
	s_nop 0
	v_fma_f32 v70, -v68, v69, 1.0
	v_fmac_f32_e32 v69, v70, v69
	v_div_scale_f32 v70, vcc, 1.0, v67, 1.0
	v_mul_f32_e32 v71, v70, v69
	v_fma_f32 v72, -v68, v71, v70
	v_fmac_f32_e32 v71, v72, v69
	v_fma_f32 v68, -v68, v71, v70
	v_div_fmas_f32 v68, v68, v69, v71
	v_div_fixup_f32 v67, v68, v67, 1.0
	v_div_scale_f32 v68, s[22:23], v66, v66, 1.0
	v_rcp_f32_e32 v69, v68
	s_nop 0
	v_fma_f32 v70, -v68, v69, 1.0
	v_fmac_f32_e32 v69, v70, v69
	v_div_scale_f32 v70, vcc, 1.0, v66, 1.0
	v_mul_f32_e32 v71, v70, v69
	v_fma_f32 v72, -v68, v71, v70
	v_fmac_f32_e32 v71, v72, v69
	v_fma_f32 v68, -v68, v71, v70
	v_div_fmas_f32 v68, v68, v69, v71
	v_div_fixup_f32 v66, v68, v66, 1.0
	v_pk_fma_f32 v[66:67], v[60:61], v[66:67], v[58:59]
	v_cvt_pk_bf16_f32 v58, v62, v63
	v_lshl_add_u64 v[62:63], s[28:29], 0, v[80:81]
	v_cvt_pk_bf16_f32 v59, v64, v65
	v_cvt_pk_bf16_f32 v60, v82, v83
	v_cvt_pk_bf16_f32 v61, v66, v67
	v_lshl_add_u64 v[66:67], v[62:63], 0, v[142:143]
	global_store_dwordx4 v[66:67], v[58:61], off
	s_nop 1
	v_lshl_add_u64 v[58:59], v[78:79], 0, v[144:145]
	s_waitcnt vmcnt(9)
; __device__ __forceinline__ unsigned pk2(float lo, float hi) { return pg8::cvt_pk_bf16(lo, hi); }
; __device__ __forceinline__ float sigmoidf_(float x) { return 1.f / (1.f + __expf(-x)); }
;     __device__ __forceinline__ void operator()(const f32x4 (&acc)[2][2][4][2], const pg8::Unit& u, int wr, int wc, int fr, int fq) const {
;     ...
;             for (int m = 0; m < 4; ++m) { const int row = row0 + ai * 128 + m * 16;
; #pragma unroll
;                 for (int bj = 0; bj < 2; ++bj) { const int col = col0 + bj * 128;
;                     const u32x4 gw = *(const u32x4*)(P + (size_t)row * NINP + GATEOFF + 2 * 2048 + col); float gt[8]; unpack8(gw, gt);
;                     const u32x4 w0 = *(const u32x4*)(br0 + (size_t)row * D + col); float b0[8]; unpack8(w0, b0);
;                     const u32x4 w1 = *(const u32x4*)(br1 + (size_t)row * D + col); float b1[8]; unpack8(w1, b1);
;                     const f32x4 v0 = acc[ai][bj][m][0], v1 = acc[ai][bj][m][1];
;                     float o[8];
; #pragma unroll
;                     for (int j = 0; j < 4; ++j) { o[j] = b0[j] + b1[j] + sigmoidf_(gt[j]) * v0[j]; o[4 + j] = b0[4 + j] + b1[4 + j] + sigmoidf_(gt[4 + j]) * v1[j]; }
;                     u32x4 w; w.x = pk2(o[0], o[1]); w.y = pk2(o[2], o[3]); w.z = pk2(o[4], o[5]); w.w = pk2(o[6], o[7]);
;                     *(u32x4*)(mrg + (size_t)row * D + col) = w; } }
	s_nop 1
	v_mov_b32_e32 v58, v184
	v_mov_b32_e32 v59, v185
	v_mov_b32_e32 v60, v186
	v_mov_b32_e32 v61, v187
	v_lshlrev_b32_e32 v78, 16, v58
	v_and_b32_e32 v73, 0xffff0000, v58
	v_lshlrev_b32_e32 v70, 16, v59
	v_and_b32_e32 v69, 0xffff0000, v59
	v_lshlrev_b32_e32 v79, 16, v60
	v_and_b32_e32 v72, 0xffff0000, v60
	v_lshlrev_b32_e32 v71, 16, v61
	v_and_b32_e32 v68, 0xffff0000, v61
	v_mul_f32_e32 v74, 0xbfb8aa3b, v78
	v_mul_f32_e32 v75, 0xbfb8aa3b, v79
	v_mul_f32_e32 v73, 0xbfb8aa3b, v73
	v_exp_f32_e32 v74, v74
	v_exp_f32_e32 v76, v75
	v_exp_f32_e32 v75, v73
	v_mov_b32_e32 v58, v214
	v_mov_b32_e32 v59, v215
	v_mov_b32_e32 v60, v216
	v_mov_b32_e32 v61, v217
	v_lshlrev_b32_e32 v78, 16, v58
	v_pk_add_f32 v[74:75], v[74:75], 1.0 op_sel_hi:[1,0]
	v_and_b32_e32 v79, 0xffff0000, v58
	v_div_scale_f32 v58, s[22:23], v75, v75, 1.0
	v_mov_b32_e32 v62, v218
	v_mov_b32_e32 v63, v219
	v_mov_b32_e32 v64, v220
	v_mov_b32_e32 v65, v221
	v_add_u32_e32 v213, 0xa0, v146
	v_mad_i64_i32 v[246:247], s[22:23], v213, s79, v[152:153]
	v_lshl_add_u64 v[246:247], v[246:247], 0, s[30:31]
	v_lshl_add_u64 v[246:247], v[246:247], 0, v[142:143]
	global_load_dwordx4 v[184:187], v[246:247], off
	v_mov_b32_e32 v248, v213
	v_ashrrev_i32_e32 v249, 31, v213
	v_lshlrev_b64 v[248:249], 12, v[248:249]
	v_lshl_add_u64 v[250:251], s[26:27], 0, v[248:249]
	v_lshl_add_u64 v[250:251], v[250:251], 0, v[142:143]
	global_load_dwordx4 v[214:217], v[250:251], off
	v_lshl_add_u64 v[248:249], s[90:91], 0, v[248:249]
	v_lshl_add_u64 v[248:249], v[248:249], 0, v[142:143]
	global_load_dwordx4 v[218:221], v[248:249], off
	v_lshlrev_b32_e32 v80, 16, v62
	v_and_b32_e32 v81, 0xffff0000, v62
	v_rcp_f32_e32 v62, v58
	v_pk_add_f32 v[78:79], v[78:79], v[80:81]
	v_fma_f32 v73, -v58, v62, 1.0
	v_fmac_f32_e32 v62, v73, v62
	v_div_scale_f32 v73, vcc, 1.0, v75, 1.0
	v_mul_f32_e32 v77, v73, v62
	v_fma_f32 v80, -v58, v77, v73
	v_fmac_f32_e32 v77, v80, v62
	v_fma_f32 v58, -v58, v77, v73
	v_div_fmas_f32 v58, v58, v62, v77
	v_div_fixup_f32 v75, v58, v75, 1.0
	v_div_scale_f32 v58, s[22:23], v74, v74, 1.0
	v_rcp_f32_e32 v62, v58
	s_nop 0
	v_fma_f32 v73, -v58, v62, 1.0
	v_fmac_f32_e32 v62, v73, v62
	v_div_scale_f32 v73, vcc, 1.0, v74, 1.0
	v_mul_f32_e32 v77, v73, v62
	v_fma_f32 v80, -v58, v77, v73
	v_fmac_f32_e32 v77, v80, v62
	v_fma_f32 v58, -v58, v77, v73
	v_div_fmas_f32 v58, v58, v62, v77
	v_div_fixup_f32 v74, v58, v74, 1.0
	v_mul_f32_e32 v58, 0xbfb8aa3b, v72
	v_exp_f32_e32 v77, v58
	v_pk_fma_f32 v[54:55], v[54:55], v[74:75], v[78:79]
	v_lshlrev_b32_e32 v72, 16, v60
	v_and_b32_e32 v73, 0xffff0000, v60
	v_lshlrev_b32_e32 v74, 16, v64
	v_and_b32_e32 v75, 0xffff0000, v64
	v_pk_add_f32 v[72:73], v[72:73], v[74:75]
	v_pk_add_f32 v[74:75], v[76:77], 1.0 op_sel_hi:[1,0]
	s_nop 0
	v_div_scale_f32 v58, s[22:23], v75, v75, 1.0
	v_rcp_f32_e32 v60, v58
	s_nop 0
	v_fma_f32 v62, -v58, v60, 1.0
	v_fmac_f32_e32 v60, v62, v60
	v_div_scale_f32 v62, vcc, 1.0, v75, 1.0
	v_mul_f32_e32 v64, v62, v60
	v_fma_f32 v76, -v58, v64, v62
	v_fmac_f32_e32 v64, v76, v60
	v_fma_f32 v58, -v58, v64, v62
	v_div_fmas_f32 v58, v58, v60, v64
	v_div_fixup_f32 v75, v58, v75, 1.0
	v_div_scale_f32 v58, s[22:23], v74, v74, 1.0
	v_rcp_f32_e32 v60, v58
	s_nop 0
	v_fma_f32 v62, -v58, v60, 1.0
	v_fmac_f32_e32 v60, v62, v60
	v_div_scale_f32 v62, vcc, 1.0, v74, 1.0
	v_mul_f32_e32 v64, v62, v60
	v_fma_f32 v76, -v58, v64, v62
	v_fmac_f32_e32 v64, v76, v60
	v_fma_f32 v58, -v58, v64, v62
	v_div_fmas_f32 v58, v58, v60, v64
	v_div_fixup_f32 v74, v58, v74, 1.0
	v_pk_fma_f32 v[72:73], v[50:51], v[74:75], v[72:73]
	v_mul_f32_e32 v51, 0xbfb8aa3b, v71
	v_mul_f32_e32 v50, 0xbfb8aa3b, v70
	v_exp_f32_e32 v58, v51
	v_mul_f32_e32 v51, 0xbfb8aa3b, v69
	v_exp_f32_e32 v50, v50
	v_exp_f32_e32 v51, v51
	v_lshlrev_b32_e32 v70, 16, v59
	v_and_b32_e32 v71, 0xffff0000, v59
	v_lshlrev_b32_e32 v62, 16, v63
	v_pk_add_f32 v[50:51], v[50:51], 1.0 op_sel_hi:[1,0]
	v_and_b32_e32 v63, 0xffff0000, v63
	v_div_scale_f32 v59, s[22:23], v51, v51, 1.0
	v_rcp_f32_e32 v60, v59
	v_pk_add_f32 v[62:63], v[70:71], v[62:63]
	v_fma_f32 v64, -v59, v60, 1.0
	v_fmac_f32_e32 v60, v64, v60
	v_div_scale_f32 v64, vcc, 1.0, v51, 1.0
	v_mul_f32_e32 v69, v64, v60
	v_fma_f32 v70, -v59, v69, v64
	v_fmac_f32_e32 v69, v70, v60
	v_fma_f32 v59, -v59, v69, v64
	v_div_fmas_f32 v59, v59, v60, v69
	v_div_fixup_f32 v51, v59, v51, 1.0
	v_div_scale_f32 v59, s[22:23], v50, v50, 1.0
	v_rcp_f32_e32 v60, v59
	s_nop 0
	v_fma_f32 v64, -v59, v60, 1.0
	v_fmac_f32_e32 v60, v64, v60
	v_div_scale_f32 v64, vcc, 1.0, v50, 1.0
	v_mul_f32_e32 v69, v64, v60
	v_fma_f32 v70, -v59, v69, v64
	v_fmac_f32_e32 v69, v70, v60
	v_fma_f32 v59, -v59, v69, v64
	v_div_fmas_f32 v59, v59, v60, v69
	v_div_fixup_f32 v50, v59, v50, 1.0
	v_pk_fma_f32 v[56:57], v[56:57], v[50:51], v[62:63]
	v_mul_f32_e32 v50, 0xbfb8aa3b, v68
	v_exp_f32_e32 v59, v50
	v_lshlrev_b32_e32 v50, 16, v61
	v_and_b32_e32 v51, 0xffff0000, v61
	v_lshlrev_b32_e32 v60, 16, v65
	v_and_b32_e32 v61, 0xffff0000, v65
	v_pk_add_f32 v[58:59], v[58:59], 1.0 op_sel_hi:[1,0]
	v_pk_add_f32 v[50:51], v[50:51], v[60:61]
	v_div_scale_f32 v60, s[22:23], v59, v59, 1.0
	v_rcp_f32_e32 v61, v60
	s_nop 0
	v_fma_f32 v62, -v60, v61, 1.0
	v_fmac_f32_e32 v61, v62, v61
	v_div_scale_f32 v62, vcc, 1.0, v59, 1.0
	v_mul_f32_e32 v63, v62, v61
	v_fma_f32 v64, -v60, v63, v62
	v_fmac_f32_e32 v63, v64, v61
	v_fma_f32 v60, -v60, v63, v62
	v_div_fmas_f32 v60, v60, v61, v63
	v_div_fixup_f32 v59, v60, v59, 1.0
	v_div_scale_f32 v60, s[22:23], v58, v58, 1.0
	v_rcp_f32_e32 v61, v60
	s_nop 0
	v_fma_f32 v62, -v60, v61, 1.0
	v_fmac_f32_e32 v61, v62, v61
	v_div_scale_f32 v62, vcc, 1.0, v58, 1.0
	v_mul_f32_e32 v63, v62, v61
	v_fma_f32 v64, -v60, v63, v62
	v_fmac_f32_e32 v63, v64, v61
	v_fma_f32 v60, -v60, v63, v62
	v_div_fmas_f32 v60, v60, v61, v63
	v_div_fixup_f32 v58, v60, v58, 1.0
	v_pk_fma_f32 v[58:59], v[52:53], v[58:59], v[50:51]
	v_cvt_pk_bf16_f32 v50, v54, v55
	v_cvt_pk_bf16_f32 v51, v56, v57
	v_cvt_pk_bf16_f32 v52, v72, v73
	v_cvt_pk_bf16_f32 v53, v58, v59
	v_add_u32_e32 v54, 0x90, v146
	global_store_dwordx4 v[66:67], v[50:53], off offset:256
	v_ashrrev_i32_e32 v55, 31, v54
	v_lshlrev_b64 v[64:65], 12, v[54:55]
	v_mad_i64_i32 v[50:51], s[22:23], v54, s79, v[152:153]
	v_lshl_add_u64 v[62:63], v[50:51], 0, s[30:31]
	v_lshl_add_u64 v[50:51], v[62:63], 0, v[142:143]
	v_lshl_add_u64 v[54:55], s[90:91], 0, v[64:65]
	v_lshl_add_u64 v[58:59], v[54:55], 0, v[142:143]
	s_waitcnt vmcnt(9)
; __device__ __forceinline__ unsigned pk2(float lo, float hi) { return pg8::cvt_pk_bf16(lo, hi); }
; __device__ __forceinline__ float sigmoidf_(float x) { return 1.f / (1.f + __expf(-x)); }
;     __device__ __forceinline__ void operator()(const f32x4 (&acc)[2][2][4][2], const pg8::Unit& u, int wr, int wc, int fr, int fq) const {
;     ...
;             for (int m = 0; m < 4; ++m) { const int row = row0 + ai * 128 + m * 16;
; #pragma unroll
;                 for (int bj = 0; bj < 2; ++bj) { const int col = col0 + bj * 128;
;                     const u32x4 gw = *(const u32x4*)(P + (size_t)row * NINP + GATEOFF + 2 * 2048 + col); float gt[8]; unpack8(gw, gt);
;                     const u32x4 w0 = *(const u32x4*)(br0 + (size_t)row * D + col); float b0[8]; unpack8(w0, b0);
;                     const u32x4 w1 = *(const u32x4*)(br1 + (size_t)row * D + col); float b1[8]; unpack8(w1, b1);
;                     const f32x4 v0 = acc[ai][bj][m][0], v1 = acc[ai][bj][m][1];
;                     float o[8];
; #pragma unroll
;                     for (int j = 0; j < 4; ++j) { o[j] = b0[j] + b1[j] + sigmoidf_(gt[j]) * v0[j]; o[4 + j] = b0[4 + j] + b1[4 + j] + sigmoidf_(gt[4 + j]) * v1[j]; }
;                     u32x4 w; w.x = pk2(o[0], o[1]); w.y = pk2(o[2], o[3]); w.z = pk2(o[4], o[5]); w.w = pk2(o[6], o[7]);
;                     *(u32x4*)(mrg + (size_t)row * D + col) = w; } }
	s_nop 1
	v_mov_b32_e32 v50, v222
	v_mov_b32_e32 v51, v223
	v_mov_b32_e32 v52, v224
	v_mov_b32_e32 v53, v225
	v_lshlrev_b32_e32 v66, 16, v50
	v_and_b32_e32 v67, 0xffff0000, v50
	v_lshlrev_b32_e32 v74, 16, v51
	v_and_b32_e32 v75, 0xffff0000, v51
	v_lshl_add_u64 v[50:51], s[26:27], 0, v[64:65]
	v_lshl_add_u64 v[60:61], v[50:51], 0, v[142:143]
	v_lshlrev_b32_e32 v68, 16, v52
	v_and_b32_e32 v69, 0xffff0000, v52
	v_lshlrev_b32_e32 v76, 16, v53
	v_and_b32_e32 v77, 0xffff0000, v53
	v_mul_f32_e32 v66, 0xbfb8aa3b, v66
	v_mul_f32_e32 v67, 0xbfb8aa3b, v67
	v_exp_f32_e32 v66, v66
	v_exp_f32_e32 v67, v67
	v_mov_b32_e32 v54, v226
	v_mov_b32_e32 v55, v227
	v_mov_b32_e32 v56, v228
	v_mov_b32_e32 v57, v229
	v_lshlrev_b32_e32 v72, 16, v54
	v_and_b32_e32 v73, 0xffff0000, v54
	v_mul_f32_e32 v68, 0xbfb8aa3b, v68
	v_pk_add_f32 v[66:67], v[66:67], 1.0 op_sel_hi:[1,0]
	v_exp_f32_e32 v68, v68
	v_mov_b32_e32 v50, v230
	v_mov_b32_e32 v51, v231
	v_mov_b32_e32 v52, v232
	v_mov_b32_e32 v53, v233
	v_add_u32_e32 v213, 0xa0, v146
	v_mad_i64_i32 v[246:247], s[22:23], v213, s79, v[152:153]
	v_lshl_add_u64 v[246:247], v[246:247], 0, s[30:31]
	v_lshl_add_u64 v[246:247], v[246:247], 0, v[142:143]
	global_load_dwordx4 v[222:225], v[246:247], off offset:256
	v_mov_b32_e32 v248, v213
	v_ashrrev_i32_e32 v249, 31, v213
	v_lshlrev_b64 v[248:249], 12, v[248:249]
	v_lshl_add_u64 v[250:251], s[26:27], 0, v[248:249]
	v_lshl_add_u64 v[250:251], v[250:251], 0, v[142:143]
	global_load_dwordx4 v[226:229], v[250:251], off offset:256
	v_lshl_add_u64 v[248:249], s[90:91], 0, v[248:249]
	v_lshl_add_u64 v[248:249], v[248:249], 0, v[142:143]
	global_load_dwordx4 v[230:233], v[248:249], off offset:256
	v_lshlrev_b32_e32 v70, 16, v50
	v_and_b32_e32 v71, 0xffff0000, v50
	v_div_scale_f32 v50, s[22:23], v67, v67, 1.0
	v_rcp_f32_e32 v54, v50
	v_pk_add_f32 v[70:71], v[70:71], v[72:73]
	v_fma_f32 v72, -v50, v54, 1.0
	v_fmac_f32_e32 v54, v72, v54
	v_div_scale_f32 v72, vcc, 1.0, v67, 1.0
	v_mul_f32_e32 v73, v72, v54
	v_fma_f32 v78, -v50, v73, v72
	v_fmac_f32_e32 v73, v78, v54
	v_fma_f32 v50, -v50, v73, v72
	v_div_fmas_f32 v50, v50, v54, v73
	v_div_fixup_f32 v67, v50, v67, 1.0
	v_div_scale_f32 v50, s[22:23], v66, v66, 1.0
	v_rcp_f32_e32 v54, v50
	s_nop 0
	v_fma_f32 v72, -v50, v54, 1.0
	v_fmac_f32_e32 v54, v72, v54
	v_div_scale_f32 v72, vcc, 1.0, v66, 1.0
	v_mul_f32_e32 v73, v72, v54
	v_fma_f32 v78, -v50, v73, v72
	v_fmac_f32_e32 v73, v78, v54
	v_fma_f32 v50, -v50, v73, v72
	v_div_fmas_f32 v50, v50, v54, v73
	v_div_fixup_f32 v66, v50, v66, 1.0
	v_mul_f32_e32 v50, 0xbfb8aa3b, v69
	v_exp_f32_e32 v69, v50
	v_pk_fma_f32 v[46:47], v[46:47], v[66:67], v[70:71]
	v_lshlrev_b32_e32 v66, 16, v52
	v_and_b32_e32 v67, 0xffff0000, v52
	v_pk_add_f32 v[68:69], v[68:69], 1.0 op_sel_hi:[1,0]
	v_lshlrev_b32_e32 v70, 16, v56
	v_div_scale_f32 v50, s[22:23], v69, v69, 1.0
	v_rcp_f32_e32 v52, v50
	v_and_b32_e32 v71, 0xffff0000, v56
	v_pk_add_f32 v[66:67], v[66:67], v[70:71]
	v_fma_f32 v54, -v50, v52, 1.0
	v_fmac_f32_e32 v52, v54, v52
	v_div_scale_f32 v54, vcc, 1.0, v69, 1.0
	v_mul_f32_e32 v56, v54, v52
	v_fma_f32 v70, -v50, v56, v54
	v_fmac_f32_e32 v56, v70, v52
	v_fma_f32 v50, -v50, v56, v54
	v_div_fmas_f32 v50, v50, v52, v56
	v_div_fixup_f32 v69, v50, v69, 1.0
	v_div_scale_f32 v50, s[22:23], v68, v68, 1.0
	v_rcp_f32_e32 v52, v50
	s_nop 0
	v_fma_f32 v54, -v50, v52, 1.0
	v_fmac_f32_e32 v52, v54, v52
	v_div_scale_f32 v54, vcc, 1.0, v68, 1.0
	v_mul_f32_e32 v56, v54, v52
	v_fma_f32 v70, -v50, v56, v54
	v_fmac_f32_e32 v56, v70, v52
	v_fma_f32 v50, -v50, v56, v54
	v_div_fmas_f32 v50, v50, v52, v56
	v_div_fixup_f32 v68, v50, v68, 1.0
	v_pk_fma_f32 v[66:67], v[42:43], v[68:69], v[66:67]
	v_mul_f32_e32 v43, 0xbfb8aa3b, v76
	v_mul_f32_e32 v42, 0xbfb8aa3b, v74
	v_exp_f32_e32 v50, v43
	v_mul_f32_e32 v43, 0xbfb8aa3b, v75
	v_exp_f32_e32 v42, v42
	v_exp_f32_e32 v43, v43
	v_lshlrev_b32_e32 v68, 16, v51
	v_and_b32_e32 v69, 0xffff0000, v51
	v_lshlrev_b32_e32 v54, 16, v55
	v_pk_add_f32 v[42:43], v[42:43], 1.0 op_sel_hi:[1,0]
	v_and_b32_e32 v55, 0xffff0000, v55
	v_div_scale_f32 v51, s[22:23], v43, v43, 1.0
	v_rcp_f32_e32 v52, v51
	v_pk_add_f32 v[54:55], v[68:69], v[54:55]
	v_fma_f32 v56, -v51, v52, 1.0
	v_fmac_f32_e32 v52, v56, v52
	v_div_scale_f32 v56, vcc, 1.0, v43, 1.0
	v_mul_f32_e32 v68, v56, v52
	v_fma_f32 v69, -v51, v68, v56
	v_fmac_f32_e32 v68, v69, v52
	v_fma_f32 v51, -v51, v68, v56
	v_div_fmas_f32 v51, v51, v52, v68
	v_div_fixup_f32 v43, v51, v43, 1.0
	v_div_scale_f32 v51, s[22:23], v42, v42, 1.0
	v_rcp_f32_e32 v52, v51
	s_nop 0
	v_fma_f32 v56, -v51, v52, 1.0
	v_fmac_f32_e32 v52, v56, v52
	v_div_scale_f32 v56, vcc, 1.0, v42, 1.0
	v_mul_f32_e32 v68, v56, v52
	v_fma_f32 v69, -v51, v68, v56
	v_fmac_f32_e32 v68, v69, v52
	v_fma_f32 v51, -v51, v68, v56
	v_div_fmas_f32 v51, v51, v52, v68
	v_div_fixup_f32 v42, v51, v42, 1.0
	v_pk_fma_f32 v[48:49], v[48:49], v[42:43], v[54:55]
	v_mul_f32_e32 v42, 0xbfb8aa3b, v77
	v_exp_f32_e32 v51, v42
	v_lshlrev_b32_e32 v42, 16, v53
	v_and_b32_e32 v43, 0xffff0000, v53
	v_lshlrev_b32_e32 v52, 16, v57
	v_and_b32_e32 v53, 0xffff0000, v57
	v_pk_add_f32 v[50:51], v[50:51], 1.0 op_sel_hi:[1,0]
	v_pk_add_f32 v[42:43], v[42:43], v[52:53]
	v_div_scale_f32 v52, s[22:23], v51, v51, 1.0
	v_rcp_f32_e32 v53, v52
	s_nop 0
	v_fma_f32 v54, -v52, v53, 1.0
	v_fmac_f32_e32 v53, v54, v53
	v_div_scale_f32 v54, vcc, 1.0, v51, 1.0
	v_mul_f32_e32 v55, v54, v53
	v_fma_f32 v56, -v52, v55, v54
	v_fmac_f32_e32 v55, v56, v53
	v_fma_f32 v52, -v52, v55, v54
	v_div_fmas_f32 v52, v52, v53, v55
	v_div_fixup_f32 v51, v52, v51, 1.0
	v_div_scale_f32 v52, s[22:23], v50, v50, 1.0
	v_rcp_f32_e32 v53, v52
	s_nop 0
	v_fma_f32 v54, -v52, v53, 1.0
	v_fmac_f32_e32 v53, v54, v53
	v_div_scale_f32 v54, vcc, 1.0, v50, 1.0
	v_mul_f32_e32 v55, v54, v53
	v_fma_f32 v56, -v52, v55, v54
	v_fmac_f32_e32 v55, v56, v53
	v_fma_f32 v52, -v52, v55, v54
	v_div_fmas_f32 v52, v52, v53, v55
	v_div_fixup_f32 v50, v52, v50, 1.0
	v_pk_fma_f32 v[50:51], v[44:45], v[50:51], v[42:43]
	v_cvt_pk_bf16_f32 v42, v46, v47
	v_lshl_add_u64 v[46:47], s[28:29], 0, v[64:65]
	v_cvt_pk_bf16_f32 v43, v48, v49
	v_cvt_pk_bf16_f32 v44, v66, v67
	v_cvt_pk_bf16_f32 v45, v50, v51
	v_lshl_add_u64 v[50:51], v[46:47], 0, v[142:143]
	global_store_dwordx4 v[50:51], v[42:45], off
	s_nop 1
	v_lshl_add_u64 v[42:43], v[62:63], 0, v[144:145]
	s_waitcnt vmcnt(9)
; __device__ __forceinline__ unsigned pk2(float lo, float hi) { return pg8::cvt_pk_bf16(lo, hi); }
; __device__ __forceinline__ float sigmoidf_(float x) { return 1.f / (1.f + __expf(-x)); }
;     __device__ __forceinline__ void operator()(const f32x4 (&acc)[2][2][4][2], const pg8::Unit& u, int wr, int wc, int fr, int fq) const {
;     ...
;             for (int m = 0; m < 4; ++m) { const int row = row0 + ai * 128 + m * 16;
; #pragma unroll
;                 for (int bj = 0; bj < 2; ++bj) { const int col = col0 + bj * 128;
;                     const u32x4 gw = *(const u32x4*)(P + (size_t)row * NINP + GATEOFF + 2 * 2048 + col); float gt[8]; unpack8(gw, gt);
;                     const u32x4 w0 = *(const u32x4*)(br0 + (size_t)row * D + col); float b0[8]; unpack8(w0, b0);
;                     const u32x4 w1 = *(const u32x4*)(br1 + (size_t)row * D + col); float b1[8]; unpack8(w1, b1);
;                     const f32x4 v0 = acc[ai][bj][m][0], v1 = acc[ai][bj][m][1];
;                     float o[8];
; #pragma unroll
;                     for (int j = 0; j < 4; ++j) { o[j] = b0[j] + b1[j] + sigmoidf_(gt[j]) * v0[j]; o[4 + j] = b0[4 + j] + b1[4 + j] + sigmoidf_(gt[4 + j]) * v1[j]; }
;                     u32x4 w; w.x = pk2(o[0], o[1]); w.y = pk2(o[2], o[3]); w.z = pk2(o[4], o[5]); w.w = pk2(o[6], o[7]);
;                     *(u32x4*)(mrg + (size_t)row * D + col) = w; } }
	s_nop 1
	v_mov_b32_e32 v42, v234
	v_mov_b32_e32 v43, v235
	v_mov_b32_e32 v44, v236
	v_mov_b32_e32 v45, v237
	v_lshlrev_b32_e32 v62, 16, v42
	v_and_b32_e32 v57, 0xffff0000, v42
	v_lshlrev_b32_e32 v54, 16, v43
	v_and_b32_e32 v53, 0xffff0000, v43
	v_lshlrev_b32_e32 v63, 16, v44
	v_and_b32_e32 v56, 0xffff0000, v44
	v_lshlrev_b32_e32 v55, 16, v45
	v_and_b32_e32 v52, 0xffff0000, v45
	v_mul_f32_e32 v58, 0xbfb8aa3b, v62
	v_mul_f32_e32 v59, 0xbfb8aa3b, v63
	v_mul_f32_e32 v57, 0xbfb8aa3b, v57
	v_exp_f32_e32 v58, v58
	v_exp_f32_e32 v60, v59
	v_exp_f32_e32 v59, v57
	v_mov_b32_e32 v42, v238
	v_mov_b32_e32 v43, v239
	v_mov_b32_e32 v44, v240
	v_mov_b32_e32 v45, v241
	v_lshlrev_b32_e32 v62, 16, v42
	v_pk_add_f32 v[58:59], v[58:59], 1.0 op_sel_hi:[1,0]
	v_and_b32_e32 v63, 0xffff0000, v42
	v_div_scale_f32 v42, s[22:23], v59, v59, 1.0
	v_mov_b32_e32 v46, v242
	v_mov_b32_e32 v47, v243
	v_mov_b32_e32 v48, v244
	v_mov_b32_e32 v49, v245
	v_add_u32_e32 v213, 0xb0, v146
	v_mad_i64_i32 v[246:247], s[22:23], v213, s79, v[152:153]
	v_lshl_add_u64 v[246:247], v[246:247], 0, s[30:31]
	v_lshl_add_u64 v[246:247], v[246:247], 0, v[142:143]
	global_load_dwordx4 v[234:237], v[246:247], off
	v_mov_b32_e32 v248, v213
	v_ashrrev_i32_e32 v249, 31, v213
	v_lshlrev_b64 v[248:249], 12, v[248:249]
	v_lshl_add_u64 v[250:251], s[26:27], 0, v[248:249]
	v_lshl_add_u64 v[250:251], v[250:251], 0, v[142:143]
	global_load_dwordx4 v[238:241], v[250:251], off
	v_lshl_add_u64 v[248:249], s[90:91], 0, v[248:249]
	v_lshl_add_u64 v[248:249], v[248:249], 0, v[142:143]
	global_load_dwordx4 v[242:245], v[248:249], off
	v_lshlrev_b32_e32 v64, 16, v46
	v_and_b32_e32 v65, 0xffff0000, v46
	v_rcp_f32_e32 v46, v42
	v_pk_add_f32 v[62:63], v[62:63], v[64:65]
	v_fma_f32 v57, -v42, v46, 1.0
	v_fmac_f32_e32 v46, v57, v46
	v_div_scale_f32 v57, vcc, 1.0, v59, 1.0
	v_mul_f32_e32 v61, v57, v46
	v_fma_f32 v64, -v42, v61, v57
	v_fmac_f32_e32 v61, v64, v46
	v_fma_f32 v42, -v42, v61, v57
	v_div_fmas_f32 v42, v42, v46, v61
	v_div_fixup_f32 v59, v42, v59, 1.0
	v_div_scale_f32 v42, s[22:23], v58, v58, 1.0
	v_rcp_f32_e32 v46, v42
	s_nop 0
	v_fma_f32 v57, -v42, v46, 1.0
	v_fmac_f32_e32 v46, v57, v46
	v_div_scale_f32 v57, vcc, 1.0, v58, 1.0
	v_mul_f32_e32 v61, v57, v46
	v_fma_f32 v64, -v42, v61, v57
	v_fmac_f32_e32 v61, v64, v46
	v_fma_f32 v42, -v42, v61, v57
	v_div_fmas_f32 v42, v42, v46, v61
	v_div_fixup_f32 v58, v42, v58, 1.0
	v_mul_f32_e32 v42, 0xbfb8aa3b, v56
	v_exp_f32_e32 v61, v42
	v_pk_fma_f32 v[38:39], v[38:39], v[58:59], v[62:63]
	v_lshlrev_b32_e32 v56, 16, v44
	v_and_b32_e32 v57, 0xffff0000, v44
	v_lshlrev_b32_e32 v58, 16, v48
	v_and_b32_e32 v59, 0xffff0000, v48
	v_pk_add_f32 v[56:57], v[56:57], v[58:59]
	v_pk_add_f32 v[58:59], v[60:61], 1.0 op_sel_hi:[1,0]
	s_nop 0
	v_div_scale_f32 v42, s[22:23], v59, v59, 1.0
	v_rcp_f32_e32 v44, v42
	s_nop 0
	v_fma_f32 v46, -v42, v44, 1.0
	v_fmac_f32_e32 v44, v46, v44
	v_div_scale_f32 v46, vcc, 1.0, v59, 1.0
	v_mul_f32_e32 v48, v46, v44
	v_fma_f32 v60, -v42, v48, v46
	v_fmac_f32_e32 v48, v60, v44
	v_fma_f32 v42, -v42, v48, v46
	v_div_fmas_f32 v42, v42, v44, v48
	v_div_fixup_f32 v59, v42, v59, 1.0
	v_div_scale_f32 v42, s[22:23], v58, v58, 1.0
	v_rcp_f32_e32 v44, v42
	s_nop 0
	v_fma_f32 v46, -v42, v44, 1.0
	v_fmac_f32_e32 v44, v46, v44
	v_div_scale_f32 v46, vcc, 1.0, v58, 1.0
	v_mul_f32_e32 v48, v46, v44
	v_fma_f32 v60, -v42, v48, v46
	v_fmac_f32_e32 v48, v60, v44
	v_fma_f32 v42, -v42, v48, v46
	v_div_fmas_f32 v42, v42, v44, v48
	v_div_fixup_f32 v58, v42, v58, 1.0
	v_pk_fma_f32 v[56:57], v[34:35], v[58:59], v[56:57]
	v_mul_f32_e32 v35, 0xbfb8aa3b, v55
	v_mul_f32_e32 v34, 0xbfb8aa3b, v54
	v_exp_f32_e32 v42, v35
	v_mul_f32_e32 v35, 0xbfb8aa3b, v53
	v_exp_f32_e32 v34, v34
	v_exp_f32_e32 v35, v35
	v_lshlrev_b32_e32 v54, 16, v43
	v_and_b32_e32 v55, 0xffff0000, v43
	v_lshlrev_b32_e32 v46, 16, v47
	v_pk_add_f32 v[34:35], v[34:35], 1.0 op_sel_hi:[1,0]
	v_and_b32_e32 v47, 0xffff0000, v47
	v_div_scale_f32 v43, s[22:23], v35, v35, 1.0
	v_rcp_f32_e32 v44, v43
	v_pk_add_f32 v[46:47], v[54:55], v[46:47]
	v_fma_f32 v48, -v43, v44, 1.0
	v_fmac_f32_e32 v44, v48, v44
	v_div_scale_f32 v48, vcc, 1.0, v35, 1.0
	v_mul_f32_e32 v53, v48, v44
	v_fma_f32 v54, -v43, v53, v48
	v_fmac_f32_e32 v53, v54, v44
	v_fma_f32 v43, -v43, v53, v48
	v_div_fmas_f32 v43, v43, v44, v53
	v_div_fixup_f32 v35, v43, v35, 1.0
	v_div_scale_f32 v43, s[22:23], v34, v34, 1.0
	v_rcp_f32_e32 v44, v43
	s_nop 0
	v_fma_f32 v48, -v43, v44, 1.0
	v_fmac_f32_e32 v44, v48, v44
	v_div_scale_f32 v48, vcc, 1.0, v34, 1.0
	v_mul_f32_e32 v53, v48, v44
	v_fma_f32 v54, -v43, v53, v48
	v_fmac_f32_e32 v53, v54, v44
	v_fma_f32 v43, -v43, v53, v48
	v_div_fmas_f32 v43, v43, v44, v53
	v_div_fixup_f32 v34, v43, v34, 1.0
	v_pk_fma_f32 v[40:41], v[40:41], v[34:35], v[46:47]
	v_mul_f32_e32 v34, 0xbfb8aa3b, v52
	v_exp_f32_e32 v43, v34
	v_lshlrev_b32_e32 v34, 16, v45
	v_and_b32_e32 v35, 0xffff0000, v45
	v_lshlrev_b32_e32 v44, 16, v49
	v_and_b32_e32 v45, 0xffff0000, v49
	v_pk_add_f32 v[42:43], v[42:43], 1.0 op_sel_hi:[1,0]
	v_pk_add_f32 v[34:35], v[34:35], v[44:45]
	v_div_scale_f32 v44, s[22:23], v43, v43, 1.0
	v_rcp_f32_e32 v45, v44
	s_nop 0
	v_fma_f32 v46, -v44, v45, 1.0
	v_fmac_f32_e32 v45, v46, v45
	v_div_scale_f32 v46, vcc, 1.0, v43, 1.0
	v_mul_f32_e32 v47, v46, v45
	v_fma_f32 v48, -v44, v47, v46
	v_fmac_f32_e32 v47, v48, v45
	v_fma_f32 v44, -v44, v47, v46
	v_div_fmas_f32 v44, v44, v45, v47
	v_div_fixup_f32 v43, v44, v43, 1.0
	v_div_scale_f32 v44, s[22:23], v42, v42, 1.0
	v_rcp_f32_e32 v45, v44
	s_nop 0
	v_fma_f32 v46, -v44, v45, 1.0
	v_fmac_f32_e32 v45, v46, v45
	v_div_scale_f32 v46, vcc, 1.0, v42, 1.0
	v_mul_f32_e32 v47, v46, v45
	v_fma_f32 v48, -v44, v47, v46
	v_fmac_f32_e32 v47, v48, v45
	v_fma_f32 v44, -v44, v47, v46
	v_div_fmas_f32 v44, v44, v45, v47
	v_div_fixup_f32 v42, v44, v42, 1.0
	v_pk_fma_f32 v[42:43], v[36:37], v[42:43], v[34:35]
	v_cvt_pk_bf16_f32 v34, v38, v39
	v_cvt_pk_bf16_f32 v35, v40, v41
	v_cvt_pk_bf16_f32 v36, v56, v57
	v_cvt_pk_bf16_f32 v37, v42, v43
	v_add_u32_e32 v38, 0xa0, v146
	global_store_dwordx4 v[50:51], v[34:37], off offset:256
	v_ashrrev_i32_e32 v39, 31, v38
	v_lshlrev_b64 v[48:49], 12, v[38:39]
	v_mad_i64_i32 v[34:35], s[22:23], v38, s79, v[152:153]
	v_lshl_add_u64 v[46:47], v[34:35], 0, s[30:31]
	v_lshl_add_u64 v[34:35], v[46:47], 0, v[142:143]
	v_lshl_add_u64 v[38:39], s[90:91], 0, v[48:49]
	v_lshl_add_u64 v[42:43], v[38:39], 0, v[142:143]
	s_waitcnt vmcnt(9)
; __device__ __forceinline__ unsigned pk2(float lo, float hi) { return pg8::cvt_pk_bf16(lo, hi); }
; __device__ __forceinline__ float sigmoidf_(float x) { return 1.f / (1.f + __expf(-x)); }
;     __device__ __forceinline__ void operator()(const f32x4 (&acc)[2][2][4][2], const pg8::Unit& u, int wr, int wc, int fr, int fq) const {
;     ...
;             for (int m = 0; m < 4; ++m) { const int row = row0 + ai * 128 + m * 16;
; #pragma unroll
;                 for (int bj = 0; bj < 2; ++bj) { const int col = col0 + bj * 128;
;                     const u32x4 gw = *(const u32x4*)(P + (size_t)row * NINP + GATEOFF + 2 * 2048 + col); float gt[8]; unpack8(gw, gt);
;                     const u32x4 w0 = *(const u32x4*)(br0 + (size_t)row * D + col); float b0[8]; unpack8(w0, b0);
;                     const u32x4 w1 = *(const u32x4*)(br1 + (size_t)row * D + col); float b1[8]; unpack8(w1, b1);
;                     const f32x4 v0 = acc[ai][bj][m][0], v1 = acc[ai][bj][m][1];
;                     float o[8];
; #pragma unroll
;                     for (int j = 0; j < 4; ++j) { o[j] = b0[j] + b1[j] + sigmoidf_(gt[j]) * v0[j]; o[4 + j] = b0[4 + j] + b1[4 + j] + sigmoidf_(gt[4 + j]) * v1[j]; }
;                     u32x4 w; w.x = pk2(o[0], o[1]); w.y = pk2(o[2], o[3]); w.z = pk2(o[4], o[5]); w.w = pk2(o[6], o[7]);
;                     *(u32x4*)(mrg + (size_t)row * D + col) = w; } }
	s_nop 1
	v_mov_b32_e32 v34, v184
	v_mov_b32_e32 v35, v185
	v_mov_b32_e32 v36, v186
	v_mov_b32_e32 v37, v187
	v_lshlrev_b32_e32 v50, 16, v34
	v_and_b32_e32 v51, 0xffff0000, v34
	v_lshlrev_b32_e32 v58, 16, v35
	v_and_b32_e32 v59, 0xffff0000, v35
	v_lshl_add_u64 v[34:35], s[26:27], 0, v[48:49]
	v_lshl_add_u64 v[44:45], v[34:35], 0, v[142:143]
	v_lshlrev_b32_e32 v52, 16, v36
	v_and_b32_e32 v53, 0xffff0000, v36
	v_lshlrev_b32_e32 v60, 16, v37
	v_and_b32_e32 v61, 0xffff0000, v37
	v_mul_f32_e32 v50, 0xbfb8aa3b, v50
	v_mul_f32_e32 v51, 0xbfb8aa3b, v51
	v_exp_f32_e32 v50, v50
	v_exp_f32_e32 v51, v51
	v_mov_b32_e32 v38, v214
	v_mov_b32_e32 v39, v215
	v_mov_b32_e32 v40, v216
	v_mov_b32_e32 v41, v217
	v_lshlrev_b32_e32 v56, 16, v38
	v_and_b32_e32 v57, 0xffff0000, v38
	v_mul_f32_e32 v52, 0xbfb8aa3b, v52
	v_pk_add_f32 v[50:51], v[50:51], 1.0 op_sel_hi:[1,0]
	v_exp_f32_e32 v52, v52
	v_mov_b32_e32 v34, v218
	v_mov_b32_e32 v35, v219
	v_mov_b32_e32 v36, v220
	v_mov_b32_e32 v37, v221
	v_add_u32_e32 v213, 0xb0, v146
	v_mad_i64_i32 v[246:247], s[22:23], v213, s79, v[152:153]
	v_lshl_add_u64 v[246:247], v[246:247], 0, s[30:31]
	v_lshl_add_u64 v[246:247], v[246:247], 0, v[142:143]
	global_load_dwordx4 v[184:187], v[246:247], off offset:256
	v_mov_b32_e32 v248, v213
	v_ashrrev_i32_e32 v249, 31, v213
	v_lshlrev_b64 v[248:249], 12, v[248:249]
	v_lshl_add_u64 v[250:251], s[26:27], 0, v[248:249]
	v_lshl_add_u64 v[250:251], v[250:251], 0, v[142:143]
	global_load_dwordx4 v[214:217], v[250:251], off offset:256
	v_lshl_add_u64 v[248:249], s[90:91], 0, v[248:249]
	v_lshl_add_u64 v[248:249], v[248:249], 0, v[142:143]
	global_load_dwordx4 v[218:221], v[248:249], off offset:256
	v_lshlrev_b32_e32 v54, 16, v34
	v_and_b32_e32 v55, 0xffff0000, v34
	v_div_scale_f32 v34, s[22:23], v51, v51, 1.0
	v_rcp_f32_e32 v38, v34
	v_pk_add_f32 v[54:55], v[54:55], v[56:57]
	v_fma_f32 v56, -v34, v38, 1.0
	v_fmac_f32_e32 v38, v56, v38
	v_div_scale_f32 v56, vcc, 1.0, v51, 1.0
	v_mul_f32_e32 v57, v56, v38
	v_fma_f32 v62, -v34, v57, v56
	v_fmac_f32_e32 v57, v62, v38
	v_fma_f32 v34, -v34, v57, v56
	v_div_fmas_f32 v34, v34, v38, v57
	v_div_fixup_f32 v51, v34, v51, 1.0
	v_div_scale_f32 v34, s[22:23], v50, v50, 1.0
	v_rcp_f32_e32 v38, v34
	s_nop 0
	v_fma_f32 v56, -v34, v38, 1.0
	v_fmac_f32_e32 v38, v56, v38
	v_div_scale_f32 v56, vcc, 1.0, v50, 1.0
	v_mul_f32_e32 v57, v56, v38
	v_fma_f32 v62, -v34, v57, v56
	v_fmac_f32_e32 v57, v62, v38
	v_fma_f32 v34, -v34, v57, v56
	v_div_fmas_f32 v34, v34, v38, v57
	v_div_fixup_f32 v50, v34, v50, 1.0
	v_mul_f32_e32 v34, 0xbfb8aa3b, v53
	v_exp_f32_e32 v53, v34
	v_pk_fma_f32 v[30:31], v[30:31], v[50:51], v[54:55]
	v_lshlrev_b32_e32 v50, 16, v36
	v_and_b32_e32 v51, 0xffff0000, v36
	v_pk_add_f32 v[52:53], v[52:53], 1.0 op_sel_hi:[1,0]
	v_lshlrev_b32_e32 v54, 16, v40
	v_div_scale_f32 v34, s[22:23], v53, v53, 1.0
	v_rcp_f32_e32 v36, v34
	v_and_b32_e32 v55, 0xffff0000, v40
	v_pk_add_f32 v[50:51], v[50:51], v[54:55]
	v_fma_f32 v38, -v34, v36, 1.0
	v_fmac_f32_e32 v36, v38, v36
	v_div_scale_f32 v38, vcc, 1.0, v53, 1.0
	v_mul_f32_e32 v40, v38, v36
	v_fma_f32 v54, -v34, v40, v38
	v_fmac_f32_e32 v40, v54, v36
	v_fma_f32 v34, -v34, v40, v38
	v_div_fmas_f32 v34, v34, v36, v40
	v_div_fixup_f32 v53, v34, v53, 1.0
	v_div_scale_f32 v34, s[22:23], v52, v52, 1.0
	v_rcp_f32_e32 v36, v34
	s_nop 0
	v_fma_f32 v38, -v34, v36, 1.0
	v_fmac_f32_e32 v36, v38, v36
	v_div_scale_f32 v38, vcc, 1.0, v52, 1.0
	v_mul_f32_e32 v40, v38, v36
	v_fma_f32 v54, -v34, v40, v38
	v_fmac_f32_e32 v40, v54, v36
	v_fma_f32 v34, -v34, v40, v38
	v_div_fmas_f32 v34, v34, v36, v40
	v_div_fixup_f32 v52, v34, v52, 1.0
	v_pk_fma_f32 v[50:51], v[26:27], v[52:53], v[50:51]
	v_mul_f32_e32 v27, 0xbfb8aa3b, v60
	v_mul_f32_e32 v26, 0xbfb8aa3b, v58
	v_exp_f32_e32 v34, v27
	v_mul_f32_e32 v27, 0xbfb8aa3b, v59
	v_exp_f32_e32 v26, v26
	v_exp_f32_e32 v27, v27
	v_lshlrev_b32_e32 v52, 16, v35
	v_and_b32_e32 v53, 0xffff0000, v35
	v_lshlrev_b32_e32 v38, 16, v39
	v_pk_add_f32 v[26:27], v[26:27], 1.0 op_sel_hi:[1,0]
	v_and_b32_e32 v39, 0xffff0000, v39
	v_div_scale_f32 v35, s[22:23], v27, v27, 1.0
	v_rcp_f32_e32 v36, v35
	v_pk_add_f32 v[38:39], v[52:53], v[38:39]
	v_fma_f32 v40, -v35, v36, 1.0
	v_fmac_f32_e32 v36, v40, v36
	v_div_scale_f32 v40, vcc, 1.0, v27, 1.0
	v_mul_f32_e32 v52, v40, v36
	v_fma_f32 v53, -v35, v52, v40
	v_fmac_f32_e32 v52, v53, v36
	v_fma_f32 v35, -v35, v52, v40
	v_div_fmas_f32 v35, v35, v36, v52
	v_div_fixup_f32 v27, v35, v27, 1.0
	v_div_scale_f32 v35, s[22:23], v26, v26, 1.0
	v_rcp_f32_e32 v36, v35
	s_nop 0
	v_fma_f32 v40, -v35, v36, 1.0
	v_fmac_f32_e32 v36, v40, v36
	v_div_scale_f32 v40, vcc, 1.0, v26, 1.0
	v_mul_f32_e32 v52, v40, v36
	v_fma_f32 v53, -v35, v52, v40
	v_fmac_f32_e32 v52, v53, v36
	v_fma_f32 v35, -v35, v52, v40
	v_div_fmas_f32 v35, v35, v36, v52
	v_div_fixup_f32 v26, v35, v26, 1.0
	v_pk_fma_f32 v[32:33], v[32:33], v[26:27], v[38:39]
	v_mul_f32_e32 v26, 0xbfb8aa3b, v61
	v_exp_f32_e32 v35, v26
	v_lshlrev_b32_e32 v26, 16, v37
	v_and_b32_e32 v27, 0xffff0000, v37
	v_lshlrev_b32_e32 v36, 16, v41
	v_and_b32_e32 v37, 0xffff0000, v41
	v_pk_add_f32 v[34:35], v[34:35], 1.0 op_sel_hi:[1,0]
	v_pk_add_f32 v[26:27], v[26:27], v[36:37]
	v_div_scale_f32 v36, s[22:23], v35, v35, 1.0
	v_rcp_f32_e32 v37, v36
	s_nop 0
	v_fma_f32 v38, -v36, v37, 1.0
	v_fmac_f32_e32 v37, v38, v37
	v_div_scale_f32 v38, vcc, 1.0, v35, 1.0
	v_mul_f32_e32 v39, v38, v37
	v_fma_f32 v40, -v36, v39, v38
	v_fmac_f32_e32 v39, v40, v37
	v_fma_f32 v36, -v36, v39, v38
	v_div_fmas_f32 v36, v36, v37, v39
	v_div_fixup_f32 v35, v36, v35, 1.0
	v_div_scale_f32 v36, s[22:23], v34, v34, 1.0
	v_rcp_f32_e32 v37, v36
	s_nop 0
	v_fma_f32 v38, -v36, v37, 1.0
	v_fmac_f32_e32 v37, v38, v37
	v_div_scale_f32 v38, vcc, 1.0, v34, 1.0
	v_mul_f32_e32 v39, v38, v37
	v_fma_f32 v40, -v36, v39, v38
	v_fmac_f32_e32 v39, v40, v37
	v_fma_f32 v36, -v36, v39, v38
	v_div_fmas_f32 v36, v36, v37, v39
	v_div_fixup_f32 v34, v36, v34, 1.0
	v_pk_fma_f32 v[34:35], v[28:29], v[34:35], v[26:27]
	v_cvt_pk_bf16_f32 v26, v30, v31
	v_lshl_add_u64 v[30:31], s[28:29], 0, v[48:49]
	v_cvt_pk_bf16_f32 v27, v32, v33
	v_cvt_pk_bf16_f32 v28, v50, v51
	v_cvt_pk_bf16_f32 v29, v34, v35
	v_lshl_add_u64 v[34:35], v[30:31], 0, v[142:143]
	global_store_dwordx4 v[34:35], v[26:29], off
	s_nop 1
	v_lshl_add_u64 v[26:27], v[46:47], 0, v[144:145]
	s_waitcnt vmcnt(9)
; __device__ __forceinline__ unsigned pk2(float lo, float hi) { return pg8::cvt_pk_bf16(lo, hi); }
; __device__ __forceinline__ float sigmoidf_(float x) { return 1.f / (1.f + __expf(-x)); }
;     __device__ __forceinline__ void operator()(const f32x4 (&acc)[2][2][4][2], const pg8::Unit& u, int wr, int wc, int fr, int fq) const {
;     ...
;             for (int m = 0; m < 4; ++m) { const int row = row0 + ai * 128 + m * 16;
; #pragma unroll
;                 for (int bj = 0; bj < 2; ++bj) { const int col = col0 + bj * 128;
;                     const u32x4 gw = *(const u32x4*)(P + (size_t)row * NINP + GATEOFF + 2 * 2048 + col); float gt[8]; unpack8(gw, gt);
;                     const u32x4 w0 = *(const u32x4*)(br0 + (size_t)row * D + col); float b0[8]; unpack8(w0, b0);
;                     const u32x4 w1 = *(const u32x4*)(br1 + (size_t)row * D + col); float b1[8]; unpack8(w1, b1);
;                     const f32x4 v0 = acc[ai][bj][m][0], v1 = acc[ai][bj][m][1];
;                     float o[8];
; #pragma unroll
;                     for (int j = 0; j < 4; ++j) { o[j] = b0[j] + b1[j] + sigmoidf_(gt[j]) * v0[j]; o[4 + j] = b0[4 + j] + b1[4 + j] + sigmoidf_(gt[4 + j]) * v1[j]; }
;                     u32x4 w; w.x = pk2(o[0], o[1]); w.y = pk2(o[2], o[3]); w.z = pk2(o[4], o[5]); w.w = pk2(o[6], o[7]);
;                     *(u32x4*)(mrg + (size_t)row * D + col) = w; } }
	s_nop 1
	v_mov_b32_e32 v26, v222
	v_mov_b32_e32 v27, v223
	v_mov_b32_e32 v28, v224
	v_mov_b32_e32 v29, v225
	v_lshlrev_b32_e32 v46, 16, v26
	v_and_b32_e32 v41, 0xffff0000, v26
	v_lshlrev_b32_e32 v38, 16, v27
	v_and_b32_e32 v37, 0xffff0000, v27
	v_lshlrev_b32_e32 v47, 16, v28
	v_and_b32_e32 v40, 0xffff0000, v28
	v_lshlrev_b32_e32 v39, 16, v29
	v_and_b32_e32 v36, 0xffff0000, v29
	v_mul_f32_e32 v42, 0xbfb8aa3b, v46
	v_mul_f32_e32 v43, 0xbfb8aa3b, v47
	v_mul_f32_e32 v41, 0xbfb8aa3b, v41
	v_exp_f32_e32 v42, v42
	v_exp_f32_e32 v44, v43
	v_exp_f32_e32 v43, v41
	v_mov_b32_e32 v26, v226
	v_mov_b32_e32 v27, v227
	v_mov_b32_e32 v28, v228
	v_mov_b32_e32 v29, v229
	v_lshlrev_b32_e32 v46, 16, v26
	v_pk_add_f32 v[42:43], v[42:43], 1.0 op_sel_hi:[1,0]
	v_and_b32_e32 v47, 0xffff0000, v26
	v_div_scale_f32 v26, s[22:23], v43, v43, 1.0
	v_mov_b32_e32 v30, v230
	v_mov_b32_e32 v31, v231
	v_mov_b32_e32 v32, v232
	v_mov_b32_e32 v33, v233
	v_lshlrev_b32_e32 v48, 16, v30
	v_and_b32_e32 v49, 0xffff0000, v30
	v_rcp_f32_e32 v30, v26
	v_pk_add_f32 v[46:47], v[46:47], v[48:49]
	v_fma_f32 v41, -v26, v30, 1.0
	v_fmac_f32_e32 v30, v41, v30
	v_div_scale_f32 v41, vcc, 1.0, v43, 1.0
	v_mul_f32_e32 v45, v41, v30
	v_fma_f32 v48, -v26, v45, v41
	v_fmac_f32_e32 v45, v48, v30
	v_fma_f32 v26, -v26, v45, v41
	v_div_fmas_f32 v26, v26, v30, v45
	v_div_fixup_f32 v43, v26, v43, 1.0
	v_div_scale_f32 v26, s[22:23], v42, v42, 1.0
	v_rcp_f32_e32 v30, v26
	s_nop 0
	v_fma_f32 v41, -v26, v30, 1.0
	v_fmac_f32_e32 v30, v41, v30
	v_div_scale_f32 v41, vcc, 1.0, v42, 1.0
	v_mul_f32_e32 v45, v41, v30
	v_fma_f32 v48, -v26, v45, v41
	v_fmac_f32_e32 v45, v48, v30
	v_fma_f32 v26, -v26, v45, v41
	v_div_fmas_f32 v26, v26, v30, v45
	v_div_fixup_f32 v42, v26, v42, 1.0
	v_mul_f32_e32 v26, 0xbfb8aa3b, v40
	v_exp_f32_e32 v45, v26
	v_pk_fma_f32 v[22:23], v[22:23], v[42:43], v[46:47]
	v_lshlrev_b32_e32 v40, 16, v28
	v_and_b32_e32 v41, 0xffff0000, v28
	v_lshlrev_b32_e32 v42, 16, v32
	v_and_b32_e32 v43, 0xffff0000, v32
	v_pk_add_f32 v[40:41], v[40:41], v[42:43]
	v_pk_add_f32 v[42:43], v[44:45], 1.0 op_sel_hi:[1,0]
	s_nop 0
	v_div_scale_f32 v26, s[22:23], v43, v43, 1.0
	v_rcp_f32_e32 v28, v26
	s_nop 0
	v_fma_f32 v30, -v26, v28, 1.0
	v_fmac_f32_e32 v28, v30, v28
	v_div_scale_f32 v30, vcc, 1.0, v43, 1.0
	v_mul_f32_e32 v32, v30, v28
	v_fma_f32 v44, -v26, v32, v30
	v_fmac_f32_e32 v32, v44, v28
	v_fma_f32 v26, -v26, v32, v30
	v_div_fmas_f32 v26, v26, v28, v32
	v_div_fixup_f32 v43, v26, v43, 1.0
	v_div_scale_f32 v26, s[22:23], v42, v42, 1.0
	v_rcp_f32_e32 v28, v26
	s_nop 0
	v_fma_f32 v30, -v26, v28, 1.0
	v_fmac_f32_e32 v28, v30, v28
	v_div_scale_f32 v30, vcc, 1.0, v42, 1.0
	v_mul_f32_e32 v32, v30, v28
	v_fma_f32 v44, -v26, v32, v30
	v_fmac_f32_e32 v32, v44, v28
	v_fma_f32 v26, -v26, v32, v30
	v_div_fmas_f32 v26, v26, v28, v32
	v_div_fixup_f32 v42, v26, v42, 1.0
	v_pk_fma_f32 v[40:41], v[18:19], v[42:43], v[40:41]
	v_mul_f32_e32 v19, 0xbfb8aa3b, v39
	v_mul_f32_e32 v18, 0xbfb8aa3b, v38
	v_exp_f32_e32 v26, v19
	v_mul_f32_e32 v19, 0xbfb8aa3b, v37
	v_exp_f32_e32 v18, v18
	v_exp_f32_e32 v19, v19
	v_lshlrev_b32_e32 v38, 16, v27
	v_and_b32_e32 v39, 0xffff0000, v27
	v_lshlrev_b32_e32 v30, 16, v31
	v_pk_add_f32 v[18:19], v[18:19], 1.0 op_sel_hi:[1,0]
	v_and_b32_e32 v31, 0xffff0000, v31
	v_div_scale_f32 v27, s[22:23], v19, v19, 1.0
	v_rcp_f32_e32 v28, v27
	v_pk_add_f32 v[30:31], v[38:39], v[30:31]
	v_fma_f32 v32, -v27, v28, 1.0
	v_fmac_f32_e32 v28, v32, v28
	v_div_scale_f32 v32, vcc, 1.0, v19, 1.0
	v_mul_f32_e32 v37, v32, v28
	v_fma_f32 v38, -v27, v37, v32
	v_fmac_f32_e32 v37, v38, v28
	v_fma_f32 v27, -v27, v37, v32
	v_div_fmas_f32 v27, v27, v28, v37
	v_div_fixup_f32 v19, v27, v19, 1.0
	v_div_scale_f32 v27, s[22:23], v18, v18, 1.0
	v_rcp_f32_e32 v28, v27
	s_nop 0
	v_fma_f32 v32, -v27, v28, 1.0
	v_fmac_f32_e32 v28, v32, v28
	v_div_scale_f32 v32, vcc, 1.0, v18, 1.0
	v_mul_f32_e32 v37, v32, v28
	v_fma_f32 v38, -v27, v37, v32
	v_fmac_f32_e32 v37, v38, v28
	v_fma_f32 v27, -v27, v37, v32
	v_div_fmas_f32 v27, v27, v28, v37
	v_div_fixup_f32 v18, v27, v18, 1.0
	v_pk_fma_f32 v[24:25], v[24:25], v[18:19], v[30:31]
	v_mul_f32_e32 v18, 0xbfb8aa3b, v36
	v_exp_f32_e32 v27, v18
	v_lshlrev_b32_e32 v18, 16, v29
	v_and_b32_e32 v19, 0xffff0000, v29
	v_lshlrev_b32_e32 v28, 16, v33
	v_and_b32_e32 v29, 0xffff0000, v33
	v_pk_add_f32 v[26:27], v[26:27], 1.0 op_sel_hi:[1,0]
	v_pk_add_f32 v[18:19], v[18:19], v[28:29]
	v_div_scale_f32 v28, s[22:23], v27, v27, 1.0
	v_rcp_f32_e32 v29, v28
	s_nop 0
	v_fma_f32 v30, -v28, v29, 1.0
	v_fmac_f32_e32 v29, v30, v29
	v_div_scale_f32 v30, vcc, 1.0, v27, 1.0
	v_mul_f32_e32 v31, v30, v29
	v_fma_f32 v32, -v28, v31, v30
	v_fmac_f32_e32 v31, v32, v29
	v_fma_f32 v28, -v28, v31, v30
	v_div_fmas_f32 v28, v28, v29, v31
	v_div_fixup_f32 v27, v28, v27, 1.0
	v_div_scale_f32 v28, s[22:23], v26, v26, 1.0
	v_rcp_f32_e32 v29, v28
	s_nop 0
	v_fma_f32 v30, -v28, v29, 1.0
	v_fmac_f32_e32 v29, v30, v29
	v_div_scale_f32 v30, vcc, 1.0, v26, 1.0
	v_mul_f32_e32 v31, v30, v29
	v_fma_f32 v32, -v28, v31, v30
	v_fmac_f32_e32 v31, v32, v29
	v_fma_f32 v28, -v28, v31, v30
	v_div_fmas_f32 v28, v28, v29, v31
	v_div_fixup_f32 v26, v28, v26, 1.0
	v_pk_fma_f32 v[26:27], v[20:21], v[26:27], v[18:19]
	v_cvt_pk_bf16_f32 v18, v22, v23
	v_cvt_pk_bf16_f32 v19, v24, v25
	v_cvt_pk_bf16_f32 v20, v40, v41
	v_cvt_pk_bf16_f32 v21, v26, v27
	v_add_u32_e32 v22, 0xb0, v146
	global_store_dwordx4 v[34:35], v[18:21], off offset:256
	v_ashrrev_i32_e32 v23, 31, v22
	v_lshlrev_b64 v[32:33], 12, v[22:23]
	v_mad_i64_i32 v[18:19], s[22:23], v22, s79, v[152:153]
	v_lshl_add_u64 v[30:31], v[18:19], 0, s[30:31]
	v_lshl_add_u64 v[18:19], v[30:31], 0, v[142:143]
	v_lshl_add_u64 v[22:23], s[90:91], 0, v[32:33]
	v_lshl_add_u64 v[26:27], v[22:23], 0, v[142:143]
	s_waitcnt vmcnt(6)
; __device__ __forceinline__ unsigned pk2(float lo, float hi) { return pg8::cvt_pk_bf16(lo, hi); }
; __device__ __forceinline__ float sigmoidf_(float x) { return 1.f / (1.f + __expf(-x)); }
;     __device__ __forceinline__ void operator()(const f32x4 (&acc)[2][2][4][2], const pg8::Unit& u, int wr, int wc, int fr, int fq) const {
;     ...
;             for (int m = 0; m < 4; ++m) { const int row = row0 + ai * 128 + m * 16;
; #pragma unroll
;                 for (int bj = 0; bj < 2; ++bj) { const int col = col0 + bj * 128;
;                     const u32x4 gw = *(const u32x4*)(P + (size_t)row * NINP + GATEOFF + 2 * 2048 + col); float gt[8]; unpack8(gw, gt);
;                     const u32x4 w0 = *(const u32x4*)(br0 + (size_t)row * D + col); float b0[8]; unpack8(w0, b0);
;                     const u32x4 w1 = *(const u32x4*)(br1 + (size_t)row * D + col); float b1[8]; unpack8(w1, b1);
;                     const f32x4 v0 = acc[ai][bj][m][0], v1 = acc[ai][bj][m][1];
;                     float o[8];
; #pragma unroll
;                     for (int j = 0; j < 4; ++j) { o[j] = b0[j] + b1[j] + sigmoidf_(gt[j]) * v0[j]; o[4 + j] = b0[4 + j] + b1[4 + j] + sigmoidf_(gt[4 + j]) * v1[j]; }
;                     u32x4 w; w.x = pk2(o[0], o[1]); w.y = pk2(o[2], o[3]); w.z = pk2(o[4], o[5]); w.w = pk2(o[6], o[7]);
;                     *(u32x4*)(mrg + (size_t)row * D + col) = w; } }
	s_nop 1
	v_mov_b32_e32 v18, v234
	v_mov_b32_e32 v19, v235
	v_mov_b32_e32 v20, v236
	v_mov_b32_e32 v21, v237
	v_lshlrev_b32_e32 v34, 16, v18
	v_and_b32_e32 v35, 0xffff0000, v18
	v_lshlrev_b32_e32 v42, 16, v19
	v_and_b32_e32 v43, 0xffff0000, v19
	v_lshl_add_u64 v[18:19], s[26:27], 0, v[32:33]
	v_lshl_add_u64 v[28:29], v[18:19], 0, v[142:143]
	v_lshlrev_b32_e32 v36, 16, v20
	v_and_b32_e32 v37, 0xffff0000, v20
	v_lshlrev_b32_e32 v44, 16, v21
	v_and_b32_e32 v45, 0xffff0000, v21
	v_mul_f32_e32 v34, 0xbfb8aa3b, v34
	v_mul_f32_e32 v35, 0xbfb8aa3b, v35
	v_exp_f32_e32 v34, v34
	v_exp_f32_e32 v35, v35
	v_mov_b32_e32 v22, v238
	v_mov_b32_e32 v23, v239
	v_mov_b32_e32 v24, v240
	v_mov_b32_e32 v25, v241
	v_lshlrev_b32_e32 v40, 16, v22
	v_and_b32_e32 v41, 0xffff0000, v22
	v_mul_f32_e32 v36, 0xbfb8aa3b, v36
	v_pk_add_f32 v[34:35], v[34:35], 1.0 op_sel_hi:[1,0]
	v_exp_f32_e32 v36, v36
	v_mov_b32_e32 v18, v242
	v_mov_b32_e32 v19, v243
	v_mov_b32_e32 v20, v244
	v_mov_b32_e32 v21, v245
	v_lshlrev_b32_e32 v38, 16, v18
	v_and_b32_e32 v39, 0xffff0000, v18
	v_div_scale_f32 v18, s[22:23], v35, v35, 1.0
	v_rcp_f32_e32 v22, v18
	v_pk_add_f32 v[38:39], v[38:39], v[40:41]
	v_fma_f32 v40, -v18, v22, 1.0
	v_fmac_f32_e32 v22, v40, v22
	v_div_scale_f32 v40, vcc, 1.0, v35, 1.0
	v_mul_f32_e32 v41, v40, v22
	v_fma_f32 v46, -v18, v41, v40
	v_fmac_f32_e32 v41, v46, v22
	v_fma_f32 v18, -v18, v41, v40
	v_div_fmas_f32 v18, v18, v22, v41
	v_div_fixup_f32 v35, v18, v35, 1.0
	v_div_scale_f32 v18, s[22:23], v34, v34, 1.0
	v_rcp_f32_e32 v22, v18
	s_nop 0
	v_fma_f32 v40, -v18, v22, 1.0
	v_fmac_f32_e32 v22, v40, v22
	v_div_scale_f32 v40, vcc, 1.0, v34, 1.0
	v_mul_f32_e32 v41, v40, v22
	v_fma_f32 v46, -v18, v41, v40
	v_fmac_f32_e32 v41, v46, v22
	v_fma_f32 v18, -v18, v41, v40
	v_div_fmas_f32 v18, v18, v22, v41
	v_div_fixup_f32 v34, v18, v34, 1.0
	v_mul_f32_e32 v18, 0xbfb8aa3b, v37
	v_exp_f32_e32 v37, v18
	v_pk_fma_f32 v[14:15], v[14:15], v[34:35], v[38:39]
	v_lshlrev_b32_e32 v34, 16, v20
	v_and_b32_e32 v35, 0xffff0000, v20
	v_pk_add_f32 v[36:37], v[36:37], 1.0 op_sel_hi:[1,0]
	v_lshlrev_b32_e32 v38, 16, v24
	v_div_scale_f32 v18, s[22:23], v37, v37, 1.0
	v_rcp_f32_e32 v20, v18
	v_and_b32_e32 v39, 0xffff0000, v24
	v_pk_add_f32 v[34:35], v[34:35], v[38:39]
	v_fma_f32 v22, -v18, v20, 1.0
	v_fmac_f32_e32 v20, v22, v20
	v_div_scale_f32 v22, vcc, 1.0, v37, 1.0
	v_mul_f32_e32 v24, v22, v20
	v_fma_f32 v38, -v18, v24, v22
	v_fmac_f32_e32 v24, v38, v20
	v_fma_f32 v18, -v18, v24, v22
	v_div_fmas_f32 v18, v18, v20, v24
	v_div_fixup_f32 v37, v18, v37, 1.0
	v_div_scale_f32 v18, s[22:23], v36, v36, 1.0
	v_rcp_f32_e32 v20, v18
	s_nop 0
	v_fma_f32 v22, -v18, v20, 1.0
	v_fmac_f32_e32 v20, v22, v20
	v_div_scale_f32 v22, vcc, 1.0, v36, 1.0
	v_mul_f32_e32 v24, v22, v20
	v_fma_f32 v38, -v18, v24, v22
	v_fmac_f32_e32 v24, v38, v20
	v_fma_f32 v18, -v18, v24, v22
	v_div_fmas_f32 v18, v18, v20, v24
	v_div_fixup_f32 v36, v18, v36, 1.0
	v_pk_fma_f32 v[34:35], v[10:11], v[36:37], v[34:35]
	v_mul_f32_e32 v11, 0xbfb8aa3b, v44
	v_mul_f32_e32 v10, 0xbfb8aa3b, v42
	v_exp_f32_e32 v18, v11
	v_mul_f32_e32 v11, 0xbfb8aa3b, v43
	v_exp_f32_e32 v10, v10
	v_exp_f32_e32 v11, v11
	v_lshlrev_b32_e32 v36, 16, v19
	v_and_b32_e32 v37, 0xffff0000, v19
	v_lshlrev_b32_e32 v22, 16, v23
	v_pk_add_f32 v[10:11], v[10:11], 1.0 op_sel_hi:[1,0]
	v_and_b32_e32 v23, 0xffff0000, v23
	v_div_scale_f32 v19, s[22:23], v11, v11, 1.0
	v_rcp_f32_e32 v20, v19
	v_pk_add_f32 v[22:23], v[36:37], v[22:23]
	v_fma_f32 v24, -v19, v20, 1.0
	v_fmac_f32_e32 v20, v24, v20
	v_div_scale_f32 v24, vcc, 1.0, v11, 1.0
	v_mul_f32_e32 v36, v24, v20
	v_fma_f32 v37, -v19, v36, v24
	v_fmac_f32_e32 v36, v37, v20
	v_fma_f32 v19, -v19, v36, v24
	v_div_fmas_f32 v19, v19, v20, v36
	v_div_fixup_f32 v11, v19, v11, 1.0
	v_div_scale_f32 v19, s[22:23], v10, v10, 1.0
	v_rcp_f32_e32 v20, v19
	s_nop 0
	v_fma_f32 v24, -v19, v20, 1.0
	v_fmac_f32_e32 v20, v24, v20
	v_div_scale_f32 v24, vcc, 1.0, v10, 1.0
	v_mul_f32_e32 v36, v24, v20
	v_fma_f32 v37, -v19, v36, v24
	v_fmac_f32_e32 v36, v37, v20
	v_fma_f32 v19, -v19, v36, v24
	v_div_fmas_f32 v19, v19, v20, v36
	v_div_fixup_f32 v10, v19, v10, 1.0
	v_pk_fma_f32 v[16:17], v[16:17], v[10:11], v[22:23]
	v_mul_f32_e32 v10, 0xbfb8aa3b, v45
	v_exp_f32_e32 v19, v10
	v_lshlrev_b32_e32 v10, 16, v21
	v_and_b32_e32 v11, 0xffff0000, v21
	v_lshlrev_b32_e32 v20, 16, v25
	v_and_b32_e32 v21, 0xffff0000, v25
	v_pk_add_f32 v[18:19], v[18:19], 1.0 op_sel_hi:[1,0]
	v_pk_add_f32 v[10:11], v[10:11], v[20:21]
	v_div_scale_f32 v20, s[22:23], v19, v19, 1.0
	v_rcp_f32_e32 v21, v20
	s_nop 0
	v_fma_f32 v22, -v20, v21, 1.0
	v_fmac_f32_e32 v21, v22, v21
	v_div_scale_f32 v22, vcc, 1.0, v19, 1.0
	v_mul_f32_e32 v23, v22, v21
	v_fma_f32 v24, -v20, v23, v22
	v_fmac_f32_e32 v23, v24, v21
	v_fma_f32 v20, -v20, v23, v22
	v_div_fmas_f32 v20, v20, v21, v23
	v_div_fixup_f32 v19, v20, v19, 1.0
	v_div_scale_f32 v20, s[22:23], v18, v18, 1.0
	v_rcp_f32_e32 v21, v20
	s_nop 0
	v_fma_f32 v22, -v20, v21, 1.0
	v_fmac_f32_e32 v21, v22, v21
	v_div_scale_f32 v22, vcc, 1.0, v18, 1.0
	v_mul_f32_e32 v23, v22, v21
	v_fma_f32 v24, -v20, v23, v22
	v_fmac_f32_e32 v23, v24, v21
	v_fma_f32 v20, -v20, v23, v22
	v_div_fmas_f32 v20, v20, v21, v23
	v_div_fixup_f32 v18, v20, v18, 1.0
	v_pk_fma_f32 v[18:19], v[12:13], v[18:19], v[10:11]
	v_cvt_pk_bf16_f32 v10, v14, v15
	v_lshl_add_u64 v[14:15], s[28:29], 0, v[32:33]
	v_cvt_pk_bf16_f32 v11, v16, v17
	v_cvt_pk_bf16_f32 v12, v34, v35
	v_cvt_pk_bf16_f32 v13, v18, v19
	v_lshl_add_u64 v[18:19], v[14:15], 0, v[142:143]
	global_store_dwordx4 v[18:19], v[10:13], off
	s_nop 1
	v_lshl_add_u64 v[10:11], v[30:31], 0, v[144:145]
	s_waitcnt vmcnt(3)
; __device__ __forceinline__ unsigned pk2(float lo, float hi) { return pg8::cvt_pk_bf16(lo, hi); }
; __device__ __forceinline__ float sigmoidf_(float x) { return 1.f / (1.f + __expf(-x)); }
;     __device__ __forceinline__ void operator()(const f32x4 (&acc)[2][2][4][2], const pg8::Unit& u, int wr, int wc, int fr, int fq) const {
;     ...
;             for (int m = 0; m < 4; ++m) { const int row = row0 + ai * 128 + m * 16;
; #pragma unroll
;                 for (int bj = 0; bj < 2; ++bj) { const int col = col0 + bj * 128;
;                     const u32x4 gw = *(const u32x4*)(P + (size_t)row * NINP + GATEOFF + 2 * 2048 + col); float gt[8]; unpack8(gw, gt);
;                     const u32x4 w0 = *(const u32x4*)(br0 + (size_t)row * D + col); float b0[8]; unpack8(w0, b0);
;                     const u32x4 w1 = *(const u32x4*)(br1 + (size_t)row * D + col); float b1[8]; unpack8(w1, b1);
;                     const f32x4 v0 = acc[ai][bj][m][0], v1 = acc[ai][bj][m][1];
;                     float o[8];
; #pragma unroll
;                     for (int j = 0; j < 4; ++j) { o[j] = b0[j] + b1[j] + sigmoidf_(gt[j]) * v0[j]; o[4 + j] = b0[4 + j] + b1[4 + j] + sigmoidf_(gt[4 + j]) * v1[j]; }
;                     u32x4 w; w.x = pk2(o[0], o[1]); w.y = pk2(o[2], o[3]); w.z = pk2(o[4], o[5]); w.w = pk2(o[6], o[7]);
;                     *(u32x4*)(mrg + (size_t)row * D + col) = w; } }
	s_nop 1
	v_mov_b32_e32 v10, v184
	v_mov_b32_e32 v11, v185
	v_mov_b32_e32 v12, v186
	v_mov_b32_e32 v13, v187
	v_lshlrev_b32_e32 v30, 16, v10
	v_and_b32_e32 v25, 0xffff0000, v10
	v_lshlrev_b32_e32 v22, 16, v11
	v_and_b32_e32 v21, 0xffff0000, v11
	v_lshlrev_b32_e32 v31, 16, v12
	v_and_b32_e32 v24, 0xffff0000, v12
	v_lshlrev_b32_e32 v23, 16, v13
	v_and_b32_e32 v20, 0xffff0000, v13
	v_mul_f32_e32 v26, 0xbfb8aa3b, v30
	v_mul_f32_e32 v27, 0xbfb8aa3b, v31
	v_mul_f32_e32 v25, 0xbfb8aa3b, v25
	v_exp_f32_e32 v26, v26
	v_exp_f32_e32 v28, v27
	v_exp_f32_e32 v27, v25
	v_mov_b32_e32 v10, v214
	v_mov_b32_e32 v11, v215
	v_mov_b32_e32 v12, v216
	v_mov_b32_e32 v13, v217
	v_lshlrev_b32_e32 v30, 16, v10
	v_pk_add_f32 v[26:27], v[26:27], 1.0 op_sel_hi:[1,0]
	v_and_b32_e32 v31, 0xffff0000, v10
	v_div_scale_f32 v10, s[22:23], v27, v27, 1.0
	v_mov_b32_e32 v14, v218
	v_mov_b32_e32 v15, v219
	v_mov_b32_e32 v16, v220
	v_mov_b32_e32 v17, v221
	v_lshlrev_b32_e32 v32, 16, v14
	v_and_b32_e32 v33, 0xffff0000, v14
	v_rcp_f32_e32 v14, v10
	v_pk_add_f32 v[30:31], v[30:31], v[32:33]
	v_fma_f32 v25, -v10, v14, 1.0
	v_fmac_f32_e32 v14, v25, v14
	v_div_scale_f32 v25, vcc, 1.0, v27, 1.0
	v_mul_f32_e32 v29, v25, v14
	v_fma_f32 v32, -v10, v29, v25
	v_fmac_f32_e32 v29, v32, v14
	v_fma_f32 v10, -v10, v29, v25
	v_div_fmas_f32 v10, v10, v14, v29
	v_div_fixup_f32 v27, v10, v27, 1.0
	v_div_scale_f32 v10, s[22:23], v26, v26, 1.0
	v_rcp_f32_e32 v14, v10
	s_nop 0
	v_fma_f32 v25, -v10, v14, 1.0
	v_fmac_f32_e32 v14, v25, v14
	v_div_scale_f32 v25, vcc, 1.0, v26, 1.0
	v_mul_f32_e32 v29, v25, v14
	v_fma_f32 v32, -v10, v29, v25
	v_fmac_f32_e32 v29, v32, v14
	v_fma_f32 v10, -v10, v29, v25
	v_div_fmas_f32 v10, v10, v14, v29
	v_div_fixup_f32 v26, v10, v26, 1.0
	v_mul_f32_e32 v10, 0xbfb8aa3b, v24
	v_exp_f32_e32 v29, v10
	v_pk_fma_f32 v[6:7], v[6:7], v[26:27], v[30:31]
	v_lshlrev_b32_e32 v24, 16, v12
	v_and_b32_e32 v25, 0xffff0000, v12
	v_lshlrev_b32_e32 v26, 16, v16
	v_and_b32_e32 v27, 0xffff0000, v16
	v_pk_add_f32 v[24:25], v[24:25], v[26:27]
	v_pk_add_f32 v[26:27], v[28:29], 1.0 op_sel_hi:[1,0]
	s_nop 0
	v_div_scale_f32 v10, s[22:23], v27, v27, 1.0
	v_rcp_f32_e32 v12, v10
	s_nop 0
	v_fma_f32 v14, -v10, v12, 1.0
	v_fmac_f32_e32 v12, v14, v12
	v_div_scale_f32 v14, vcc, 1.0, v27, 1.0
	v_mul_f32_e32 v16, v14, v12
	v_fma_f32 v28, -v10, v16, v14
	v_fmac_f32_e32 v16, v28, v12
	v_fma_f32 v10, -v10, v16, v14
	v_div_fmas_f32 v10, v10, v12, v16
	v_div_fixup_f32 v27, v10, v27, 1.0
	v_div_scale_f32 v10, s[22:23], v26, v26, 1.0
	v_rcp_f32_e32 v12, v10
	s_nop 0
	v_fma_f32 v14, -v10, v12, 1.0
	v_fmac_f32_e32 v12, v14, v12
	v_div_scale_f32 v14, vcc, 1.0, v26, 1.0
	v_mul_f32_e32 v16, v14, v12
	v_fma_f32 v28, -v10, v16, v14
	v_fmac_f32_e32 v16, v28, v12
	v_fma_f32 v10, -v10, v16, v14
	v_div_fmas_f32 v10, v10, v12, v16
	v_div_fixup_f32 v26, v10, v26, 1.0
	v_pk_fma_f32 v[24:25], v[2:3], v[26:27], v[24:25]
	v_mul_f32_e32 v3, 0xbfb8aa3b, v23
	v_mul_f32_e32 v2, 0xbfb8aa3b, v22
	v_exp_f32_e32 v10, v3
	v_mul_f32_e32 v3, 0xbfb8aa3b, v21
	v_exp_f32_e32 v2, v2
	v_exp_f32_e32 v3, v3
	v_lshlrev_b32_e32 v22, 16, v11
	v_and_b32_e32 v23, 0xffff0000, v11
	v_lshlrev_b32_e32 v14, 16, v15
	v_pk_add_f32 v[2:3], v[2:3], 1.0 op_sel_hi:[1,0]
	v_and_b32_e32 v15, 0xffff0000, v15
	v_div_scale_f32 v11, s[22:23], v3, v3, 1.0
	v_rcp_f32_e32 v12, v11
	v_pk_add_f32 v[14:15], v[22:23], v[14:15]
	v_fma_f32 v16, -v11, v12, 1.0
	v_fmac_f32_e32 v12, v16, v12
	v_div_scale_f32 v16, vcc, 1.0, v3, 1.0
	v_mul_f32_e32 v21, v16, v12
	v_fma_f32 v22, -v11, v21, v16
	v_fmac_f32_e32 v21, v22, v12
	v_fma_f32 v11, -v11, v21, v16
	v_div_fmas_f32 v11, v11, v12, v21
	v_div_fixup_f32 v3, v11, v3, 1.0
	v_div_scale_f32 v11, s[22:23], v2, v2, 1.0
	v_rcp_f32_e32 v12, v11
	s_nop 0
	v_fma_f32 v16, -v11, v12, 1.0
	v_fmac_f32_e32 v12, v16, v12
	v_div_scale_f32 v16, vcc, 1.0, v2, 1.0
	v_mul_f32_e32 v21, v16, v12
	v_fma_f32 v22, -v11, v21, v16
	v_fmac_f32_e32 v21, v22, v12
	v_fma_f32 v11, -v11, v21, v16
	v_div_fmas_f32 v11, v11, v12, v21
	v_div_fixup_f32 v2, v11, v2, 1.0
	v_pk_fma_f32 v[8:9], v[8:9], v[2:3], v[14:15]
	v_mul_f32_e32 v2, 0xbfb8aa3b, v20
	v_exp_f32_e32 v11, v2
	v_lshlrev_b32_e32 v2, 16, v13
	v_and_b32_e32 v3, 0xffff0000, v13
	v_lshlrev_b32_e32 v12, 16, v17
	v_and_b32_e32 v13, 0xffff0000, v17
	v_pk_add_f32 v[10:11], v[10:11], 1.0 op_sel_hi:[1,0]
	v_pk_add_f32 v[2:3], v[2:3], v[12:13]
	v_div_scale_f32 v12, s[22:23], v11, v11, 1.0
	v_rcp_f32_e32 v13, v12
	s_nop 0
	v_fma_f32 v14, -v12, v13, 1.0
	v_fmac_f32_e32 v13, v14, v13
	v_div_scale_f32 v14, vcc, 1.0, v11, 1.0
	v_mul_f32_e32 v15, v14, v13
	v_fma_f32 v16, -v12, v15, v14
	v_fmac_f32_e32 v15, v16, v13
	v_fma_f32 v12, -v12, v15, v14
	v_div_fmas_f32 v12, v12, v13, v15
	v_div_fixup_f32 v11, v12, v11, 1.0
	v_div_scale_f32 v12, s[22:23], v10, v10, 1.0
	v_rcp_f32_e32 v13, v12
	s_mov_b64 s[22:23], -1
	v_fma_f32 v14, -v12, v13, 1.0
	v_fmac_f32_e32 v13, v14, v13
	v_div_scale_f32 v14, vcc, 1.0, v10, 1.0
	v_mul_f32_e32 v15, v14, v13
	v_fma_f32 v16, -v12, v15, v14
	v_fmac_f32_e32 v15, v16, v13
	v_fma_f32 v12, -v12, v15, v14
	v_div_fmas_f32 v12, v12, v13, v15
	v_div_fixup_f32 v10, v12, v10, 1.0
	v_pk_fma_f32 v[10:11], v[4:5], v[10:11], v[2:3]
	v_cvt_pk_bf16_f32 v2, v6, v7
	v_cvt_pk_bf16_f32 v3, v8, v9
	v_cvt_pk_bf16_f32 v4, v24, v25
	v_cvt_pk_bf16_f32 v5, v10, v11
	s_andn2_b64 vcc, exec, s[4:5]
	global_store_dwordx4 v[18:19], v[2:5], off offset:256
	s_cbranch_vccnz .LBB0_752
	s_andn2_b64 vcc, exec, s[6:7]
	s_cbranch_vccnz .LBB0_751
	s_barrier
	s_branch .LBB0_751
